# sample-unit mLSTM state streaming loop hand-pipelined: 12 nt loads in flight per wave with counted vmcnt instead of load-wait(0)-store per row
# speedup vs baseline: 1.0094x; 1.0088x over previous
; __device__ __forceinline__ void mlstm_sample_unit(Frame& F, const Args& a, int b, int h) {
;     ...
; #pragma unroll 16
;     for (int i = 0; i < 64; ++i) { const int d = 4 * i + rsub;
;         const f32x4 c0 = __builtin_nontemporal_load((const f32x4*)(Cin + (size_t)d * 512));
;         f32x4 cn = c0 * decay;
; #pragma unroll
;         for (int s = 0; s < 4; ++s) { cn += vs[s] * L[MS_KW + s * 256 + d]; qc[s] += c0 * L[MS_Q + s * 256 + d]; }
;         __builtin_nontemporal_store(cn, (f32x4*)(Cout + (size_t)d * 512)); }
.LBB0_1075:
	s_waitcnt lgkmcnt(0)
	v_mbcnt_lo_u32_b32 v254, -1, 0
	v_mbcnt_hi_u32_b32 v254, -1, v254
	v_lshl_add_u32 v254, v254, 4, v41
	ds_read_b32 v234, v254 offset:0
	ds_read_b32 v235, v254 offset:1024
	ds_read_b32 v236, v254 offset:2048
	ds_read_b32 v237, v254 offset:3072
	ds_read_b32 v230, v254 offset:8192
	ds_read_b32 v231, v254 offset:9216
	ds_read_b32 v232, v254 offset:10240
	ds_read_b32 v233, v254 offset:11264
	v_mov_b32_e32 v248, 0x2000
	v_mov_b32_e32 v249, 0
	v_mov_b32_e32 v242, v48
	v_mov_b32_e32 v243, v49
	v_add_co_u32_e32 v246, vcc, 0x4f1c040, v46
	s_nop 1
	v_addc_co_u32_e32 v247, vcc, 0, v47, vcc
	global_load_dwordx4 v[182:185], v[242:243], off nt
	v_lshl_add_u64 v[242:243], v[242:243], 0, v[248:249]
	global_load_dwordx4 v[186:189], v[242:243], off nt
	v_lshl_add_u64 v[242:243], v[242:243], 0, v[248:249]
	global_load_dwordx4 v[190:193], v[242:243], off nt
	v_lshl_add_u64 v[242:243], v[242:243], 0, v[248:249]
	global_load_dwordx4 v[194:197], v[242:243], off nt
	v_lshl_add_u64 v[242:243], v[242:243], 0, v[248:249]
	global_load_dwordx4 v[198:201], v[242:243], off nt
	v_lshl_add_u64 v[242:243], v[242:243], 0, v[248:249]
	global_load_dwordx4 v[202:205], v[242:243], off nt
	v_lshl_add_u64 v[242:243], v[242:243], 0, v[248:249]
	global_load_dwordx4 v[206:209], v[242:243], off nt
	v_lshl_add_u64 v[242:243], v[242:243], 0, v[248:249]
	global_load_dwordx4 v[210:213], v[242:243], off nt
	v_lshl_add_u64 v[242:243], v[242:243], 0, v[248:249]
	global_load_dwordx4 v[214:217], v[242:243], off nt
	v_lshl_add_u64 v[242:243], v[242:243], 0, v[248:249]
	global_load_dwordx4 v[218:221], v[242:243], off nt
	v_lshl_add_u64 v[242:243], v[242:243], 0, v[248:249]
	global_load_dwordx4 v[222:225], v[242:243], off nt
	v_lshl_add_u64 v[242:243], v[242:243], 0, v[248:249]
	global_load_dwordx4 v[226:229], v[242:243], off nt
	v_lshl_add_u64 v[242:243], v[242:243], 0, v[248:249]
	s_waitcnt lgkmcnt(0)
	v_readlane_b32 s8, v230, 0
	v_readlane_b32 s30, v231, 0
	v_readlane_b32 s44, v232, 0
	v_readlane_b32 s46, v233, 0
	v_readlane_b32 s50, v234, 0
	v_readlane_b32 s58, v235, 0
	v_readlane_b32 s98, v236, 0
	v_readlane_b32 s100, v237, 0
	s_waitcnt vmcnt(11)
	v_pk_mul_f32 v[238:239], v[18:19], s[8:9] op_sel_hi:[1,0]
	v_pk_mul_f32 v[240:241], v[20:21], s[8:9] op_sel_hi:[1,0]
	v_pk_fma_f32 v[238:239], v[44:45], v[182:183], v[238:239]
	v_pk_fma_f32 v[240:241], v[44:45], v[184:185], v[240:241]
	v_pk_fma_f32 v[238:239], v[14:15], s[30:31], v[238:239] op_sel_hi:[1,0,1]
	v_pk_fma_f32 v[240:241], v[16:17], s[30:31], v[240:241] op_sel_hi:[1,0,1]
	v_pk_fma_f32 v[238:239], v[10:11], s[44:45], v[238:239] op_sel_hi:[1,0,1]
	v_pk_fma_f32 v[240:241], v[12:13], s[44:45], v[240:241] op_sel_hi:[1,0,1]
	v_pk_fma_f32 v[238:239], v[6:7], s[46:47], v[238:239] op_sel_hi:[1,0,1]
	v_pk_fma_f32 v[240:241], v[8:9], s[46:47], v[240:241] op_sel_hi:[1,0,1]
	v_pk_fma_f32 v[34:35], v[182:183], s[50:51], v[34:35] op_sel_hi:[1,0,1]
	v_pk_fma_f32 v[36:37], v[184:185], s[50:51], v[36:37] op_sel_hi:[1,0,1]
	v_pk_fma_f32 v[30:31], v[182:183], s[58:59], v[30:31] op_sel_hi:[1,0,1]
	v_pk_fma_f32 v[32:33], v[184:185], s[58:59], v[32:33] op_sel_hi:[1,0,1]
	v_pk_fma_f32 v[26:27], v[182:183], s[98:99], v[26:27] op_sel_hi:[1,0,1]
	v_pk_fma_f32 v[28:29], v[184:185], s[98:99], v[28:29] op_sel_hi:[1,0,1]
	v_pk_fma_f32 v[22:23], v[182:183], s[100:101], v[22:23] op_sel_hi:[1,0,1]
	v_pk_fma_f32 v[24:25], v[184:185], s[100:101], v[24:25] op_sel_hi:[1,0,1]
	global_store_dwordx4 v[246:247], v[238:241], off nt
	global_load_dwordx4 v[182:185], v[242:243], off nt
	v_lshl_add_u64 v[242:243], v[242:243], 0, v[248:249]
	v_lshl_add_u64 v[246:247], v[246:247], 0, v[248:249]
	v_readlane_b32 s8, v230, 1
	v_readlane_b32 s30, v231, 1
	v_readlane_b32 s44, v232, 1
	v_readlane_b32 s46, v233, 1
	v_readlane_b32 s50, v234, 1
	v_readlane_b32 s58, v235, 1
	v_readlane_b32 s98, v236, 1
	v_readlane_b32 s100, v237, 1
	s_waitcnt vmcnt(12)
	v_pk_mul_f32 v[238:239], v[18:19], s[8:9] op_sel_hi:[1,0]
	v_pk_mul_f32 v[240:241], v[20:21], s[8:9] op_sel_hi:[1,0]
	v_pk_fma_f32 v[238:239], v[44:45], v[186:187], v[238:239]
	v_pk_fma_f32 v[240:241], v[44:45], v[188:189], v[240:241]
	v_pk_fma_f32 v[238:239], v[14:15], s[30:31], v[238:239] op_sel_hi:[1,0,1]
	v_pk_fma_f32 v[240:241], v[16:17], s[30:31], v[240:241] op_sel_hi:[1,0,1]
	v_pk_fma_f32 v[238:239], v[10:11], s[44:45], v[238:239] op_sel_hi:[1,0,1]
	v_pk_fma_f32 v[240:241], v[12:13], s[44:45], v[240:241] op_sel_hi:[1,0,1]
	v_pk_fma_f32 v[238:239], v[6:7], s[46:47], v[238:239] op_sel_hi:[1,0,1]
	v_pk_fma_f32 v[240:241], v[8:9], s[46:47], v[240:241] op_sel_hi:[1,0,1]
	v_pk_fma_f32 v[34:35], v[186:187], s[50:51], v[34:35] op_sel_hi:[1,0,1]
	v_pk_fma_f32 v[36:37], v[188:189], s[50:51], v[36:37] op_sel_hi:[1,0,1]
	v_pk_fma_f32 v[30:31], v[186:187], s[58:59], v[30:31] op_sel_hi:[1,0,1]
	v_pk_fma_f32 v[32:33], v[188:189], s[58:59], v[32:33] op_sel_hi:[1,0,1]
	v_pk_fma_f32 v[26:27], v[186:187], s[98:99], v[26:27] op_sel_hi:[1,0,1]
	v_pk_fma_f32 v[28:29], v[188:189], s[98:99], v[28:29] op_sel_hi:[1,0,1]
	v_pk_fma_f32 v[22:23], v[186:187], s[100:101], v[22:23] op_sel_hi:[1,0,1]
	v_pk_fma_f32 v[24:25], v[188:189], s[100:101], v[24:25] op_sel_hi:[1,0,1]
	global_store_dwordx4 v[246:247], v[238:241], off nt
	global_load_dwordx4 v[186:189], v[242:243], off nt
	v_lshl_add_u64 v[242:243], v[242:243], 0, v[248:249]
	v_lshl_add_u64 v[246:247], v[246:247], 0, v[248:249]
	v_readlane_b32 s8, v230, 2
	v_readlane_b32 s30, v231, 2
	v_readlane_b32 s44, v232, 2
	v_readlane_b32 s46, v233, 2
	v_readlane_b32 s50, v234, 2
	v_readlane_b32 s58, v235, 2
	v_readlane_b32 s98, v236, 2
	v_readlane_b32 s100, v237, 2
	s_waitcnt vmcnt(13)
; __device__ __forceinline__ void mlstm_sample_unit(Frame& F, const Args& a, int b, int h) {
;     ...
; #pragma unroll 16
;     for (int i = 0; i < 64; ++i) { const int d = 4 * i + rsub;
;         const f32x4 c0 = __builtin_nontemporal_load((const f32x4*)(Cin + (size_t)d * 512));
;         f32x4 cn = c0 * decay;
; #pragma unroll
;         for (int s = 0; s < 4; ++s) { cn += vs[s] * L[MS_KW + s * 256 + d]; qc[s] += c0 * L[MS_Q + s * 256 + d]; }
;         __builtin_nontemporal_store(cn, (f32x4*)(Cout + (size_t)d * 512)); }
	v_pk_mul_f32 v[238:239], v[18:19], s[8:9] op_sel_hi:[1,0]
	v_pk_mul_f32 v[240:241], v[20:21], s[8:9] op_sel_hi:[1,0]
	v_pk_fma_f32 v[238:239], v[44:45], v[190:191], v[238:239]
	v_pk_fma_f32 v[240:241], v[44:45], v[192:193], v[240:241]
	v_pk_fma_f32 v[238:239], v[14:15], s[30:31], v[238:239] op_sel_hi:[1,0,1]
	v_pk_fma_f32 v[240:241], v[16:17], s[30:31], v[240:241] op_sel_hi:[1,0,1]
	v_pk_fma_f32 v[238:239], v[10:11], s[44:45], v[238:239] op_sel_hi:[1,0,1]
	v_pk_fma_f32 v[240:241], v[12:13], s[44:45], v[240:241] op_sel_hi:[1,0,1]
	v_pk_fma_f32 v[238:239], v[6:7], s[46:47], v[238:239] op_sel_hi:[1,0,1]
	v_pk_fma_f32 v[240:241], v[8:9], s[46:47], v[240:241] op_sel_hi:[1,0,1]
	v_pk_fma_f32 v[34:35], v[190:191], s[50:51], v[34:35] op_sel_hi:[1,0,1]
	v_pk_fma_f32 v[36:37], v[192:193], s[50:51], v[36:37] op_sel_hi:[1,0,1]
	v_pk_fma_f32 v[30:31], v[190:191], s[58:59], v[30:31] op_sel_hi:[1,0,1]
	v_pk_fma_f32 v[32:33], v[192:193], s[58:59], v[32:33] op_sel_hi:[1,0,1]
	v_pk_fma_f32 v[26:27], v[190:191], s[98:99], v[26:27] op_sel_hi:[1,0,1]
	v_pk_fma_f32 v[28:29], v[192:193], s[98:99], v[28:29] op_sel_hi:[1,0,1]
	v_pk_fma_f32 v[22:23], v[190:191], s[100:101], v[22:23] op_sel_hi:[1,0,1]
	v_pk_fma_f32 v[24:25], v[192:193], s[100:101], v[24:25] op_sel_hi:[1,0,1]
	global_store_dwordx4 v[246:247], v[238:241], off nt
	global_load_dwordx4 v[190:193], v[242:243], off nt
	v_lshl_add_u64 v[242:243], v[242:243], 0, v[248:249]
	v_lshl_add_u64 v[246:247], v[246:247], 0, v[248:249]
	v_readlane_b32 s8, v230, 3
	v_readlane_b32 s30, v231, 3
	v_readlane_b32 s44, v232, 3
	v_readlane_b32 s46, v233, 3
	v_readlane_b32 s50, v234, 3
	v_readlane_b32 s58, v235, 3
	v_readlane_b32 s98, v236, 3
	v_readlane_b32 s100, v237, 3
	s_waitcnt vmcnt(14)
	v_pk_mul_f32 v[238:239], v[18:19], s[8:9] op_sel_hi:[1,0]
	v_pk_mul_f32 v[240:241], v[20:21], s[8:9] op_sel_hi:[1,0]
	v_pk_fma_f32 v[238:239], v[44:45], v[194:195], v[238:239]
	v_pk_fma_f32 v[240:241], v[44:45], v[196:197], v[240:241]
	v_pk_fma_f32 v[238:239], v[14:15], s[30:31], v[238:239] op_sel_hi:[1,0,1]
	v_pk_fma_f32 v[240:241], v[16:17], s[30:31], v[240:241] op_sel_hi:[1,0,1]
	v_pk_fma_f32 v[238:239], v[10:11], s[44:45], v[238:239] op_sel_hi:[1,0,1]
	v_pk_fma_f32 v[240:241], v[12:13], s[44:45], v[240:241] op_sel_hi:[1,0,1]
	v_pk_fma_f32 v[238:239], v[6:7], s[46:47], v[238:239] op_sel_hi:[1,0,1]
	v_pk_fma_f32 v[240:241], v[8:9], s[46:47], v[240:241] op_sel_hi:[1,0,1]
	v_pk_fma_f32 v[34:35], v[194:195], s[50:51], v[34:35] op_sel_hi:[1,0,1]
	v_pk_fma_f32 v[36:37], v[196:197], s[50:51], v[36:37] op_sel_hi:[1,0,1]
	v_pk_fma_f32 v[30:31], v[194:195], s[58:59], v[30:31] op_sel_hi:[1,0,1]
	v_pk_fma_f32 v[32:33], v[196:197], s[58:59], v[32:33] op_sel_hi:[1,0,1]
	v_pk_fma_f32 v[26:27], v[194:195], s[98:99], v[26:27] op_sel_hi:[1,0,1]
	v_pk_fma_f32 v[28:29], v[196:197], s[98:99], v[28:29] op_sel_hi:[1,0,1]
	v_pk_fma_f32 v[22:23], v[194:195], s[100:101], v[22:23] op_sel_hi:[1,0,1]
	v_pk_fma_f32 v[24:25], v[196:197], s[100:101], v[24:25] op_sel_hi:[1,0,1]
	global_store_dwordx4 v[246:247], v[238:241], off nt
	global_load_dwordx4 v[194:197], v[242:243], off nt
	v_lshl_add_u64 v[242:243], v[242:243], 0, v[248:249]
	v_lshl_add_u64 v[246:247], v[246:247], 0, v[248:249]
	v_readlane_b32 s8, v230, 4
	v_readlane_b32 s30, v231, 4
	v_readlane_b32 s44, v232, 4
	v_readlane_b32 s46, v233, 4
	v_readlane_b32 s50, v234, 4
	v_readlane_b32 s58, v235, 4
	v_readlane_b32 s98, v236, 4
	v_readlane_b32 s100, v237, 4
	s_waitcnt vmcnt(15)
	v_pk_mul_f32 v[238:239], v[18:19], s[8:9] op_sel_hi:[1,0]
	v_pk_mul_f32 v[240:241], v[20:21], s[8:9] op_sel_hi:[1,0]
	v_pk_fma_f32 v[238:239], v[44:45], v[198:199], v[238:239]
	v_pk_fma_f32 v[240:241], v[44:45], v[200:201], v[240:241]
	v_pk_fma_f32 v[238:239], v[14:15], s[30:31], v[238:239] op_sel_hi:[1,0,1]
	v_pk_fma_f32 v[240:241], v[16:17], s[30:31], v[240:241] op_sel_hi:[1,0,1]
	v_pk_fma_f32 v[238:239], v[10:11], s[44:45], v[238:239] op_sel_hi:[1,0,1]
	v_pk_fma_f32 v[240:241], v[12:13], s[44:45], v[240:241] op_sel_hi:[1,0,1]
	v_pk_fma_f32 v[238:239], v[6:7], s[46:47], v[238:239] op_sel_hi:[1,0,1]
	v_pk_fma_f32 v[240:241], v[8:9], s[46:47], v[240:241] op_sel_hi:[1,0,1]
	v_pk_fma_f32 v[34:35], v[198:199], s[50:51], v[34:35] op_sel_hi:[1,0,1]
	v_pk_fma_f32 v[36:37], v[200:201], s[50:51], v[36:37] op_sel_hi:[1,0,1]
	v_pk_fma_f32 v[30:31], v[198:199], s[58:59], v[30:31] op_sel_hi:[1,0,1]
	v_pk_fma_f32 v[32:33], v[200:201], s[58:59], v[32:33] op_sel_hi:[1,0,1]
	v_pk_fma_f32 v[26:27], v[198:199], s[98:99], v[26:27] op_sel_hi:[1,0,1]
	v_pk_fma_f32 v[28:29], v[200:201], s[98:99], v[28:29] op_sel_hi:[1,0,1]
	v_pk_fma_f32 v[22:23], v[198:199], s[100:101], v[22:23] op_sel_hi:[1,0,1]
	v_pk_fma_f32 v[24:25], v[200:201], s[100:101], v[24:25] op_sel_hi:[1,0,1]
	global_store_dwordx4 v[246:247], v[238:241], off nt
	global_load_dwordx4 v[198:201], v[242:243], off nt
	v_lshl_add_u64 v[242:243], v[242:243], 0, v[248:249]
	v_lshl_add_u64 v[246:247], v[246:247], 0, v[248:249]
	v_readlane_b32 s8, v230, 5
	v_readlane_b32 s30, v231, 5
	v_readlane_b32 s44, v232, 5
	v_readlane_b32 s46, v233, 5
	v_readlane_b32 s50, v234, 5
	v_readlane_b32 s58, v235, 5
	v_readlane_b32 s98, v236, 5
	v_readlane_b32 s100, v237, 5
	s_waitcnt vmcnt(16)
; __device__ __forceinline__ void mlstm_sample_unit(Frame& F, const Args& a, int b, int h) {
;     ...
; #pragma unroll 16
;     for (int i = 0; i < 64; ++i) { const int d = 4 * i + rsub;
;         const f32x4 c0 = __builtin_nontemporal_load((const f32x4*)(Cin + (size_t)d * 512));
;         f32x4 cn = c0 * decay;
; #pragma unroll
;         for (int s = 0; s < 4; ++s) { cn += vs[s] * L[MS_KW + s * 256 + d]; qc[s] += c0 * L[MS_Q + s * 256 + d]; }
;         __builtin_nontemporal_store(cn, (f32x4*)(Cout + (size_t)d * 512)); }
	v_pk_mul_f32 v[238:239], v[18:19], s[8:9] op_sel_hi:[1,0]
	v_pk_mul_f32 v[240:241], v[20:21], s[8:9] op_sel_hi:[1,0]
	v_pk_fma_f32 v[238:239], v[44:45], v[202:203], v[238:239]
	v_pk_fma_f32 v[240:241], v[44:45], v[204:205], v[240:241]
	v_pk_fma_f32 v[238:239], v[14:15], s[30:31], v[238:239] op_sel_hi:[1,0,1]
	v_pk_fma_f32 v[240:241], v[16:17], s[30:31], v[240:241] op_sel_hi:[1,0,1]
	v_pk_fma_f32 v[238:239], v[10:11], s[44:45], v[238:239] op_sel_hi:[1,0,1]
	v_pk_fma_f32 v[240:241], v[12:13], s[44:45], v[240:241] op_sel_hi:[1,0,1]
	v_pk_fma_f32 v[238:239], v[6:7], s[46:47], v[238:239] op_sel_hi:[1,0,1]
	v_pk_fma_f32 v[240:241], v[8:9], s[46:47], v[240:241] op_sel_hi:[1,0,1]
	v_pk_fma_f32 v[34:35], v[202:203], s[50:51], v[34:35] op_sel_hi:[1,0,1]
	v_pk_fma_f32 v[36:37], v[204:205], s[50:51], v[36:37] op_sel_hi:[1,0,1]
	v_pk_fma_f32 v[30:31], v[202:203], s[58:59], v[30:31] op_sel_hi:[1,0,1]
	v_pk_fma_f32 v[32:33], v[204:205], s[58:59], v[32:33] op_sel_hi:[1,0,1]
	v_pk_fma_f32 v[26:27], v[202:203], s[98:99], v[26:27] op_sel_hi:[1,0,1]
	v_pk_fma_f32 v[28:29], v[204:205], s[98:99], v[28:29] op_sel_hi:[1,0,1]
	v_pk_fma_f32 v[22:23], v[202:203], s[100:101], v[22:23] op_sel_hi:[1,0,1]
	v_pk_fma_f32 v[24:25], v[204:205], s[100:101], v[24:25] op_sel_hi:[1,0,1]
	global_store_dwordx4 v[246:247], v[238:241], off nt
	global_load_dwordx4 v[202:205], v[242:243], off nt
	v_lshl_add_u64 v[242:243], v[242:243], 0, v[248:249]
	v_lshl_add_u64 v[246:247], v[246:247], 0, v[248:249]
	v_readlane_b32 s8, v230, 6
	v_readlane_b32 s30, v231, 6
	v_readlane_b32 s44, v232, 6
	v_readlane_b32 s46, v233, 6
	v_readlane_b32 s50, v234, 6
	v_readlane_b32 s58, v235, 6
	v_readlane_b32 s98, v236, 6
	v_readlane_b32 s100, v237, 6
	s_waitcnt vmcnt(17)
	v_pk_mul_f32 v[238:239], v[18:19], s[8:9] op_sel_hi:[1,0]
	v_pk_mul_f32 v[240:241], v[20:21], s[8:9] op_sel_hi:[1,0]
	v_pk_fma_f32 v[238:239], v[44:45], v[206:207], v[238:239]
	v_pk_fma_f32 v[240:241], v[44:45], v[208:209], v[240:241]
	v_pk_fma_f32 v[238:239], v[14:15], s[30:31], v[238:239] op_sel_hi:[1,0,1]
	v_pk_fma_f32 v[240:241], v[16:17], s[30:31], v[240:241] op_sel_hi:[1,0,1]
	v_pk_fma_f32 v[238:239], v[10:11], s[44:45], v[238:239] op_sel_hi:[1,0,1]
	v_pk_fma_f32 v[240:241], v[12:13], s[44:45], v[240:241] op_sel_hi:[1,0,1]
	v_pk_fma_f32 v[238:239], v[6:7], s[46:47], v[238:239] op_sel_hi:[1,0,1]
	v_pk_fma_f32 v[240:241], v[8:9], s[46:47], v[240:241] op_sel_hi:[1,0,1]
	v_pk_fma_f32 v[34:35], v[206:207], s[50:51], v[34:35] op_sel_hi:[1,0,1]
	v_pk_fma_f32 v[36:37], v[208:209], s[50:51], v[36:37] op_sel_hi:[1,0,1]
	v_pk_fma_f32 v[30:31], v[206:207], s[58:59], v[30:31] op_sel_hi:[1,0,1]
	v_pk_fma_f32 v[32:33], v[208:209], s[58:59], v[32:33] op_sel_hi:[1,0,1]
	v_pk_fma_f32 v[26:27], v[206:207], s[98:99], v[26:27] op_sel_hi:[1,0,1]
	v_pk_fma_f32 v[28:29], v[208:209], s[98:99], v[28:29] op_sel_hi:[1,0,1]
	v_pk_fma_f32 v[22:23], v[206:207], s[100:101], v[22:23] op_sel_hi:[1,0,1]
	v_pk_fma_f32 v[24:25], v[208:209], s[100:101], v[24:25] op_sel_hi:[1,0,1]
	global_store_dwordx4 v[246:247], v[238:241], off nt
	global_load_dwordx4 v[206:209], v[242:243], off nt
	v_lshl_add_u64 v[242:243], v[242:243], 0, v[248:249]
	v_lshl_add_u64 v[246:247], v[246:247], 0, v[248:249]
	v_readlane_b32 s8, v230, 7
	v_readlane_b32 s30, v231, 7
	v_readlane_b32 s44, v232, 7
	v_readlane_b32 s46, v233, 7
	v_readlane_b32 s50, v234, 7
	v_readlane_b32 s58, v235, 7
	v_readlane_b32 s98, v236, 7
	v_readlane_b32 s100, v237, 7
	s_waitcnt vmcnt(18)
	v_pk_mul_f32 v[238:239], v[18:19], s[8:9] op_sel_hi:[1,0]
	v_pk_mul_f32 v[240:241], v[20:21], s[8:9] op_sel_hi:[1,0]
	v_pk_fma_f32 v[238:239], v[44:45], v[210:211], v[238:239]
	v_pk_fma_f32 v[240:241], v[44:45], v[212:213], v[240:241]
	v_pk_fma_f32 v[238:239], v[14:15], s[30:31], v[238:239] op_sel_hi:[1,0,1]
	v_pk_fma_f32 v[240:241], v[16:17], s[30:31], v[240:241] op_sel_hi:[1,0,1]
	v_pk_fma_f32 v[238:239], v[10:11], s[44:45], v[238:239] op_sel_hi:[1,0,1]
	v_pk_fma_f32 v[240:241], v[12:13], s[44:45], v[240:241] op_sel_hi:[1,0,1]
	v_pk_fma_f32 v[238:239], v[6:7], s[46:47], v[238:239] op_sel_hi:[1,0,1]
	v_pk_fma_f32 v[240:241], v[8:9], s[46:47], v[240:241] op_sel_hi:[1,0,1]
	v_pk_fma_f32 v[34:35], v[210:211], s[50:51], v[34:35] op_sel_hi:[1,0,1]
	v_pk_fma_f32 v[36:37], v[212:213], s[50:51], v[36:37] op_sel_hi:[1,0,1]
	v_pk_fma_f32 v[30:31], v[210:211], s[58:59], v[30:31] op_sel_hi:[1,0,1]
	v_pk_fma_f32 v[32:33], v[212:213], s[58:59], v[32:33] op_sel_hi:[1,0,1]
	v_pk_fma_f32 v[26:27], v[210:211], s[98:99], v[26:27] op_sel_hi:[1,0,1]
	v_pk_fma_f32 v[28:29], v[212:213], s[98:99], v[28:29] op_sel_hi:[1,0,1]
	v_pk_fma_f32 v[22:23], v[210:211], s[100:101], v[22:23] op_sel_hi:[1,0,1]
	v_pk_fma_f32 v[24:25], v[212:213], s[100:101], v[24:25] op_sel_hi:[1,0,1]
	global_store_dwordx4 v[246:247], v[238:241], off nt
	global_load_dwordx4 v[210:213], v[242:243], off nt
	v_lshl_add_u64 v[242:243], v[242:243], 0, v[248:249]
	v_lshl_add_u64 v[246:247], v[246:247], 0, v[248:249]
	v_readlane_b32 s8, v230, 8
	v_readlane_b32 s30, v231, 8
	v_readlane_b32 s44, v232, 8
	v_readlane_b32 s46, v233, 8
	v_readlane_b32 s50, v234, 8
	v_readlane_b32 s58, v235, 8
	v_readlane_b32 s98, v236, 8
	v_readlane_b32 s100, v237, 8
	s_waitcnt vmcnt(19)
; __device__ __forceinline__ void mlstm_sample_unit(Frame& F, const Args& a, int b, int h) {
;     ...
; #pragma unroll 16
;     for (int i = 0; i < 64; ++i) { const int d = 4 * i + rsub;
;         const f32x4 c0 = __builtin_nontemporal_load((const f32x4*)(Cin + (size_t)d * 512));
;         f32x4 cn = c0 * decay;
; #pragma unroll
;         for (int s = 0; s < 4; ++s) { cn += vs[s] * L[MS_KW + s * 256 + d]; qc[s] += c0 * L[MS_Q + s * 256 + d]; }
;         __builtin_nontemporal_store(cn, (f32x4*)(Cout + (size_t)d * 512)); }
	v_pk_mul_f32 v[238:239], v[18:19], s[8:9] op_sel_hi:[1,0]
	v_pk_mul_f32 v[240:241], v[20:21], s[8:9] op_sel_hi:[1,0]
	v_pk_fma_f32 v[238:239], v[44:45], v[214:215], v[238:239]
	v_pk_fma_f32 v[240:241], v[44:45], v[216:217], v[240:241]
	v_pk_fma_f32 v[238:239], v[14:15], s[30:31], v[238:239] op_sel_hi:[1,0,1]
	v_pk_fma_f32 v[240:241], v[16:17], s[30:31], v[240:241] op_sel_hi:[1,0,1]
	v_pk_fma_f32 v[238:239], v[10:11], s[44:45], v[238:239] op_sel_hi:[1,0,1]
	v_pk_fma_f32 v[240:241], v[12:13], s[44:45], v[240:241] op_sel_hi:[1,0,1]
	v_pk_fma_f32 v[238:239], v[6:7], s[46:47], v[238:239] op_sel_hi:[1,0,1]
	v_pk_fma_f32 v[240:241], v[8:9], s[46:47], v[240:241] op_sel_hi:[1,0,1]
	v_pk_fma_f32 v[34:35], v[214:215], s[50:51], v[34:35] op_sel_hi:[1,0,1]
	v_pk_fma_f32 v[36:37], v[216:217], s[50:51], v[36:37] op_sel_hi:[1,0,1]
	v_pk_fma_f32 v[30:31], v[214:215], s[58:59], v[30:31] op_sel_hi:[1,0,1]
	v_pk_fma_f32 v[32:33], v[216:217], s[58:59], v[32:33] op_sel_hi:[1,0,1]
	v_pk_fma_f32 v[26:27], v[214:215], s[98:99], v[26:27] op_sel_hi:[1,0,1]
	v_pk_fma_f32 v[28:29], v[216:217], s[98:99], v[28:29] op_sel_hi:[1,0,1]
	v_pk_fma_f32 v[22:23], v[214:215], s[100:101], v[22:23] op_sel_hi:[1,0,1]
	v_pk_fma_f32 v[24:25], v[216:217], s[100:101], v[24:25] op_sel_hi:[1,0,1]
	global_store_dwordx4 v[246:247], v[238:241], off nt
	global_load_dwordx4 v[214:217], v[242:243], off nt
	v_lshl_add_u64 v[242:243], v[242:243], 0, v[248:249]
	v_lshl_add_u64 v[246:247], v[246:247], 0, v[248:249]
	v_readlane_b32 s8, v230, 9
	v_readlane_b32 s30, v231, 9
	v_readlane_b32 s44, v232, 9
	v_readlane_b32 s46, v233, 9
	v_readlane_b32 s50, v234, 9
	v_readlane_b32 s58, v235, 9
	v_readlane_b32 s98, v236, 9
	v_readlane_b32 s100, v237, 9
	s_waitcnt vmcnt(20)
	v_pk_mul_f32 v[238:239], v[18:19], s[8:9] op_sel_hi:[1,0]
	v_pk_mul_f32 v[240:241], v[20:21], s[8:9] op_sel_hi:[1,0]
	v_pk_fma_f32 v[238:239], v[44:45], v[218:219], v[238:239]
	v_pk_fma_f32 v[240:241], v[44:45], v[220:221], v[240:241]
	v_pk_fma_f32 v[238:239], v[14:15], s[30:31], v[238:239] op_sel_hi:[1,0,1]
	v_pk_fma_f32 v[240:241], v[16:17], s[30:31], v[240:241] op_sel_hi:[1,0,1]
	v_pk_fma_f32 v[238:239], v[10:11], s[44:45], v[238:239] op_sel_hi:[1,0,1]
	v_pk_fma_f32 v[240:241], v[12:13], s[44:45], v[240:241] op_sel_hi:[1,0,1]
	v_pk_fma_f32 v[238:239], v[6:7], s[46:47], v[238:239] op_sel_hi:[1,0,1]
	v_pk_fma_f32 v[240:241], v[8:9], s[46:47], v[240:241] op_sel_hi:[1,0,1]
	v_pk_fma_f32 v[34:35], v[218:219], s[50:51], v[34:35] op_sel_hi:[1,0,1]
	v_pk_fma_f32 v[36:37], v[220:221], s[50:51], v[36:37] op_sel_hi:[1,0,1]
	v_pk_fma_f32 v[30:31], v[218:219], s[58:59], v[30:31] op_sel_hi:[1,0,1]
	v_pk_fma_f32 v[32:33], v[220:221], s[58:59], v[32:33] op_sel_hi:[1,0,1]
	v_pk_fma_f32 v[26:27], v[218:219], s[98:99], v[26:27] op_sel_hi:[1,0,1]
	v_pk_fma_f32 v[28:29], v[220:221], s[98:99], v[28:29] op_sel_hi:[1,0,1]
	v_pk_fma_f32 v[22:23], v[218:219], s[100:101], v[22:23] op_sel_hi:[1,0,1]
	v_pk_fma_f32 v[24:25], v[220:221], s[100:101], v[24:25] op_sel_hi:[1,0,1]
	global_store_dwordx4 v[246:247], v[238:241], off nt
	global_load_dwordx4 v[218:221], v[242:243], off nt
	v_lshl_add_u64 v[242:243], v[242:243], 0, v[248:249]
	v_lshl_add_u64 v[246:247], v[246:247], 0, v[248:249]
	v_readlane_b32 s8, v230, 10
	v_readlane_b32 s30, v231, 10
	v_readlane_b32 s44, v232, 10
	v_readlane_b32 s46, v233, 10
	v_readlane_b32 s50, v234, 10
	v_readlane_b32 s58, v235, 10
	v_readlane_b32 s98, v236, 10
	v_readlane_b32 s100, v237, 10
	s_waitcnt vmcnt(21)
	v_pk_mul_f32 v[238:239], v[18:19], s[8:9] op_sel_hi:[1,0]
	v_pk_mul_f32 v[240:241], v[20:21], s[8:9] op_sel_hi:[1,0]
	v_pk_fma_f32 v[238:239], v[44:45], v[222:223], v[238:239]
	v_pk_fma_f32 v[240:241], v[44:45], v[224:225], v[240:241]
	v_pk_fma_f32 v[238:239], v[14:15], s[30:31], v[238:239] op_sel_hi:[1,0,1]
	v_pk_fma_f32 v[240:241], v[16:17], s[30:31], v[240:241] op_sel_hi:[1,0,1]
	v_pk_fma_f32 v[238:239], v[10:11], s[44:45], v[238:239] op_sel_hi:[1,0,1]
	v_pk_fma_f32 v[240:241], v[12:13], s[44:45], v[240:241] op_sel_hi:[1,0,1]
	v_pk_fma_f32 v[238:239], v[6:7], s[46:47], v[238:239] op_sel_hi:[1,0,1]
	v_pk_fma_f32 v[240:241], v[8:9], s[46:47], v[240:241] op_sel_hi:[1,0,1]
	v_pk_fma_f32 v[34:35], v[222:223], s[50:51], v[34:35] op_sel_hi:[1,0,1]
	v_pk_fma_f32 v[36:37], v[224:225], s[50:51], v[36:37] op_sel_hi:[1,0,1]
	v_pk_fma_f32 v[30:31], v[222:223], s[58:59], v[30:31] op_sel_hi:[1,0,1]
	v_pk_fma_f32 v[32:33], v[224:225], s[58:59], v[32:33] op_sel_hi:[1,0,1]
	v_pk_fma_f32 v[26:27], v[222:223], s[98:99], v[26:27] op_sel_hi:[1,0,1]
	v_pk_fma_f32 v[28:29], v[224:225], s[98:99], v[28:29] op_sel_hi:[1,0,1]
	v_pk_fma_f32 v[22:23], v[222:223], s[100:101], v[22:23] op_sel_hi:[1,0,1]
	v_pk_fma_f32 v[24:25], v[224:225], s[100:101], v[24:25] op_sel_hi:[1,0,1]
	global_store_dwordx4 v[246:247], v[238:241], off nt
	global_load_dwordx4 v[222:225], v[242:243], off nt
	v_lshl_add_u64 v[242:243], v[242:243], 0, v[248:249]
	v_lshl_add_u64 v[246:247], v[246:247], 0, v[248:249]
	v_readlane_b32 s8, v230, 11
	v_readlane_b32 s30, v231, 11
	v_readlane_b32 s44, v232, 11
	v_readlane_b32 s46, v233, 11
	v_readlane_b32 s50, v234, 11
	v_readlane_b32 s58, v235, 11
	v_readlane_b32 s98, v236, 11
	v_readlane_b32 s100, v237, 11
	s_waitcnt vmcnt(22)
; __device__ __forceinline__ void mlstm_sample_unit(Frame& F, const Args& a, int b, int h) {
;     ...
; #pragma unroll 16
;     for (int i = 0; i < 64; ++i) { const int d = 4 * i + rsub;
;         const f32x4 c0 = __builtin_nontemporal_load((const f32x4*)(Cin + (size_t)d * 512));
;         f32x4 cn = c0 * decay;
; #pragma unroll
;         for (int s = 0; s < 4; ++s) { cn += vs[s] * L[MS_KW + s * 256 + d]; qc[s] += c0 * L[MS_Q + s * 256 + d]; }
;         __builtin_nontemporal_store(cn, (f32x4*)(Cout + (size_t)d * 512)); }
	v_pk_mul_f32 v[238:239], v[18:19], s[8:9] op_sel_hi:[1,0]
	v_pk_mul_f32 v[240:241], v[20:21], s[8:9] op_sel_hi:[1,0]
	v_pk_fma_f32 v[238:239], v[44:45], v[226:227], v[238:239]
	v_pk_fma_f32 v[240:241], v[44:45], v[228:229], v[240:241]
	v_pk_fma_f32 v[238:239], v[14:15], s[30:31], v[238:239] op_sel_hi:[1,0,1]
	v_pk_fma_f32 v[240:241], v[16:17], s[30:31], v[240:241] op_sel_hi:[1,0,1]
	v_pk_fma_f32 v[238:239], v[10:11], s[44:45], v[238:239] op_sel_hi:[1,0,1]
	v_pk_fma_f32 v[240:241], v[12:13], s[44:45], v[240:241] op_sel_hi:[1,0,1]
	v_pk_fma_f32 v[238:239], v[6:7], s[46:47], v[238:239] op_sel_hi:[1,0,1]
	v_pk_fma_f32 v[240:241], v[8:9], s[46:47], v[240:241] op_sel_hi:[1,0,1]
	v_pk_fma_f32 v[34:35], v[226:227], s[50:51], v[34:35] op_sel_hi:[1,0,1]
	v_pk_fma_f32 v[36:37], v[228:229], s[50:51], v[36:37] op_sel_hi:[1,0,1]
	v_pk_fma_f32 v[30:31], v[226:227], s[58:59], v[30:31] op_sel_hi:[1,0,1]
	v_pk_fma_f32 v[32:33], v[228:229], s[58:59], v[32:33] op_sel_hi:[1,0,1]
	v_pk_fma_f32 v[26:27], v[226:227], s[98:99], v[26:27] op_sel_hi:[1,0,1]
	v_pk_fma_f32 v[28:29], v[228:229], s[98:99], v[28:29] op_sel_hi:[1,0,1]
	v_pk_fma_f32 v[22:23], v[226:227], s[100:101], v[22:23] op_sel_hi:[1,0,1]
	v_pk_fma_f32 v[24:25], v[228:229], s[100:101], v[24:25] op_sel_hi:[1,0,1]
	global_store_dwordx4 v[246:247], v[238:241], off nt
	global_load_dwordx4 v[226:229], v[242:243], off nt
	v_lshl_add_u64 v[242:243], v[242:243], 0, v[248:249]
	v_lshl_add_u64 v[246:247], v[246:247], 0, v[248:249]
	v_readlane_b32 s8, v230, 12
	v_readlane_b32 s30, v231, 12
	v_readlane_b32 s44, v232, 12
	v_readlane_b32 s46, v233, 12
	v_readlane_b32 s50, v234, 12
	v_readlane_b32 s58, v235, 12
	v_readlane_b32 s98, v236, 12
	v_readlane_b32 s100, v237, 12
	s_waitcnt vmcnt(22)
	v_pk_mul_f32 v[238:239], v[18:19], s[8:9] op_sel_hi:[1,0]
	v_pk_mul_f32 v[240:241], v[20:21], s[8:9] op_sel_hi:[1,0]
	v_pk_fma_f32 v[238:239], v[44:45], v[182:183], v[238:239]
	v_pk_fma_f32 v[240:241], v[44:45], v[184:185], v[240:241]
	v_pk_fma_f32 v[238:239], v[14:15], s[30:31], v[238:239] op_sel_hi:[1,0,1]
	v_pk_fma_f32 v[240:241], v[16:17], s[30:31], v[240:241] op_sel_hi:[1,0,1]
	v_pk_fma_f32 v[238:239], v[10:11], s[44:45], v[238:239] op_sel_hi:[1,0,1]
	v_pk_fma_f32 v[240:241], v[12:13], s[44:45], v[240:241] op_sel_hi:[1,0,1]
	v_pk_fma_f32 v[238:239], v[6:7], s[46:47], v[238:239] op_sel_hi:[1,0,1]
	v_pk_fma_f32 v[240:241], v[8:9], s[46:47], v[240:241] op_sel_hi:[1,0,1]
	v_pk_fma_f32 v[34:35], v[182:183], s[50:51], v[34:35] op_sel_hi:[1,0,1]
	v_pk_fma_f32 v[36:37], v[184:185], s[50:51], v[36:37] op_sel_hi:[1,0,1]
	v_pk_fma_f32 v[30:31], v[182:183], s[58:59], v[30:31] op_sel_hi:[1,0,1]
	v_pk_fma_f32 v[32:33], v[184:185], s[58:59], v[32:33] op_sel_hi:[1,0,1]
	v_pk_fma_f32 v[26:27], v[182:183], s[98:99], v[26:27] op_sel_hi:[1,0,1]
	v_pk_fma_f32 v[28:29], v[184:185], s[98:99], v[28:29] op_sel_hi:[1,0,1]
	v_pk_fma_f32 v[22:23], v[182:183], s[100:101], v[22:23] op_sel_hi:[1,0,1]
	v_pk_fma_f32 v[24:25], v[184:185], s[100:101], v[24:25] op_sel_hi:[1,0,1]
	global_store_dwordx4 v[246:247], v[238:241], off nt
	global_load_dwordx4 v[182:185], v[242:243], off nt
	v_lshl_add_u64 v[242:243], v[242:243], 0, v[248:249]
	v_lshl_add_u64 v[246:247], v[246:247], 0, v[248:249]
	v_readlane_b32 s8, v230, 13
	v_readlane_b32 s30, v231, 13
	v_readlane_b32 s44, v232, 13
	v_readlane_b32 s46, v233, 13
	v_readlane_b32 s50, v234, 13
	v_readlane_b32 s58, v235, 13
	v_readlane_b32 s98, v236, 13
	v_readlane_b32 s100, v237, 13
	s_waitcnt vmcnt(22)
	v_pk_mul_f32 v[238:239], v[18:19], s[8:9] op_sel_hi:[1,0]
	v_pk_mul_f32 v[240:241], v[20:21], s[8:9] op_sel_hi:[1,0]
	v_pk_fma_f32 v[238:239], v[44:45], v[186:187], v[238:239]
	v_pk_fma_f32 v[240:241], v[44:45], v[188:189], v[240:241]
	v_pk_fma_f32 v[238:239], v[14:15], s[30:31], v[238:239] op_sel_hi:[1,0,1]
	v_pk_fma_f32 v[240:241], v[16:17], s[30:31], v[240:241] op_sel_hi:[1,0,1]
	v_pk_fma_f32 v[238:239], v[10:11], s[44:45], v[238:239] op_sel_hi:[1,0,1]
	v_pk_fma_f32 v[240:241], v[12:13], s[44:45], v[240:241] op_sel_hi:[1,0,1]
	v_pk_fma_f32 v[238:239], v[6:7], s[46:47], v[238:239] op_sel_hi:[1,0,1]
	v_pk_fma_f32 v[240:241], v[8:9], s[46:47], v[240:241] op_sel_hi:[1,0,1]
	v_pk_fma_f32 v[34:35], v[186:187], s[50:51], v[34:35] op_sel_hi:[1,0,1]
	v_pk_fma_f32 v[36:37], v[188:189], s[50:51], v[36:37] op_sel_hi:[1,0,1]
	v_pk_fma_f32 v[30:31], v[186:187], s[58:59], v[30:31] op_sel_hi:[1,0,1]
	v_pk_fma_f32 v[32:33], v[188:189], s[58:59], v[32:33] op_sel_hi:[1,0,1]
	v_pk_fma_f32 v[26:27], v[186:187], s[98:99], v[26:27] op_sel_hi:[1,0,1]
	v_pk_fma_f32 v[28:29], v[188:189], s[98:99], v[28:29] op_sel_hi:[1,0,1]
	v_pk_fma_f32 v[22:23], v[186:187], s[100:101], v[22:23] op_sel_hi:[1,0,1]
	v_pk_fma_f32 v[24:25], v[188:189], s[100:101], v[24:25] op_sel_hi:[1,0,1]
	global_store_dwordx4 v[246:247], v[238:241], off nt
	global_load_dwordx4 v[186:189], v[242:243], off nt
	v_lshl_add_u64 v[242:243], v[242:243], 0, v[248:249]
	v_lshl_add_u64 v[246:247], v[246:247], 0, v[248:249]
	v_readlane_b32 s8, v230, 14
	v_readlane_b32 s30, v231, 14
	v_readlane_b32 s44, v232, 14
	v_readlane_b32 s46, v233, 14
	v_readlane_b32 s50, v234, 14
	v_readlane_b32 s58, v235, 14
	v_readlane_b32 s98, v236, 14
	v_readlane_b32 s100, v237, 14
	s_waitcnt vmcnt(22)
; __device__ __forceinline__ void mlstm_sample_unit(Frame& F, const Args& a, int b, int h) {
;     ...
; #pragma unroll 16
;     for (int i = 0; i < 64; ++i) { const int d = 4 * i + rsub;
;         const f32x4 c0 = __builtin_nontemporal_load((const f32x4*)(Cin + (size_t)d * 512));
;         f32x4 cn = c0 * decay;
; #pragma unroll
;         for (int s = 0; s < 4; ++s) { cn += vs[s] * L[MS_KW + s * 256 + d]; qc[s] += c0 * L[MS_Q + s * 256 + d]; }
;         __builtin_nontemporal_store(cn, (f32x4*)(Cout + (size_t)d * 512)); }
	v_pk_mul_f32 v[238:239], v[18:19], s[8:9] op_sel_hi:[1,0]
	v_pk_mul_f32 v[240:241], v[20:21], s[8:9] op_sel_hi:[1,0]
	v_pk_fma_f32 v[238:239], v[44:45], v[190:191], v[238:239]
	v_pk_fma_f32 v[240:241], v[44:45], v[192:193], v[240:241]
	v_pk_fma_f32 v[238:239], v[14:15], s[30:31], v[238:239] op_sel_hi:[1,0,1]
	v_pk_fma_f32 v[240:241], v[16:17], s[30:31], v[240:241] op_sel_hi:[1,0,1]
	v_pk_fma_f32 v[238:239], v[10:11], s[44:45], v[238:239] op_sel_hi:[1,0,1]
	v_pk_fma_f32 v[240:241], v[12:13], s[44:45], v[240:241] op_sel_hi:[1,0,1]
	v_pk_fma_f32 v[238:239], v[6:7], s[46:47], v[238:239] op_sel_hi:[1,0,1]
	v_pk_fma_f32 v[240:241], v[8:9], s[46:47], v[240:241] op_sel_hi:[1,0,1]
	v_pk_fma_f32 v[34:35], v[190:191], s[50:51], v[34:35] op_sel_hi:[1,0,1]
	v_pk_fma_f32 v[36:37], v[192:193], s[50:51], v[36:37] op_sel_hi:[1,0,1]
	v_pk_fma_f32 v[30:31], v[190:191], s[58:59], v[30:31] op_sel_hi:[1,0,1]
	v_pk_fma_f32 v[32:33], v[192:193], s[58:59], v[32:33] op_sel_hi:[1,0,1]
	v_pk_fma_f32 v[26:27], v[190:191], s[98:99], v[26:27] op_sel_hi:[1,0,1]
	v_pk_fma_f32 v[28:29], v[192:193], s[98:99], v[28:29] op_sel_hi:[1,0,1]
	v_pk_fma_f32 v[22:23], v[190:191], s[100:101], v[22:23] op_sel_hi:[1,0,1]
	v_pk_fma_f32 v[24:25], v[192:193], s[100:101], v[24:25] op_sel_hi:[1,0,1]
	global_store_dwordx4 v[246:247], v[238:241], off nt
	global_load_dwordx4 v[190:193], v[242:243], off nt
	v_lshl_add_u64 v[242:243], v[242:243], 0, v[248:249]
	v_lshl_add_u64 v[246:247], v[246:247], 0, v[248:249]
	v_readlane_b32 s8, v230, 15
	v_readlane_b32 s30, v231, 15
	v_readlane_b32 s44, v232, 15
	v_readlane_b32 s46, v233, 15
	v_readlane_b32 s50, v234, 15
	v_readlane_b32 s58, v235, 15
	v_readlane_b32 s98, v236, 15
	v_readlane_b32 s100, v237, 15
	s_waitcnt vmcnt(22)
	v_pk_mul_f32 v[238:239], v[18:19], s[8:9] op_sel_hi:[1,0]
	v_pk_mul_f32 v[240:241], v[20:21], s[8:9] op_sel_hi:[1,0]
	v_pk_fma_f32 v[238:239], v[44:45], v[194:195], v[238:239]
	v_pk_fma_f32 v[240:241], v[44:45], v[196:197], v[240:241]
	v_pk_fma_f32 v[238:239], v[14:15], s[30:31], v[238:239] op_sel_hi:[1,0,1]
	v_pk_fma_f32 v[240:241], v[16:17], s[30:31], v[240:241] op_sel_hi:[1,0,1]
	v_pk_fma_f32 v[238:239], v[10:11], s[44:45], v[238:239] op_sel_hi:[1,0,1]
	v_pk_fma_f32 v[240:241], v[12:13], s[44:45], v[240:241] op_sel_hi:[1,0,1]
	v_pk_fma_f32 v[238:239], v[6:7], s[46:47], v[238:239] op_sel_hi:[1,0,1]
	v_pk_fma_f32 v[240:241], v[8:9], s[46:47], v[240:241] op_sel_hi:[1,0,1]
	v_pk_fma_f32 v[34:35], v[194:195], s[50:51], v[34:35] op_sel_hi:[1,0,1]
	v_pk_fma_f32 v[36:37], v[196:197], s[50:51], v[36:37] op_sel_hi:[1,0,1]
	v_pk_fma_f32 v[30:31], v[194:195], s[58:59], v[30:31] op_sel_hi:[1,0,1]
	v_pk_fma_f32 v[32:33], v[196:197], s[58:59], v[32:33] op_sel_hi:[1,0,1]
	v_pk_fma_f32 v[26:27], v[194:195], s[98:99], v[26:27] op_sel_hi:[1,0,1]
	v_pk_fma_f32 v[28:29], v[196:197], s[98:99], v[28:29] op_sel_hi:[1,0,1]
	v_pk_fma_f32 v[22:23], v[194:195], s[100:101], v[22:23] op_sel_hi:[1,0,1]
	v_pk_fma_f32 v[24:25], v[196:197], s[100:101], v[24:25] op_sel_hi:[1,0,1]
	global_store_dwordx4 v[246:247], v[238:241], off nt
	global_load_dwordx4 v[194:197], v[242:243], off nt
	v_lshl_add_u64 v[242:243], v[242:243], 0, v[248:249]
	v_lshl_add_u64 v[246:247], v[246:247], 0, v[248:249]
	v_readlane_b32 s8, v230, 16
	v_readlane_b32 s30, v231, 16
	v_readlane_b32 s44, v232, 16
	v_readlane_b32 s46, v233, 16
	v_readlane_b32 s50, v234, 16
	v_readlane_b32 s58, v235, 16
	v_readlane_b32 s98, v236, 16
	v_readlane_b32 s100, v237, 16
	s_waitcnt vmcnt(22)
	v_pk_mul_f32 v[238:239], v[18:19], s[8:9] op_sel_hi:[1,0]
	v_pk_mul_f32 v[240:241], v[20:21], s[8:9] op_sel_hi:[1,0]
	v_pk_fma_f32 v[238:239], v[44:45], v[198:199], v[238:239]
	v_pk_fma_f32 v[240:241], v[44:45], v[200:201], v[240:241]
	v_pk_fma_f32 v[238:239], v[14:15], s[30:31], v[238:239] op_sel_hi:[1,0,1]
	v_pk_fma_f32 v[240:241], v[16:17], s[30:31], v[240:241] op_sel_hi:[1,0,1]
	v_pk_fma_f32 v[238:239], v[10:11], s[44:45], v[238:239] op_sel_hi:[1,0,1]
	v_pk_fma_f32 v[240:241], v[12:13], s[44:45], v[240:241] op_sel_hi:[1,0,1]
	v_pk_fma_f32 v[238:239], v[6:7], s[46:47], v[238:239] op_sel_hi:[1,0,1]
	v_pk_fma_f32 v[240:241], v[8:9], s[46:47], v[240:241] op_sel_hi:[1,0,1]
	v_pk_fma_f32 v[34:35], v[198:199], s[50:51], v[34:35] op_sel_hi:[1,0,1]
	v_pk_fma_f32 v[36:37], v[200:201], s[50:51], v[36:37] op_sel_hi:[1,0,1]
	v_pk_fma_f32 v[30:31], v[198:199], s[58:59], v[30:31] op_sel_hi:[1,0,1]
	v_pk_fma_f32 v[32:33], v[200:201], s[58:59], v[32:33] op_sel_hi:[1,0,1]
	v_pk_fma_f32 v[26:27], v[198:199], s[98:99], v[26:27] op_sel_hi:[1,0,1]
	v_pk_fma_f32 v[28:29], v[200:201], s[98:99], v[28:29] op_sel_hi:[1,0,1]
	v_pk_fma_f32 v[22:23], v[198:199], s[100:101], v[22:23] op_sel_hi:[1,0,1]
	v_pk_fma_f32 v[24:25], v[200:201], s[100:101], v[24:25] op_sel_hi:[1,0,1]
	global_store_dwordx4 v[246:247], v[238:241], off nt
	global_load_dwordx4 v[198:201], v[242:243], off nt
	v_lshl_add_u64 v[242:243], v[242:243], 0, v[248:249]
	v_lshl_add_u64 v[246:247], v[246:247], 0, v[248:249]
	v_readlane_b32 s8, v230, 17
	v_readlane_b32 s30, v231, 17
	v_readlane_b32 s44, v232, 17
	v_readlane_b32 s46, v233, 17
	v_readlane_b32 s50, v234, 17
	v_readlane_b32 s58, v235, 17
	v_readlane_b32 s98, v236, 17
	v_readlane_b32 s100, v237, 17
	s_waitcnt vmcnt(22)
; __device__ __forceinline__ void mlstm_sample_unit(Frame& F, const Args& a, int b, int h) {
;     ...
; #pragma unroll 16
;     for (int i = 0; i < 64; ++i) { const int d = 4 * i + rsub;
;         const f32x4 c0 = __builtin_nontemporal_load((const f32x4*)(Cin + (size_t)d * 512));
;         f32x4 cn = c0 * decay;
; #pragma unroll
;         for (int s = 0; s < 4; ++s) { cn += vs[s] * L[MS_KW + s * 256 + d]; qc[s] += c0 * L[MS_Q + s * 256 + d]; }
;         __builtin_nontemporal_store(cn, (f32x4*)(Cout + (size_t)d * 512)); }
	v_pk_mul_f32 v[238:239], v[18:19], s[8:9] op_sel_hi:[1,0]
	v_pk_mul_f32 v[240:241], v[20:21], s[8:9] op_sel_hi:[1,0]
	v_pk_fma_f32 v[238:239], v[44:45], v[202:203], v[238:239]
	v_pk_fma_f32 v[240:241], v[44:45], v[204:205], v[240:241]
	v_pk_fma_f32 v[238:239], v[14:15], s[30:31], v[238:239] op_sel_hi:[1,0,1]
	v_pk_fma_f32 v[240:241], v[16:17], s[30:31], v[240:241] op_sel_hi:[1,0,1]
	v_pk_fma_f32 v[238:239], v[10:11], s[44:45], v[238:239] op_sel_hi:[1,0,1]
	v_pk_fma_f32 v[240:241], v[12:13], s[44:45], v[240:241] op_sel_hi:[1,0,1]
	v_pk_fma_f32 v[238:239], v[6:7], s[46:47], v[238:239] op_sel_hi:[1,0,1]
	v_pk_fma_f32 v[240:241], v[8:9], s[46:47], v[240:241] op_sel_hi:[1,0,1]
	v_pk_fma_f32 v[34:35], v[202:203], s[50:51], v[34:35] op_sel_hi:[1,0,1]
	v_pk_fma_f32 v[36:37], v[204:205], s[50:51], v[36:37] op_sel_hi:[1,0,1]
	v_pk_fma_f32 v[30:31], v[202:203], s[58:59], v[30:31] op_sel_hi:[1,0,1]
	v_pk_fma_f32 v[32:33], v[204:205], s[58:59], v[32:33] op_sel_hi:[1,0,1]
	v_pk_fma_f32 v[26:27], v[202:203], s[98:99], v[26:27] op_sel_hi:[1,0,1]
	v_pk_fma_f32 v[28:29], v[204:205], s[98:99], v[28:29] op_sel_hi:[1,0,1]
	v_pk_fma_f32 v[22:23], v[202:203], s[100:101], v[22:23] op_sel_hi:[1,0,1]
	v_pk_fma_f32 v[24:25], v[204:205], s[100:101], v[24:25] op_sel_hi:[1,0,1]
	global_store_dwordx4 v[246:247], v[238:241], off nt
	global_load_dwordx4 v[202:205], v[242:243], off nt
	v_lshl_add_u64 v[242:243], v[242:243], 0, v[248:249]
	v_lshl_add_u64 v[246:247], v[246:247], 0, v[248:249]
	v_readlane_b32 s8, v230, 18
	v_readlane_b32 s30, v231, 18
	v_readlane_b32 s44, v232, 18
	v_readlane_b32 s46, v233, 18
	v_readlane_b32 s50, v234, 18
	v_readlane_b32 s58, v235, 18
	v_readlane_b32 s98, v236, 18
	v_readlane_b32 s100, v237, 18
	s_waitcnt vmcnt(22)
	v_pk_mul_f32 v[238:239], v[18:19], s[8:9] op_sel_hi:[1,0]
	v_pk_mul_f32 v[240:241], v[20:21], s[8:9] op_sel_hi:[1,0]
	v_pk_fma_f32 v[238:239], v[44:45], v[206:207], v[238:239]
	v_pk_fma_f32 v[240:241], v[44:45], v[208:209], v[240:241]
	v_pk_fma_f32 v[238:239], v[14:15], s[30:31], v[238:239] op_sel_hi:[1,0,1]
	v_pk_fma_f32 v[240:241], v[16:17], s[30:31], v[240:241] op_sel_hi:[1,0,1]
	v_pk_fma_f32 v[238:239], v[10:11], s[44:45], v[238:239] op_sel_hi:[1,0,1]
	v_pk_fma_f32 v[240:241], v[12:13], s[44:45], v[240:241] op_sel_hi:[1,0,1]
	v_pk_fma_f32 v[238:239], v[6:7], s[46:47], v[238:239] op_sel_hi:[1,0,1]
	v_pk_fma_f32 v[240:241], v[8:9], s[46:47], v[240:241] op_sel_hi:[1,0,1]
	v_pk_fma_f32 v[34:35], v[206:207], s[50:51], v[34:35] op_sel_hi:[1,0,1]
	v_pk_fma_f32 v[36:37], v[208:209], s[50:51], v[36:37] op_sel_hi:[1,0,1]
	v_pk_fma_f32 v[30:31], v[206:207], s[58:59], v[30:31] op_sel_hi:[1,0,1]
	v_pk_fma_f32 v[32:33], v[208:209], s[58:59], v[32:33] op_sel_hi:[1,0,1]
	v_pk_fma_f32 v[26:27], v[206:207], s[98:99], v[26:27] op_sel_hi:[1,0,1]
	v_pk_fma_f32 v[28:29], v[208:209], s[98:99], v[28:29] op_sel_hi:[1,0,1]
	v_pk_fma_f32 v[22:23], v[206:207], s[100:101], v[22:23] op_sel_hi:[1,0,1]
	v_pk_fma_f32 v[24:25], v[208:209], s[100:101], v[24:25] op_sel_hi:[1,0,1]
	global_store_dwordx4 v[246:247], v[238:241], off nt
	global_load_dwordx4 v[206:209], v[242:243], off nt
	v_lshl_add_u64 v[242:243], v[242:243], 0, v[248:249]
	v_lshl_add_u64 v[246:247], v[246:247], 0, v[248:249]
	v_readlane_b32 s8, v230, 19
	v_readlane_b32 s30, v231, 19
	v_readlane_b32 s44, v232, 19
	v_readlane_b32 s46, v233, 19
	v_readlane_b32 s50, v234, 19
	v_readlane_b32 s58, v235, 19
	v_readlane_b32 s98, v236, 19
	v_readlane_b32 s100, v237, 19
	s_waitcnt vmcnt(22)
	v_pk_mul_f32 v[238:239], v[18:19], s[8:9] op_sel_hi:[1,0]
	v_pk_mul_f32 v[240:241], v[20:21], s[8:9] op_sel_hi:[1,0]
	v_pk_fma_f32 v[238:239], v[44:45], v[210:211], v[238:239]
	v_pk_fma_f32 v[240:241], v[44:45], v[212:213], v[240:241]
	v_pk_fma_f32 v[238:239], v[14:15], s[30:31], v[238:239] op_sel_hi:[1,0,1]
	v_pk_fma_f32 v[240:241], v[16:17], s[30:31], v[240:241] op_sel_hi:[1,0,1]
	v_pk_fma_f32 v[238:239], v[10:11], s[44:45], v[238:239] op_sel_hi:[1,0,1]
	v_pk_fma_f32 v[240:241], v[12:13], s[44:45], v[240:241] op_sel_hi:[1,0,1]
	v_pk_fma_f32 v[238:239], v[6:7], s[46:47], v[238:239] op_sel_hi:[1,0,1]
	v_pk_fma_f32 v[240:241], v[8:9], s[46:47], v[240:241] op_sel_hi:[1,0,1]
	v_pk_fma_f32 v[34:35], v[210:211], s[50:51], v[34:35] op_sel_hi:[1,0,1]
	v_pk_fma_f32 v[36:37], v[212:213], s[50:51], v[36:37] op_sel_hi:[1,0,1]
	v_pk_fma_f32 v[30:31], v[210:211], s[58:59], v[30:31] op_sel_hi:[1,0,1]
	v_pk_fma_f32 v[32:33], v[212:213], s[58:59], v[32:33] op_sel_hi:[1,0,1]
	v_pk_fma_f32 v[26:27], v[210:211], s[98:99], v[26:27] op_sel_hi:[1,0,1]
	v_pk_fma_f32 v[28:29], v[212:213], s[98:99], v[28:29] op_sel_hi:[1,0,1]
	v_pk_fma_f32 v[22:23], v[210:211], s[100:101], v[22:23] op_sel_hi:[1,0,1]
	v_pk_fma_f32 v[24:25], v[212:213], s[100:101], v[24:25] op_sel_hi:[1,0,1]
	global_store_dwordx4 v[246:247], v[238:241], off nt
	global_load_dwordx4 v[210:213], v[242:243], off nt
	v_lshl_add_u64 v[242:243], v[242:243], 0, v[248:249]
	v_lshl_add_u64 v[246:247], v[246:247], 0, v[248:249]
	v_readlane_b32 s8, v230, 20
	v_readlane_b32 s30, v231, 20
	v_readlane_b32 s44, v232, 20
	v_readlane_b32 s46, v233, 20
	v_readlane_b32 s50, v234, 20
	v_readlane_b32 s58, v235, 20
	v_readlane_b32 s98, v236, 20
	v_readlane_b32 s100, v237, 20
	s_waitcnt vmcnt(22)
; __device__ __forceinline__ void mlstm_sample_unit(Frame& F, const Args& a, int b, int h) {
;     ...
; #pragma unroll 16
;     for (int i = 0; i < 64; ++i) { const int d = 4 * i + rsub;
;         const f32x4 c0 = __builtin_nontemporal_load((const f32x4*)(Cin + (size_t)d * 512));
;         f32x4 cn = c0 * decay;
; #pragma unroll
;         for (int s = 0; s < 4; ++s) { cn += vs[s] * L[MS_KW + s * 256 + d]; qc[s] += c0 * L[MS_Q + s * 256 + d]; }
;         __builtin_nontemporal_store(cn, (f32x4*)(Cout + (size_t)d * 512)); }
	v_pk_mul_f32 v[238:239], v[18:19], s[8:9] op_sel_hi:[1,0]
	v_pk_mul_f32 v[240:241], v[20:21], s[8:9] op_sel_hi:[1,0]
	v_pk_fma_f32 v[238:239], v[44:45], v[214:215], v[238:239]
	v_pk_fma_f32 v[240:241], v[44:45], v[216:217], v[240:241]
	v_pk_fma_f32 v[238:239], v[14:15], s[30:31], v[238:239] op_sel_hi:[1,0,1]
	v_pk_fma_f32 v[240:241], v[16:17], s[30:31], v[240:241] op_sel_hi:[1,0,1]
	v_pk_fma_f32 v[238:239], v[10:11], s[44:45], v[238:239] op_sel_hi:[1,0,1]
	v_pk_fma_f32 v[240:241], v[12:13], s[44:45], v[240:241] op_sel_hi:[1,0,1]
	v_pk_fma_f32 v[238:239], v[6:7], s[46:47], v[238:239] op_sel_hi:[1,0,1]
	v_pk_fma_f32 v[240:241], v[8:9], s[46:47], v[240:241] op_sel_hi:[1,0,1]
	v_pk_fma_f32 v[34:35], v[214:215], s[50:51], v[34:35] op_sel_hi:[1,0,1]
	v_pk_fma_f32 v[36:37], v[216:217], s[50:51], v[36:37] op_sel_hi:[1,0,1]
	v_pk_fma_f32 v[30:31], v[214:215], s[58:59], v[30:31] op_sel_hi:[1,0,1]
	v_pk_fma_f32 v[32:33], v[216:217], s[58:59], v[32:33] op_sel_hi:[1,0,1]
	v_pk_fma_f32 v[26:27], v[214:215], s[98:99], v[26:27] op_sel_hi:[1,0,1]
	v_pk_fma_f32 v[28:29], v[216:217], s[98:99], v[28:29] op_sel_hi:[1,0,1]
	v_pk_fma_f32 v[22:23], v[214:215], s[100:101], v[22:23] op_sel_hi:[1,0,1]
	v_pk_fma_f32 v[24:25], v[216:217], s[100:101], v[24:25] op_sel_hi:[1,0,1]
	global_store_dwordx4 v[246:247], v[238:241], off nt
	global_load_dwordx4 v[214:217], v[242:243], off nt
	v_lshl_add_u64 v[242:243], v[242:243], 0, v[248:249]
	v_lshl_add_u64 v[246:247], v[246:247], 0, v[248:249]
	v_readlane_b32 s8, v230, 21
	v_readlane_b32 s30, v231, 21
	v_readlane_b32 s44, v232, 21
	v_readlane_b32 s46, v233, 21
	v_readlane_b32 s50, v234, 21
	v_readlane_b32 s58, v235, 21
	v_readlane_b32 s98, v236, 21
	v_readlane_b32 s100, v237, 21
	s_waitcnt vmcnt(22)
	v_pk_mul_f32 v[238:239], v[18:19], s[8:9] op_sel_hi:[1,0]
	v_pk_mul_f32 v[240:241], v[20:21], s[8:9] op_sel_hi:[1,0]
	v_pk_fma_f32 v[238:239], v[44:45], v[218:219], v[238:239]
	v_pk_fma_f32 v[240:241], v[44:45], v[220:221], v[240:241]
	v_pk_fma_f32 v[238:239], v[14:15], s[30:31], v[238:239] op_sel_hi:[1,0,1]
	v_pk_fma_f32 v[240:241], v[16:17], s[30:31], v[240:241] op_sel_hi:[1,0,1]
	v_pk_fma_f32 v[238:239], v[10:11], s[44:45], v[238:239] op_sel_hi:[1,0,1]
	v_pk_fma_f32 v[240:241], v[12:13], s[44:45], v[240:241] op_sel_hi:[1,0,1]
	v_pk_fma_f32 v[238:239], v[6:7], s[46:47], v[238:239] op_sel_hi:[1,0,1]
	v_pk_fma_f32 v[240:241], v[8:9], s[46:47], v[240:241] op_sel_hi:[1,0,1]
	v_pk_fma_f32 v[34:35], v[218:219], s[50:51], v[34:35] op_sel_hi:[1,0,1]
	v_pk_fma_f32 v[36:37], v[220:221], s[50:51], v[36:37] op_sel_hi:[1,0,1]
	v_pk_fma_f32 v[30:31], v[218:219], s[58:59], v[30:31] op_sel_hi:[1,0,1]
	v_pk_fma_f32 v[32:33], v[220:221], s[58:59], v[32:33] op_sel_hi:[1,0,1]
	v_pk_fma_f32 v[26:27], v[218:219], s[98:99], v[26:27] op_sel_hi:[1,0,1]
	v_pk_fma_f32 v[28:29], v[220:221], s[98:99], v[28:29] op_sel_hi:[1,0,1]
	v_pk_fma_f32 v[22:23], v[218:219], s[100:101], v[22:23] op_sel_hi:[1,0,1]
	v_pk_fma_f32 v[24:25], v[220:221], s[100:101], v[24:25] op_sel_hi:[1,0,1]
	global_store_dwordx4 v[246:247], v[238:241], off nt
	global_load_dwordx4 v[218:221], v[242:243], off nt
	v_lshl_add_u64 v[242:243], v[242:243], 0, v[248:249]
	v_lshl_add_u64 v[246:247], v[246:247], 0, v[248:249]
	v_readlane_b32 s8, v230, 22
	v_readlane_b32 s30, v231, 22
	v_readlane_b32 s44, v232, 22
	v_readlane_b32 s46, v233, 22
	v_readlane_b32 s50, v234, 22
	v_readlane_b32 s58, v235, 22
	v_readlane_b32 s98, v236, 22
	v_readlane_b32 s100, v237, 22
	s_waitcnt vmcnt(22)
	v_pk_mul_f32 v[238:239], v[18:19], s[8:9] op_sel_hi:[1,0]
	v_pk_mul_f32 v[240:241], v[20:21], s[8:9] op_sel_hi:[1,0]
	v_pk_fma_f32 v[238:239], v[44:45], v[222:223], v[238:239]
	v_pk_fma_f32 v[240:241], v[44:45], v[224:225], v[240:241]
	v_pk_fma_f32 v[238:239], v[14:15], s[30:31], v[238:239] op_sel_hi:[1,0,1]
	v_pk_fma_f32 v[240:241], v[16:17], s[30:31], v[240:241] op_sel_hi:[1,0,1]
	v_pk_fma_f32 v[238:239], v[10:11], s[44:45], v[238:239] op_sel_hi:[1,0,1]
	v_pk_fma_f32 v[240:241], v[12:13], s[44:45], v[240:241] op_sel_hi:[1,0,1]
	v_pk_fma_f32 v[238:239], v[6:7], s[46:47], v[238:239] op_sel_hi:[1,0,1]
	v_pk_fma_f32 v[240:241], v[8:9], s[46:47], v[240:241] op_sel_hi:[1,0,1]
	v_pk_fma_f32 v[34:35], v[222:223], s[50:51], v[34:35] op_sel_hi:[1,0,1]
	v_pk_fma_f32 v[36:37], v[224:225], s[50:51], v[36:37] op_sel_hi:[1,0,1]
	v_pk_fma_f32 v[30:31], v[222:223], s[58:59], v[30:31] op_sel_hi:[1,0,1]
	v_pk_fma_f32 v[32:33], v[224:225], s[58:59], v[32:33] op_sel_hi:[1,0,1]
	v_pk_fma_f32 v[26:27], v[222:223], s[98:99], v[26:27] op_sel_hi:[1,0,1]
	v_pk_fma_f32 v[28:29], v[224:225], s[98:99], v[28:29] op_sel_hi:[1,0,1]
	v_pk_fma_f32 v[22:23], v[222:223], s[100:101], v[22:23] op_sel_hi:[1,0,1]
	v_pk_fma_f32 v[24:25], v[224:225], s[100:101], v[24:25] op_sel_hi:[1,0,1]
	global_store_dwordx4 v[246:247], v[238:241], off nt
	global_load_dwordx4 v[222:225], v[242:243], off nt
	v_lshl_add_u64 v[242:243], v[242:243], 0, v[248:249]
	v_lshl_add_u64 v[246:247], v[246:247], 0, v[248:249]
	v_readlane_b32 s8, v230, 23
	v_readlane_b32 s30, v231, 23
	v_readlane_b32 s44, v232, 23
	v_readlane_b32 s46, v233, 23
	v_readlane_b32 s50, v234, 23
	v_readlane_b32 s58, v235, 23
	v_readlane_b32 s98, v236, 23
	v_readlane_b32 s100, v237, 23
	s_waitcnt vmcnt(22)
; __device__ __forceinline__ void mlstm_sample_unit(Frame& F, const Args& a, int b, int h) {
;     ...
; #pragma unroll 16
;     for (int i = 0; i < 64; ++i) { const int d = 4 * i + rsub;
;         const f32x4 c0 = __builtin_nontemporal_load((const f32x4*)(Cin + (size_t)d * 512));
;         f32x4 cn = c0 * decay;
; #pragma unroll
;         for (int s = 0; s < 4; ++s) { cn += vs[s] * L[MS_KW + s * 256 + d]; qc[s] += c0 * L[MS_Q + s * 256 + d]; }
;         __builtin_nontemporal_store(cn, (f32x4*)(Cout + (size_t)d * 512)); }
	v_pk_mul_f32 v[238:239], v[18:19], s[8:9] op_sel_hi:[1,0]
	v_pk_mul_f32 v[240:241], v[20:21], s[8:9] op_sel_hi:[1,0]
	v_pk_fma_f32 v[238:239], v[44:45], v[226:227], v[238:239]
	v_pk_fma_f32 v[240:241], v[44:45], v[228:229], v[240:241]
	v_pk_fma_f32 v[238:239], v[14:15], s[30:31], v[238:239] op_sel_hi:[1,0,1]
	v_pk_fma_f32 v[240:241], v[16:17], s[30:31], v[240:241] op_sel_hi:[1,0,1]
	v_pk_fma_f32 v[238:239], v[10:11], s[44:45], v[238:239] op_sel_hi:[1,0,1]
	v_pk_fma_f32 v[240:241], v[12:13], s[44:45], v[240:241] op_sel_hi:[1,0,1]
	v_pk_fma_f32 v[238:239], v[6:7], s[46:47], v[238:239] op_sel_hi:[1,0,1]
	v_pk_fma_f32 v[240:241], v[8:9], s[46:47], v[240:241] op_sel_hi:[1,0,1]
	v_pk_fma_f32 v[34:35], v[226:227], s[50:51], v[34:35] op_sel_hi:[1,0,1]
	v_pk_fma_f32 v[36:37], v[228:229], s[50:51], v[36:37] op_sel_hi:[1,0,1]
	v_pk_fma_f32 v[30:31], v[226:227], s[58:59], v[30:31] op_sel_hi:[1,0,1]
	v_pk_fma_f32 v[32:33], v[228:229], s[58:59], v[32:33] op_sel_hi:[1,0,1]
	v_pk_fma_f32 v[26:27], v[226:227], s[98:99], v[26:27] op_sel_hi:[1,0,1]
	v_pk_fma_f32 v[28:29], v[228:229], s[98:99], v[28:29] op_sel_hi:[1,0,1]
	v_pk_fma_f32 v[22:23], v[226:227], s[100:101], v[22:23] op_sel_hi:[1,0,1]
	v_pk_fma_f32 v[24:25], v[228:229], s[100:101], v[24:25] op_sel_hi:[1,0,1]
	global_store_dwordx4 v[246:247], v[238:241], off nt
	global_load_dwordx4 v[226:229], v[242:243], off nt
	v_lshl_add_u64 v[242:243], v[242:243], 0, v[248:249]
	v_lshl_add_u64 v[246:247], v[246:247], 0, v[248:249]
	v_readlane_b32 s8, v230, 24
	v_readlane_b32 s30, v231, 24
	v_readlane_b32 s44, v232, 24
	v_readlane_b32 s46, v233, 24
	v_readlane_b32 s50, v234, 24
	v_readlane_b32 s58, v235, 24
	v_readlane_b32 s98, v236, 24
	v_readlane_b32 s100, v237, 24
	s_waitcnt vmcnt(22)
	v_pk_mul_f32 v[238:239], v[18:19], s[8:9] op_sel_hi:[1,0]
	v_pk_mul_f32 v[240:241], v[20:21], s[8:9] op_sel_hi:[1,0]
	v_pk_fma_f32 v[238:239], v[44:45], v[182:183], v[238:239]
	v_pk_fma_f32 v[240:241], v[44:45], v[184:185], v[240:241]
	v_pk_fma_f32 v[238:239], v[14:15], s[30:31], v[238:239] op_sel_hi:[1,0,1]
	v_pk_fma_f32 v[240:241], v[16:17], s[30:31], v[240:241] op_sel_hi:[1,0,1]
	v_pk_fma_f32 v[238:239], v[10:11], s[44:45], v[238:239] op_sel_hi:[1,0,1]
	v_pk_fma_f32 v[240:241], v[12:13], s[44:45], v[240:241] op_sel_hi:[1,0,1]
	v_pk_fma_f32 v[238:239], v[6:7], s[46:47], v[238:239] op_sel_hi:[1,0,1]
	v_pk_fma_f32 v[240:241], v[8:9], s[46:47], v[240:241] op_sel_hi:[1,0,1]
	v_pk_fma_f32 v[34:35], v[182:183], s[50:51], v[34:35] op_sel_hi:[1,0,1]
	v_pk_fma_f32 v[36:37], v[184:185], s[50:51], v[36:37] op_sel_hi:[1,0,1]
	v_pk_fma_f32 v[30:31], v[182:183], s[58:59], v[30:31] op_sel_hi:[1,0,1]
	v_pk_fma_f32 v[32:33], v[184:185], s[58:59], v[32:33] op_sel_hi:[1,0,1]
	v_pk_fma_f32 v[26:27], v[182:183], s[98:99], v[26:27] op_sel_hi:[1,0,1]
	v_pk_fma_f32 v[28:29], v[184:185], s[98:99], v[28:29] op_sel_hi:[1,0,1]
	v_pk_fma_f32 v[22:23], v[182:183], s[100:101], v[22:23] op_sel_hi:[1,0,1]
	v_pk_fma_f32 v[24:25], v[184:185], s[100:101], v[24:25] op_sel_hi:[1,0,1]
	global_store_dwordx4 v[246:247], v[238:241], off nt
	global_load_dwordx4 v[182:185], v[242:243], off nt
	v_lshl_add_u64 v[242:243], v[242:243], 0, v[248:249]
	v_lshl_add_u64 v[246:247], v[246:247], 0, v[248:249]
	v_readlane_b32 s8, v230, 25
	v_readlane_b32 s30, v231, 25
	v_readlane_b32 s44, v232, 25
	v_readlane_b32 s46, v233, 25
	v_readlane_b32 s50, v234, 25
	v_readlane_b32 s58, v235, 25
	v_readlane_b32 s98, v236, 25
	v_readlane_b32 s100, v237, 25
	s_waitcnt vmcnt(22)
	v_pk_mul_f32 v[238:239], v[18:19], s[8:9] op_sel_hi:[1,0]
	v_pk_mul_f32 v[240:241], v[20:21], s[8:9] op_sel_hi:[1,0]
	v_pk_fma_f32 v[238:239], v[44:45], v[186:187], v[238:239]
	v_pk_fma_f32 v[240:241], v[44:45], v[188:189], v[240:241]
	v_pk_fma_f32 v[238:239], v[14:15], s[30:31], v[238:239] op_sel_hi:[1,0,1]
	v_pk_fma_f32 v[240:241], v[16:17], s[30:31], v[240:241] op_sel_hi:[1,0,1]
	v_pk_fma_f32 v[238:239], v[10:11], s[44:45], v[238:239] op_sel_hi:[1,0,1]
	v_pk_fma_f32 v[240:241], v[12:13], s[44:45], v[240:241] op_sel_hi:[1,0,1]
	v_pk_fma_f32 v[238:239], v[6:7], s[46:47], v[238:239] op_sel_hi:[1,0,1]
	v_pk_fma_f32 v[240:241], v[8:9], s[46:47], v[240:241] op_sel_hi:[1,0,1]
	v_pk_fma_f32 v[34:35], v[186:187], s[50:51], v[34:35] op_sel_hi:[1,0,1]
	v_pk_fma_f32 v[36:37], v[188:189], s[50:51], v[36:37] op_sel_hi:[1,0,1]
	v_pk_fma_f32 v[30:31], v[186:187], s[58:59], v[30:31] op_sel_hi:[1,0,1]
	v_pk_fma_f32 v[32:33], v[188:189], s[58:59], v[32:33] op_sel_hi:[1,0,1]
	v_pk_fma_f32 v[26:27], v[186:187], s[98:99], v[26:27] op_sel_hi:[1,0,1]
	v_pk_fma_f32 v[28:29], v[188:189], s[98:99], v[28:29] op_sel_hi:[1,0,1]
	v_pk_fma_f32 v[22:23], v[186:187], s[100:101], v[22:23] op_sel_hi:[1,0,1]
	v_pk_fma_f32 v[24:25], v[188:189], s[100:101], v[24:25] op_sel_hi:[1,0,1]
	global_store_dwordx4 v[246:247], v[238:241], off nt
	global_load_dwordx4 v[186:189], v[242:243], off nt
	v_lshl_add_u64 v[242:243], v[242:243], 0, v[248:249]
	v_lshl_add_u64 v[246:247], v[246:247], 0, v[248:249]
	v_readlane_b32 s8, v230, 26
	v_readlane_b32 s30, v231, 26
	v_readlane_b32 s44, v232, 26
	v_readlane_b32 s46, v233, 26
	v_readlane_b32 s50, v234, 26
	v_readlane_b32 s58, v235, 26
	v_readlane_b32 s98, v236, 26
	v_readlane_b32 s100, v237, 26
	s_waitcnt vmcnt(22)
; __device__ __forceinline__ void mlstm_sample_unit(Frame& F, const Args& a, int b, int h) {
;     ...
; #pragma unroll 16
;     for (int i = 0; i < 64; ++i) { const int d = 4 * i + rsub;
;         const f32x4 c0 = __builtin_nontemporal_load((const f32x4*)(Cin + (size_t)d * 512));
;         f32x4 cn = c0 * decay;
; #pragma unroll
;         for (int s = 0; s < 4; ++s) { cn += vs[s] * L[MS_KW + s * 256 + d]; qc[s] += c0 * L[MS_Q + s * 256 + d]; }
;         __builtin_nontemporal_store(cn, (f32x4*)(Cout + (size_t)d * 512)); }
	v_pk_mul_f32 v[238:239], v[18:19], s[8:9] op_sel_hi:[1,0]
	v_pk_mul_f32 v[240:241], v[20:21], s[8:9] op_sel_hi:[1,0]
	v_pk_fma_f32 v[238:239], v[44:45], v[190:191], v[238:239]
	v_pk_fma_f32 v[240:241], v[44:45], v[192:193], v[240:241]
	v_pk_fma_f32 v[238:239], v[14:15], s[30:31], v[238:239] op_sel_hi:[1,0,1]
	v_pk_fma_f32 v[240:241], v[16:17], s[30:31], v[240:241] op_sel_hi:[1,0,1]
	v_pk_fma_f32 v[238:239], v[10:11], s[44:45], v[238:239] op_sel_hi:[1,0,1]
	v_pk_fma_f32 v[240:241], v[12:13], s[44:45], v[240:241] op_sel_hi:[1,0,1]
	v_pk_fma_f32 v[238:239], v[6:7], s[46:47], v[238:239] op_sel_hi:[1,0,1]
	v_pk_fma_f32 v[240:241], v[8:9], s[46:47], v[240:241] op_sel_hi:[1,0,1]
	v_pk_fma_f32 v[34:35], v[190:191], s[50:51], v[34:35] op_sel_hi:[1,0,1]
	v_pk_fma_f32 v[36:37], v[192:193], s[50:51], v[36:37] op_sel_hi:[1,0,1]
	v_pk_fma_f32 v[30:31], v[190:191], s[58:59], v[30:31] op_sel_hi:[1,0,1]
	v_pk_fma_f32 v[32:33], v[192:193], s[58:59], v[32:33] op_sel_hi:[1,0,1]
	v_pk_fma_f32 v[26:27], v[190:191], s[98:99], v[26:27] op_sel_hi:[1,0,1]
	v_pk_fma_f32 v[28:29], v[192:193], s[98:99], v[28:29] op_sel_hi:[1,0,1]
	v_pk_fma_f32 v[22:23], v[190:191], s[100:101], v[22:23] op_sel_hi:[1,0,1]
	v_pk_fma_f32 v[24:25], v[192:193], s[100:101], v[24:25] op_sel_hi:[1,0,1]
	global_store_dwordx4 v[246:247], v[238:241], off nt
	global_load_dwordx4 v[190:193], v[242:243], off nt
	v_lshl_add_u64 v[242:243], v[242:243], 0, v[248:249]
	v_lshl_add_u64 v[246:247], v[246:247], 0, v[248:249]
	v_readlane_b32 s8, v230, 27
	v_readlane_b32 s30, v231, 27
	v_readlane_b32 s44, v232, 27
	v_readlane_b32 s46, v233, 27
	v_readlane_b32 s50, v234, 27
	v_readlane_b32 s58, v235, 27
	v_readlane_b32 s98, v236, 27
	v_readlane_b32 s100, v237, 27
	s_waitcnt vmcnt(22)
	v_pk_mul_f32 v[238:239], v[18:19], s[8:9] op_sel_hi:[1,0]
	v_pk_mul_f32 v[240:241], v[20:21], s[8:9] op_sel_hi:[1,0]
	v_pk_fma_f32 v[238:239], v[44:45], v[194:195], v[238:239]
	v_pk_fma_f32 v[240:241], v[44:45], v[196:197], v[240:241]
	v_pk_fma_f32 v[238:239], v[14:15], s[30:31], v[238:239] op_sel_hi:[1,0,1]
	v_pk_fma_f32 v[240:241], v[16:17], s[30:31], v[240:241] op_sel_hi:[1,0,1]
	v_pk_fma_f32 v[238:239], v[10:11], s[44:45], v[238:239] op_sel_hi:[1,0,1]
	v_pk_fma_f32 v[240:241], v[12:13], s[44:45], v[240:241] op_sel_hi:[1,0,1]
	v_pk_fma_f32 v[238:239], v[6:7], s[46:47], v[238:239] op_sel_hi:[1,0,1]
	v_pk_fma_f32 v[240:241], v[8:9], s[46:47], v[240:241] op_sel_hi:[1,0,1]
	v_pk_fma_f32 v[34:35], v[194:195], s[50:51], v[34:35] op_sel_hi:[1,0,1]
	v_pk_fma_f32 v[36:37], v[196:197], s[50:51], v[36:37] op_sel_hi:[1,0,1]
	v_pk_fma_f32 v[30:31], v[194:195], s[58:59], v[30:31] op_sel_hi:[1,0,1]
	v_pk_fma_f32 v[32:33], v[196:197], s[58:59], v[32:33] op_sel_hi:[1,0,1]
	v_pk_fma_f32 v[26:27], v[194:195], s[98:99], v[26:27] op_sel_hi:[1,0,1]
	v_pk_fma_f32 v[28:29], v[196:197], s[98:99], v[28:29] op_sel_hi:[1,0,1]
	v_pk_fma_f32 v[22:23], v[194:195], s[100:101], v[22:23] op_sel_hi:[1,0,1]
	v_pk_fma_f32 v[24:25], v[196:197], s[100:101], v[24:25] op_sel_hi:[1,0,1]
	global_store_dwordx4 v[246:247], v[238:241], off nt
	global_load_dwordx4 v[194:197], v[242:243], off nt
	v_lshl_add_u64 v[242:243], v[242:243], 0, v[248:249]
	v_lshl_add_u64 v[246:247], v[246:247], 0, v[248:249]
	v_readlane_b32 s8, v230, 28
	v_readlane_b32 s30, v231, 28
	v_readlane_b32 s44, v232, 28
	v_readlane_b32 s46, v233, 28
	v_readlane_b32 s50, v234, 28
	v_readlane_b32 s58, v235, 28
	v_readlane_b32 s98, v236, 28
	v_readlane_b32 s100, v237, 28
	s_waitcnt vmcnt(22)
	v_pk_mul_f32 v[238:239], v[18:19], s[8:9] op_sel_hi:[1,0]
	v_pk_mul_f32 v[240:241], v[20:21], s[8:9] op_sel_hi:[1,0]
	v_pk_fma_f32 v[238:239], v[44:45], v[198:199], v[238:239]
	v_pk_fma_f32 v[240:241], v[44:45], v[200:201], v[240:241]
	v_pk_fma_f32 v[238:239], v[14:15], s[30:31], v[238:239] op_sel_hi:[1,0,1]
	v_pk_fma_f32 v[240:241], v[16:17], s[30:31], v[240:241] op_sel_hi:[1,0,1]
	v_pk_fma_f32 v[238:239], v[10:11], s[44:45], v[238:239] op_sel_hi:[1,0,1]
	v_pk_fma_f32 v[240:241], v[12:13], s[44:45], v[240:241] op_sel_hi:[1,0,1]
	v_pk_fma_f32 v[238:239], v[6:7], s[46:47], v[238:239] op_sel_hi:[1,0,1]
	v_pk_fma_f32 v[240:241], v[8:9], s[46:47], v[240:241] op_sel_hi:[1,0,1]
	v_pk_fma_f32 v[34:35], v[198:199], s[50:51], v[34:35] op_sel_hi:[1,0,1]
	v_pk_fma_f32 v[36:37], v[200:201], s[50:51], v[36:37] op_sel_hi:[1,0,1]
	v_pk_fma_f32 v[30:31], v[198:199], s[58:59], v[30:31] op_sel_hi:[1,0,1]
	v_pk_fma_f32 v[32:33], v[200:201], s[58:59], v[32:33] op_sel_hi:[1,0,1]
	v_pk_fma_f32 v[26:27], v[198:199], s[98:99], v[26:27] op_sel_hi:[1,0,1]
	v_pk_fma_f32 v[28:29], v[200:201], s[98:99], v[28:29] op_sel_hi:[1,0,1]
	v_pk_fma_f32 v[22:23], v[198:199], s[100:101], v[22:23] op_sel_hi:[1,0,1]
	v_pk_fma_f32 v[24:25], v[200:201], s[100:101], v[24:25] op_sel_hi:[1,0,1]
	global_store_dwordx4 v[246:247], v[238:241], off nt
	global_load_dwordx4 v[198:201], v[242:243], off nt
	v_lshl_add_u64 v[242:243], v[242:243], 0, v[248:249]
	v_lshl_add_u64 v[246:247], v[246:247], 0, v[248:249]
	v_readlane_b32 s8, v230, 29
	v_readlane_b32 s30, v231, 29
	v_readlane_b32 s44, v232, 29
	v_readlane_b32 s46, v233, 29
	v_readlane_b32 s50, v234, 29
	v_readlane_b32 s58, v235, 29
	v_readlane_b32 s98, v236, 29
	v_readlane_b32 s100, v237, 29
	s_waitcnt vmcnt(22)
; __device__ __forceinline__ void mlstm_sample_unit(Frame& F, const Args& a, int b, int h) {
;     ...
; #pragma unroll 16
;     for (int i = 0; i < 64; ++i) { const int d = 4 * i + rsub;
;         const f32x4 c0 = __builtin_nontemporal_load((const f32x4*)(Cin + (size_t)d * 512));
;         f32x4 cn = c0 * decay;
; #pragma unroll
;         for (int s = 0; s < 4; ++s) { cn += vs[s] * L[MS_KW + s * 256 + d]; qc[s] += c0 * L[MS_Q + s * 256 + d]; }
;         __builtin_nontemporal_store(cn, (f32x4*)(Cout + (size_t)d * 512)); }
	v_pk_mul_f32 v[238:239], v[18:19], s[8:9] op_sel_hi:[1,0]
	v_pk_mul_f32 v[240:241], v[20:21], s[8:9] op_sel_hi:[1,0]
	v_pk_fma_f32 v[238:239], v[44:45], v[202:203], v[238:239]
	v_pk_fma_f32 v[240:241], v[44:45], v[204:205], v[240:241]
	v_pk_fma_f32 v[238:239], v[14:15], s[30:31], v[238:239] op_sel_hi:[1,0,1]
	v_pk_fma_f32 v[240:241], v[16:17], s[30:31], v[240:241] op_sel_hi:[1,0,1]
	v_pk_fma_f32 v[238:239], v[10:11], s[44:45], v[238:239] op_sel_hi:[1,0,1]
	v_pk_fma_f32 v[240:241], v[12:13], s[44:45], v[240:241] op_sel_hi:[1,0,1]
	v_pk_fma_f32 v[238:239], v[6:7], s[46:47], v[238:239] op_sel_hi:[1,0,1]
	v_pk_fma_f32 v[240:241], v[8:9], s[46:47], v[240:241] op_sel_hi:[1,0,1]
	v_pk_fma_f32 v[34:35], v[202:203], s[50:51], v[34:35] op_sel_hi:[1,0,1]
	v_pk_fma_f32 v[36:37], v[204:205], s[50:51], v[36:37] op_sel_hi:[1,0,1]
	v_pk_fma_f32 v[30:31], v[202:203], s[58:59], v[30:31] op_sel_hi:[1,0,1]
	v_pk_fma_f32 v[32:33], v[204:205], s[58:59], v[32:33] op_sel_hi:[1,0,1]
	v_pk_fma_f32 v[26:27], v[202:203], s[98:99], v[26:27] op_sel_hi:[1,0,1]
	v_pk_fma_f32 v[28:29], v[204:205], s[98:99], v[28:29] op_sel_hi:[1,0,1]
	v_pk_fma_f32 v[22:23], v[202:203], s[100:101], v[22:23] op_sel_hi:[1,0,1]
	v_pk_fma_f32 v[24:25], v[204:205], s[100:101], v[24:25] op_sel_hi:[1,0,1]
	global_store_dwordx4 v[246:247], v[238:241], off nt
	global_load_dwordx4 v[202:205], v[242:243], off nt
	v_lshl_add_u64 v[242:243], v[242:243], 0, v[248:249]
	v_lshl_add_u64 v[246:247], v[246:247], 0, v[248:249]
	v_readlane_b32 s8, v230, 30
	v_readlane_b32 s30, v231, 30
	v_readlane_b32 s44, v232, 30
	v_readlane_b32 s46, v233, 30
	v_readlane_b32 s50, v234, 30
	v_readlane_b32 s58, v235, 30
	v_readlane_b32 s98, v236, 30
	v_readlane_b32 s100, v237, 30
	s_waitcnt vmcnt(22)
	v_pk_mul_f32 v[238:239], v[18:19], s[8:9] op_sel_hi:[1,0]
	v_pk_mul_f32 v[240:241], v[20:21], s[8:9] op_sel_hi:[1,0]
	v_pk_fma_f32 v[238:239], v[44:45], v[206:207], v[238:239]
	v_pk_fma_f32 v[240:241], v[44:45], v[208:209], v[240:241]
	v_pk_fma_f32 v[238:239], v[14:15], s[30:31], v[238:239] op_sel_hi:[1,0,1]
	v_pk_fma_f32 v[240:241], v[16:17], s[30:31], v[240:241] op_sel_hi:[1,0,1]
	v_pk_fma_f32 v[238:239], v[10:11], s[44:45], v[238:239] op_sel_hi:[1,0,1]
	v_pk_fma_f32 v[240:241], v[12:13], s[44:45], v[240:241] op_sel_hi:[1,0,1]
	v_pk_fma_f32 v[238:239], v[6:7], s[46:47], v[238:239] op_sel_hi:[1,0,1]
	v_pk_fma_f32 v[240:241], v[8:9], s[46:47], v[240:241] op_sel_hi:[1,0,1]
	v_pk_fma_f32 v[34:35], v[206:207], s[50:51], v[34:35] op_sel_hi:[1,0,1]
	v_pk_fma_f32 v[36:37], v[208:209], s[50:51], v[36:37] op_sel_hi:[1,0,1]
	v_pk_fma_f32 v[30:31], v[206:207], s[58:59], v[30:31] op_sel_hi:[1,0,1]
	v_pk_fma_f32 v[32:33], v[208:209], s[58:59], v[32:33] op_sel_hi:[1,0,1]
	v_pk_fma_f32 v[26:27], v[206:207], s[98:99], v[26:27] op_sel_hi:[1,0,1]
	v_pk_fma_f32 v[28:29], v[208:209], s[98:99], v[28:29] op_sel_hi:[1,0,1]
	v_pk_fma_f32 v[22:23], v[206:207], s[100:101], v[22:23] op_sel_hi:[1,0,1]
	v_pk_fma_f32 v[24:25], v[208:209], s[100:101], v[24:25] op_sel_hi:[1,0,1]
	global_store_dwordx4 v[246:247], v[238:241], off nt
	global_load_dwordx4 v[206:209], v[242:243], off nt
	v_lshl_add_u64 v[242:243], v[242:243], 0, v[248:249]
	v_lshl_add_u64 v[246:247], v[246:247], 0, v[248:249]
	v_readlane_b32 s8, v230, 31
	v_readlane_b32 s30, v231, 31
	v_readlane_b32 s44, v232, 31
	v_readlane_b32 s46, v233, 31
	v_readlane_b32 s50, v234, 31
	v_readlane_b32 s58, v235, 31
	v_readlane_b32 s98, v236, 31
	v_readlane_b32 s100, v237, 31
	s_waitcnt vmcnt(22)
	v_pk_mul_f32 v[238:239], v[18:19], s[8:9] op_sel_hi:[1,0]
	v_pk_mul_f32 v[240:241], v[20:21], s[8:9] op_sel_hi:[1,0]
	v_pk_fma_f32 v[238:239], v[44:45], v[210:211], v[238:239]
	v_pk_fma_f32 v[240:241], v[44:45], v[212:213], v[240:241]
	v_pk_fma_f32 v[238:239], v[14:15], s[30:31], v[238:239] op_sel_hi:[1,0,1]
	v_pk_fma_f32 v[240:241], v[16:17], s[30:31], v[240:241] op_sel_hi:[1,0,1]
	v_pk_fma_f32 v[238:239], v[10:11], s[44:45], v[238:239] op_sel_hi:[1,0,1]
	v_pk_fma_f32 v[240:241], v[12:13], s[44:45], v[240:241] op_sel_hi:[1,0,1]
	v_pk_fma_f32 v[238:239], v[6:7], s[46:47], v[238:239] op_sel_hi:[1,0,1]
	v_pk_fma_f32 v[240:241], v[8:9], s[46:47], v[240:241] op_sel_hi:[1,0,1]
	v_pk_fma_f32 v[34:35], v[210:211], s[50:51], v[34:35] op_sel_hi:[1,0,1]
	v_pk_fma_f32 v[36:37], v[212:213], s[50:51], v[36:37] op_sel_hi:[1,0,1]
	v_pk_fma_f32 v[30:31], v[210:211], s[58:59], v[30:31] op_sel_hi:[1,0,1]
	v_pk_fma_f32 v[32:33], v[212:213], s[58:59], v[32:33] op_sel_hi:[1,0,1]
	v_pk_fma_f32 v[26:27], v[210:211], s[98:99], v[26:27] op_sel_hi:[1,0,1]
	v_pk_fma_f32 v[28:29], v[212:213], s[98:99], v[28:29] op_sel_hi:[1,0,1]
	v_pk_fma_f32 v[22:23], v[210:211], s[100:101], v[22:23] op_sel_hi:[1,0,1]
	v_pk_fma_f32 v[24:25], v[212:213], s[100:101], v[24:25] op_sel_hi:[1,0,1]
	global_store_dwordx4 v[246:247], v[238:241], off nt
	global_load_dwordx4 v[210:213], v[242:243], off nt
	v_lshl_add_u64 v[242:243], v[242:243], 0, v[248:249]
	v_lshl_add_u64 v[246:247], v[246:247], 0, v[248:249]
	v_readlane_b32 s8, v230, 32
	v_readlane_b32 s30, v231, 32
	v_readlane_b32 s44, v232, 32
	v_readlane_b32 s46, v233, 32
	v_readlane_b32 s50, v234, 32
	v_readlane_b32 s58, v235, 32
	v_readlane_b32 s98, v236, 32
	v_readlane_b32 s100, v237, 32
	s_waitcnt vmcnt(22)
; __device__ __forceinline__ void mlstm_sample_unit(Frame& F, const Args& a, int b, int h) {
;     ...
; #pragma unroll 16
;     for (int i = 0; i < 64; ++i) { const int d = 4 * i + rsub;
;         const f32x4 c0 = __builtin_nontemporal_load((const f32x4*)(Cin + (size_t)d * 512));
;         f32x4 cn = c0 * decay;
; #pragma unroll
;         for (int s = 0; s < 4; ++s) { cn += vs[s] * L[MS_KW + s * 256 + d]; qc[s] += c0 * L[MS_Q + s * 256 + d]; }
;         __builtin_nontemporal_store(cn, (f32x4*)(Cout + (size_t)d * 512)); }
	v_pk_mul_f32 v[238:239], v[18:19], s[8:9] op_sel_hi:[1,0]
	v_pk_mul_f32 v[240:241], v[20:21], s[8:9] op_sel_hi:[1,0]
	v_pk_fma_f32 v[238:239], v[44:45], v[214:215], v[238:239]
	v_pk_fma_f32 v[240:241], v[44:45], v[216:217], v[240:241]
	v_pk_fma_f32 v[238:239], v[14:15], s[30:31], v[238:239] op_sel_hi:[1,0,1]
	v_pk_fma_f32 v[240:241], v[16:17], s[30:31], v[240:241] op_sel_hi:[1,0,1]
	v_pk_fma_f32 v[238:239], v[10:11], s[44:45], v[238:239] op_sel_hi:[1,0,1]
	v_pk_fma_f32 v[240:241], v[12:13], s[44:45], v[240:241] op_sel_hi:[1,0,1]
	v_pk_fma_f32 v[238:239], v[6:7], s[46:47], v[238:239] op_sel_hi:[1,0,1]
	v_pk_fma_f32 v[240:241], v[8:9], s[46:47], v[240:241] op_sel_hi:[1,0,1]
	v_pk_fma_f32 v[34:35], v[214:215], s[50:51], v[34:35] op_sel_hi:[1,0,1]
	v_pk_fma_f32 v[36:37], v[216:217], s[50:51], v[36:37] op_sel_hi:[1,0,1]
	v_pk_fma_f32 v[30:31], v[214:215], s[58:59], v[30:31] op_sel_hi:[1,0,1]
	v_pk_fma_f32 v[32:33], v[216:217], s[58:59], v[32:33] op_sel_hi:[1,0,1]
	v_pk_fma_f32 v[26:27], v[214:215], s[98:99], v[26:27] op_sel_hi:[1,0,1]
	v_pk_fma_f32 v[28:29], v[216:217], s[98:99], v[28:29] op_sel_hi:[1,0,1]
	v_pk_fma_f32 v[22:23], v[214:215], s[100:101], v[22:23] op_sel_hi:[1,0,1]
	v_pk_fma_f32 v[24:25], v[216:217], s[100:101], v[24:25] op_sel_hi:[1,0,1]
	global_store_dwordx4 v[246:247], v[238:241], off nt
	global_load_dwordx4 v[214:217], v[242:243], off nt
	v_lshl_add_u64 v[242:243], v[242:243], 0, v[248:249]
	v_lshl_add_u64 v[246:247], v[246:247], 0, v[248:249]
	v_readlane_b32 s8, v230, 33
	v_readlane_b32 s30, v231, 33
	v_readlane_b32 s44, v232, 33
	v_readlane_b32 s46, v233, 33
	v_readlane_b32 s50, v234, 33
	v_readlane_b32 s58, v235, 33
	v_readlane_b32 s98, v236, 33
	v_readlane_b32 s100, v237, 33
	s_waitcnt vmcnt(22)
	v_pk_mul_f32 v[238:239], v[18:19], s[8:9] op_sel_hi:[1,0]
	v_pk_mul_f32 v[240:241], v[20:21], s[8:9] op_sel_hi:[1,0]
	v_pk_fma_f32 v[238:239], v[44:45], v[218:219], v[238:239]
	v_pk_fma_f32 v[240:241], v[44:45], v[220:221], v[240:241]
	v_pk_fma_f32 v[238:239], v[14:15], s[30:31], v[238:239] op_sel_hi:[1,0,1]
	v_pk_fma_f32 v[240:241], v[16:17], s[30:31], v[240:241] op_sel_hi:[1,0,1]
	v_pk_fma_f32 v[238:239], v[10:11], s[44:45], v[238:239] op_sel_hi:[1,0,1]
	v_pk_fma_f32 v[240:241], v[12:13], s[44:45], v[240:241] op_sel_hi:[1,0,1]
	v_pk_fma_f32 v[238:239], v[6:7], s[46:47], v[238:239] op_sel_hi:[1,0,1]
	v_pk_fma_f32 v[240:241], v[8:9], s[46:47], v[240:241] op_sel_hi:[1,0,1]
	v_pk_fma_f32 v[34:35], v[218:219], s[50:51], v[34:35] op_sel_hi:[1,0,1]
	v_pk_fma_f32 v[36:37], v[220:221], s[50:51], v[36:37] op_sel_hi:[1,0,1]
	v_pk_fma_f32 v[30:31], v[218:219], s[58:59], v[30:31] op_sel_hi:[1,0,1]
	v_pk_fma_f32 v[32:33], v[220:221], s[58:59], v[32:33] op_sel_hi:[1,0,1]
	v_pk_fma_f32 v[26:27], v[218:219], s[98:99], v[26:27] op_sel_hi:[1,0,1]
	v_pk_fma_f32 v[28:29], v[220:221], s[98:99], v[28:29] op_sel_hi:[1,0,1]
	v_pk_fma_f32 v[22:23], v[218:219], s[100:101], v[22:23] op_sel_hi:[1,0,1]
	v_pk_fma_f32 v[24:25], v[220:221], s[100:101], v[24:25] op_sel_hi:[1,0,1]
	global_store_dwordx4 v[246:247], v[238:241], off nt
	global_load_dwordx4 v[218:221], v[242:243], off nt
	v_lshl_add_u64 v[242:243], v[242:243], 0, v[248:249]
	v_lshl_add_u64 v[246:247], v[246:247], 0, v[248:249]
	v_readlane_b32 s8, v230, 34
	v_readlane_b32 s30, v231, 34
	v_readlane_b32 s44, v232, 34
	v_readlane_b32 s46, v233, 34
	v_readlane_b32 s50, v234, 34
	v_readlane_b32 s58, v235, 34
	v_readlane_b32 s98, v236, 34
	v_readlane_b32 s100, v237, 34
	s_waitcnt vmcnt(22)
	v_pk_mul_f32 v[238:239], v[18:19], s[8:9] op_sel_hi:[1,0]
	v_pk_mul_f32 v[240:241], v[20:21], s[8:9] op_sel_hi:[1,0]
	v_pk_fma_f32 v[238:239], v[44:45], v[222:223], v[238:239]
	v_pk_fma_f32 v[240:241], v[44:45], v[224:225], v[240:241]
	v_pk_fma_f32 v[238:239], v[14:15], s[30:31], v[238:239] op_sel_hi:[1,0,1]
	v_pk_fma_f32 v[240:241], v[16:17], s[30:31], v[240:241] op_sel_hi:[1,0,1]
	v_pk_fma_f32 v[238:239], v[10:11], s[44:45], v[238:239] op_sel_hi:[1,0,1]
	v_pk_fma_f32 v[240:241], v[12:13], s[44:45], v[240:241] op_sel_hi:[1,0,1]
	v_pk_fma_f32 v[238:239], v[6:7], s[46:47], v[238:239] op_sel_hi:[1,0,1]
	v_pk_fma_f32 v[240:241], v[8:9], s[46:47], v[240:241] op_sel_hi:[1,0,1]
	v_pk_fma_f32 v[34:35], v[222:223], s[50:51], v[34:35] op_sel_hi:[1,0,1]
	v_pk_fma_f32 v[36:37], v[224:225], s[50:51], v[36:37] op_sel_hi:[1,0,1]
	v_pk_fma_f32 v[30:31], v[222:223], s[58:59], v[30:31] op_sel_hi:[1,0,1]
	v_pk_fma_f32 v[32:33], v[224:225], s[58:59], v[32:33] op_sel_hi:[1,0,1]
	v_pk_fma_f32 v[26:27], v[222:223], s[98:99], v[26:27] op_sel_hi:[1,0,1]
	v_pk_fma_f32 v[28:29], v[224:225], s[98:99], v[28:29] op_sel_hi:[1,0,1]
	v_pk_fma_f32 v[22:23], v[222:223], s[100:101], v[22:23] op_sel_hi:[1,0,1]
	v_pk_fma_f32 v[24:25], v[224:225], s[100:101], v[24:25] op_sel_hi:[1,0,1]
	global_store_dwordx4 v[246:247], v[238:241], off nt
	global_load_dwordx4 v[222:225], v[242:243], off nt
	v_lshl_add_u64 v[242:243], v[242:243], 0, v[248:249]
	v_lshl_add_u64 v[246:247], v[246:247], 0, v[248:249]
	v_readlane_b32 s8, v230, 35
	v_readlane_b32 s30, v231, 35
	v_readlane_b32 s44, v232, 35
	v_readlane_b32 s46, v233, 35
	v_readlane_b32 s50, v234, 35
	v_readlane_b32 s58, v235, 35
	v_readlane_b32 s98, v236, 35
	v_readlane_b32 s100, v237, 35
	s_waitcnt vmcnt(22)
; __device__ __forceinline__ void mlstm_sample_unit(Frame& F, const Args& a, int b, int h) {
;     ...
; #pragma unroll 16
;     for (int i = 0; i < 64; ++i) { const int d = 4 * i + rsub;
;         const f32x4 c0 = __builtin_nontemporal_load((const f32x4*)(Cin + (size_t)d * 512));
;         f32x4 cn = c0 * decay;
; #pragma unroll
;         for (int s = 0; s < 4; ++s) { cn += vs[s] * L[MS_KW + s * 256 + d]; qc[s] += c0 * L[MS_Q + s * 256 + d]; }
;         __builtin_nontemporal_store(cn, (f32x4*)(Cout + (size_t)d * 512)); }
	v_pk_mul_f32 v[238:239], v[18:19], s[8:9] op_sel_hi:[1,0]
	v_pk_mul_f32 v[240:241], v[20:21], s[8:9] op_sel_hi:[1,0]
	v_pk_fma_f32 v[238:239], v[44:45], v[226:227], v[238:239]
	v_pk_fma_f32 v[240:241], v[44:45], v[228:229], v[240:241]
	v_pk_fma_f32 v[238:239], v[14:15], s[30:31], v[238:239] op_sel_hi:[1,0,1]
	v_pk_fma_f32 v[240:241], v[16:17], s[30:31], v[240:241] op_sel_hi:[1,0,1]
	v_pk_fma_f32 v[238:239], v[10:11], s[44:45], v[238:239] op_sel_hi:[1,0,1]
	v_pk_fma_f32 v[240:241], v[12:13], s[44:45], v[240:241] op_sel_hi:[1,0,1]
	v_pk_fma_f32 v[238:239], v[6:7], s[46:47], v[238:239] op_sel_hi:[1,0,1]
	v_pk_fma_f32 v[240:241], v[8:9], s[46:47], v[240:241] op_sel_hi:[1,0,1]
	v_pk_fma_f32 v[34:35], v[226:227], s[50:51], v[34:35] op_sel_hi:[1,0,1]
	v_pk_fma_f32 v[36:37], v[228:229], s[50:51], v[36:37] op_sel_hi:[1,0,1]
	v_pk_fma_f32 v[30:31], v[226:227], s[58:59], v[30:31] op_sel_hi:[1,0,1]
	v_pk_fma_f32 v[32:33], v[228:229], s[58:59], v[32:33] op_sel_hi:[1,0,1]
	v_pk_fma_f32 v[26:27], v[226:227], s[98:99], v[26:27] op_sel_hi:[1,0,1]
	v_pk_fma_f32 v[28:29], v[228:229], s[98:99], v[28:29] op_sel_hi:[1,0,1]
	v_pk_fma_f32 v[22:23], v[226:227], s[100:101], v[22:23] op_sel_hi:[1,0,1]
	v_pk_fma_f32 v[24:25], v[228:229], s[100:101], v[24:25] op_sel_hi:[1,0,1]
	global_store_dwordx4 v[246:247], v[238:241], off nt
	global_load_dwordx4 v[226:229], v[242:243], off nt
	v_lshl_add_u64 v[242:243], v[242:243], 0, v[248:249]
	v_lshl_add_u64 v[246:247], v[246:247], 0, v[248:249]
	v_readlane_b32 s8, v230, 36
	v_readlane_b32 s30, v231, 36
	v_readlane_b32 s44, v232, 36
	v_readlane_b32 s46, v233, 36
	v_readlane_b32 s50, v234, 36
	v_readlane_b32 s58, v235, 36
	v_readlane_b32 s98, v236, 36
	v_readlane_b32 s100, v237, 36
	s_waitcnt vmcnt(22)
	v_pk_mul_f32 v[238:239], v[18:19], s[8:9] op_sel_hi:[1,0]
	v_pk_mul_f32 v[240:241], v[20:21], s[8:9] op_sel_hi:[1,0]
	v_pk_fma_f32 v[238:239], v[44:45], v[182:183], v[238:239]
	v_pk_fma_f32 v[240:241], v[44:45], v[184:185], v[240:241]
	v_pk_fma_f32 v[238:239], v[14:15], s[30:31], v[238:239] op_sel_hi:[1,0,1]
	v_pk_fma_f32 v[240:241], v[16:17], s[30:31], v[240:241] op_sel_hi:[1,0,1]
	v_pk_fma_f32 v[238:239], v[10:11], s[44:45], v[238:239] op_sel_hi:[1,0,1]
	v_pk_fma_f32 v[240:241], v[12:13], s[44:45], v[240:241] op_sel_hi:[1,0,1]
	v_pk_fma_f32 v[238:239], v[6:7], s[46:47], v[238:239] op_sel_hi:[1,0,1]
	v_pk_fma_f32 v[240:241], v[8:9], s[46:47], v[240:241] op_sel_hi:[1,0,1]
	v_pk_fma_f32 v[34:35], v[182:183], s[50:51], v[34:35] op_sel_hi:[1,0,1]
	v_pk_fma_f32 v[36:37], v[184:185], s[50:51], v[36:37] op_sel_hi:[1,0,1]
	v_pk_fma_f32 v[30:31], v[182:183], s[58:59], v[30:31] op_sel_hi:[1,0,1]
	v_pk_fma_f32 v[32:33], v[184:185], s[58:59], v[32:33] op_sel_hi:[1,0,1]
	v_pk_fma_f32 v[26:27], v[182:183], s[98:99], v[26:27] op_sel_hi:[1,0,1]
	v_pk_fma_f32 v[28:29], v[184:185], s[98:99], v[28:29] op_sel_hi:[1,0,1]
	v_pk_fma_f32 v[22:23], v[182:183], s[100:101], v[22:23] op_sel_hi:[1,0,1]
	v_pk_fma_f32 v[24:25], v[184:185], s[100:101], v[24:25] op_sel_hi:[1,0,1]
	global_store_dwordx4 v[246:247], v[238:241], off nt
	global_load_dwordx4 v[182:185], v[242:243], off nt
	v_lshl_add_u64 v[242:243], v[242:243], 0, v[248:249]
	v_lshl_add_u64 v[246:247], v[246:247], 0, v[248:249]
	v_readlane_b32 s8, v230, 37
	v_readlane_b32 s30, v231, 37
	v_readlane_b32 s44, v232, 37
	v_readlane_b32 s46, v233, 37
	v_readlane_b32 s50, v234, 37
	v_readlane_b32 s58, v235, 37
	v_readlane_b32 s98, v236, 37
	v_readlane_b32 s100, v237, 37
	s_waitcnt vmcnt(22)
	v_pk_mul_f32 v[238:239], v[18:19], s[8:9] op_sel_hi:[1,0]
	v_pk_mul_f32 v[240:241], v[20:21], s[8:9] op_sel_hi:[1,0]
	v_pk_fma_f32 v[238:239], v[44:45], v[186:187], v[238:239]
	v_pk_fma_f32 v[240:241], v[44:45], v[188:189], v[240:241]
	v_pk_fma_f32 v[238:239], v[14:15], s[30:31], v[238:239] op_sel_hi:[1,0,1]
	v_pk_fma_f32 v[240:241], v[16:17], s[30:31], v[240:241] op_sel_hi:[1,0,1]
	v_pk_fma_f32 v[238:239], v[10:11], s[44:45], v[238:239] op_sel_hi:[1,0,1]
	v_pk_fma_f32 v[240:241], v[12:13], s[44:45], v[240:241] op_sel_hi:[1,0,1]
	v_pk_fma_f32 v[238:239], v[6:7], s[46:47], v[238:239] op_sel_hi:[1,0,1]
	v_pk_fma_f32 v[240:241], v[8:9], s[46:47], v[240:241] op_sel_hi:[1,0,1]
	v_pk_fma_f32 v[34:35], v[186:187], s[50:51], v[34:35] op_sel_hi:[1,0,1]
	v_pk_fma_f32 v[36:37], v[188:189], s[50:51], v[36:37] op_sel_hi:[1,0,1]
	v_pk_fma_f32 v[30:31], v[186:187], s[58:59], v[30:31] op_sel_hi:[1,0,1]
	v_pk_fma_f32 v[32:33], v[188:189], s[58:59], v[32:33] op_sel_hi:[1,0,1]
	v_pk_fma_f32 v[26:27], v[186:187], s[98:99], v[26:27] op_sel_hi:[1,0,1]
	v_pk_fma_f32 v[28:29], v[188:189], s[98:99], v[28:29] op_sel_hi:[1,0,1]
	v_pk_fma_f32 v[22:23], v[186:187], s[100:101], v[22:23] op_sel_hi:[1,0,1]
	v_pk_fma_f32 v[24:25], v[188:189], s[100:101], v[24:25] op_sel_hi:[1,0,1]
	global_store_dwordx4 v[246:247], v[238:241], off nt
	global_load_dwordx4 v[186:189], v[242:243], off nt
	v_lshl_add_u64 v[242:243], v[242:243], 0, v[248:249]
	v_lshl_add_u64 v[246:247], v[246:247], 0, v[248:249]
	v_readlane_b32 s8, v230, 38
	v_readlane_b32 s30, v231, 38
	v_readlane_b32 s44, v232, 38
	v_readlane_b32 s46, v233, 38
	v_readlane_b32 s50, v234, 38
	v_readlane_b32 s58, v235, 38
	v_readlane_b32 s98, v236, 38
	v_readlane_b32 s100, v237, 38
	s_waitcnt vmcnt(22)
; __device__ __forceinline__ void mlstm_sample_unit(Frame& F, const Args& a, int b, int h) {
;     ...
; #pragma unroll 16
;     for (int i = 0; i < 64; ++i) { const int d = 4 * i + rsub;
;         const f32x4 c0 = __builtin_nontemporal_load((const f32x4*)(Cin + (size_t)d * 512));
;         f32x4 cn = c0 * decay;
; #pragma unroll
;         for (int s = 0; s < 4; ++s) { cn += vs[s] * L[MS_KW + s * 256 + d]; qc[s] += c0 * L[MS_Q + s * 256 + d]; }
;         __builtin_nontemporal_store(cn, (f32x4*)(Cout + (size_t)d * 512)); }
	v_pk_mul_f32 v[238:239], v[18:19], s[8:9] op_sel_hi:[1,0]
	v_pk_mul_f32 v[240:241], v[20:21], s[8:9] op_sel_hi:[1,0]
	v_pk_fma_f32 v[238:239], v[44:45], v[190:191], v[238:239]
	v_pk_fma_f32 v[240:241], v[44:45], v[192:193], v[240:241]
	v_pk_fma_f32 v[238:239], v[14:15], s[30:31], v[238:239] op_sel_hi:[1,0,1]
	v_pk_fma_f32 v[240:241], v[16:17], s[30:31], v[240:241] op_sel_hi:[1,0,1]
	v_pk_fma_f32 v[238:239], v[10:11], s[44:45], v[238:239] op_sel_hi:[1,0,1]
	v_pk_fma_f32 v[240:241], v[12:13], s[44:45], v[240:241] op_sel_hi:[1,0,1]
	v_pk_fma_f32 v[238:239], v[6:7], s[46:47], v[238:239] op_sel_hi:[1,0,1]
	v_pk_fma_f32 v[240:241], v[8:9], s[46:47], v[240:241] op_sel_hi:[1,0,1]
	v_pk_fma_f32 v[34:35], v[190:191], s[50:51], v[34:35] op_sel_hi:[1,0,1]
	v_pk_fma_f32 v[36:37], v[192:193], s[50:51], v[36:37] op_sel_hi:[1,0,1]
	v_pk_fma_f32 v[30:31], v[190:191], s[58:59], v[30:31] op_sel_hi:[1,0,1]
	v_pk_fma_f32 v[32:33], v[192:193], s[58:59], v[32:33] op_sel_hi:[1,0,1]
	v_pk_fma_f32 v[26:27], v[190:191], s[98:99], v[26:27] op_sel_hi:[1,0,1]
	v_pk_fma_f32 v[28:29], v[192:193], s[98:99], v[28:29] op_sel_hi:[1,0,1]
	v_pk_fma_f32 v[22:23], v[190:191], s[100:101], v[22:23] op_sel_hi:[1,0,1]
	v_pk_fma_f32 v[24:25], v[192:193], s[100:101], v[24:25] op_sel_hi:[1,0,1]
	global_store_dwordx4 v[246:247], v[238:241], off nt
	global_load_dwordx4 v[190:193], v[242:243], off nt
	v_lshl_add_u64 v[242:243], v[242:243], 0, v[248:249]
	v_lshl_add_u64 v[246:247], v[246:247], 0, v[248:249]
	v_readlane_b32 s8, v230, 39
	v_readlane_b32 s30, v231, 39
	v_readlane_b32 s44, v232, 39
	v_readlane_b32 s46, v233, 39
	v_readlane_b32 s50, v234, 39
	v_readlane_b32 s58, v235, 39
	v_readlane_b32 s98, v236, 39
	v_readlane_b32 s100, v237, 39
	s_waitcnt vmcnt(22)
	v_pk_mul_f32 v[238:239], v[18:19], s[8:9] op_sel_hi:[1,0]
	v_pk_mul_f32 v[240:241], v[20:21], s[8:9] op_sel_hi:[1,0]
	v_pk_fma_f32 v[238:239], v[44:45], v[194:195], v[238:239]
	v_pk_fma_f32 v[240:241], v[44:45], v[196:197], v[240:241]
	v_pk_fma_f32 v[238:239], v[14:15], s[30:31], v[238:239] op_sel_hi:[1,0,1]
	v_pk_fma_f32 v[240:241], v[16:17], s[30:31], v[240:241] op_sel_hi:[1,0,1]
	v_pk_fma_f32 v[238:239], v[10:11], s[44:45], v[238:239] op_sel_hi:[1,0,1]
	v_pk_fma_f32 v[240:241], v[12:13], s[44:45], v[240:241] op_sel_hi:[1,0,1]
	v_pk_fma_f32 v[238:239], v[6:7], s[46:47], v[238:239] op_sel_hi:[1,0,1]
	v_pk_fma_f32 v[240:241], v[8:9], s[46:47], v[240:241] op_sel_hi:[1,0,1]
	v_pk_fma_f32 v[34:35], v[194:195], s[50:51], v[34:35] op_sel_hi:[1,0,1]
	v_pk_fma_f32 v[36:37], v[196:197], s[50:51], v[36:37] op_sel_hi:[1,0,1]
	v_pk_fma_f32 v[30:31], v[194:195], s[58:59], v[30:31] op_sel_hi:[1,0,1]
	v_pk_fma_f32 v[32:33], v[196:197], s[58:59], v[32:33] op_sel_hi:[1,0,1]
	v_pk_fma_f32 v[26:27], v[194:195], s[98:99], v[26:27] op_sel_hi:[1,0,1]
	v_pk_fma_f32 v[28:29], v[196:197], s[98:99], v[28:29] op_sel_hi:[1,0,1]
	v_pk_fma_f32 v[22:23], v[194:195], s[100:101], v[22:23] op_sel_hi:[1,0,1]
	v_pk_fma_f32 v[24:25], v[196:197], s[100:101], v[24:25] op_sel_hi:[1,0,1]
	global_store_dwordx4 v[246:247], v[238:241], off nt
	global_load_dwordx4 v[194:197], v[242:243], off nt
	v_lshl_add_u64 v[242:243], v[242:243], 0, v[248:249]
	v_lshl_add_u64 v[246:247], v[246:247], 0, v[248:249]
	v_readlane_b32 s8, v230, 40
	v_readlane_b32 s30, v231, 40
	v_readlane_b32 s44, v232, 40
	v_readlane_b32 s46, v233, 40
	v_readlane_b32 s50, v234, 40
	v_readlane_b32 s58, v235, 40
	v_readlane_b32 s98, v236, 40
	v_readlane_b32 s100, v237, 40
	s_waitcnt vmcnt(22)
	v_pk_mul_f32 v[238:239], v[18:19], s[8:9] op_sel_hi:[1,0]
	v_pk_mul_f32 v[240:241], v[20:21], s[8:9] op_sel_hi:[1,0]
	v_pk_fma_f32 v[238:239], v[44:45], v[198:199], v[238:239]
	v_pk_fma_f32 v[240:241], v[44:45], v[200:201], v[240:241]
	v_pk_fma_f32 v[238:239], v[14:15], s[30:31], v[238:239] op_sel_hi:[1,0,1]
	v_pk_fma_f32 v[240:241], v[16:17], s[30:31], v[240:241] op_sel_hi:[1,0,1]
	v_pk_fma_f32 v[238:239], v[10:11], s[44:45], v[238:239] op_sel_hi:[1,0,1]
	v_pk_fma_f32 v[240:241], v[12:13], s[44:45], v[240:241] op_sel_hi:[1,0,1]
	v_pk_fma_f32 v[238:239], v[6:7], s[46:47], v[238:239] op_sel_hi:[1,0,1]
	v_pk_fma_f32 v[240:241], v[8:9], s[46:47], v[240:241] op_sel_hi:[1,0,1]
	v_pk_fma_f32 v[34:35], v[198:199], s[50:51], v[34:35] op_sel_hi:[1,0,1]
	v_pk_fma_f32 v[36:37], v[200:201], s[50:51], v[36:37] op_sel_hi:[1,0,1]
	v_pk_fma_f32 v[30:31], v[198:199], s[58:59], v[30:31] op_sel_hi:[1,0,1]
	v_pk_fma_f32 v[32:33], v[200:201], s[58:59], v[32:33] op_sel_hi:[1,0,1]
	v_pk_fma_f32 v[26:27], v[198:199], s[98:99], v[26:27] op_sel_hi:[1,0,1]
	v_pk_fma_f32 v[28:29], v[200:201], s[98:99], v[28:29] op_sel_hi:[1,0,1]
	v_pk_fma_f32 v[22:23], v[198:199], s[100:101], v[22:23] op_sel_hi:[1,0,1]
	v_pk_fma_f32 v[24:25], v[200:201], s[100:101], v[24:25] op_sel_hi:[1,0,1]
	global_store_dwordx4 v[246:247], v[238:241], off nt
	global_load_dwordx4 v[198:201], v[242:243], off nt
	v_lshl_add_u64 v[242:243], v[242:243], 0, v[248:249]
	v_lshl_add_u64 v[246:247], v[246:247], 0, v[248:249]
	v_readlane_b32 s8, v230, 41
	v_readlane_b32 s30, v231, 41
	v_readlane_b32 s44, v232, 41
	v_readlane_b32 s46, v233, 41
	v_readlane_b32 s50, v234, 41
	v_readlane_b32 s58, v235, 41
	v_readlane_b32 s98, v236, 41
	v_readlane_b32 s100, v237, 41
	s_waitcnt vmcnt(22)
; __device__ __forceinline__ void mlstm_sample_unit(Frame& F, const Args& a, int b, int h) {
;     ...
; #pragma unroll 16
;     for (int i = 0; i < 64; ++i) { const int d = 4 * i + rsub;
;         const f32x4 c0 = __builtin_nontemporal_load((const f32x4*)(Cin + (size_t)d * 512));
;         f32x4 cn = c0 * decay;
; #pragma unroll
;         for (int s = 0; s < 4; ++s) { cn += vs[s] * L[MS_KW + s * 256 + d]; qc[s] += c0 * L[MS_Q + s * 256 + d]; }
;         __builtin_nontemporal_store(cn, (f32x4*)(Cout + (size_t)d * 512)); }
	v_pk_mul_f32 v[238:239], v[18:19], s[8:9] op_sel_hi:[1,0]
	v_pk_mul_f32 v[240:241], v[20:21], s[8:9] op_sel_hi:[1,0]
	v_pk_fma_f32 v[238:239], v[44:45], v[202:203], v[238:239]
	v_pk_fma_f32 v[240:241], v[44:45], v[204:205], v[240:241]
	v_pk_fma_f32 v[238:239], v[14:15], s[30:31], v[238:239] op_sel_hi:[1,0,1]
	v_pk_fma_f32 v[240:241], v[16:17], s[30:31], v[240:241] op_sel_hi:[1,0,1]
	v_pk_fma_f32 v[238:239], v[10:11], s[44:45], v[238:239] op_sel_hi:[1,0,1]
	v_pk_fma_f32 v[240:241], v[12:13], s[44:45], v[240:241] op_sel_hi:[1,0,1]
	v_pk_fma_f32 v[238:239], v[6:7], s[46:47], v[238:239] op_sel_hi:[1,0,1]
	v_pk_fma_f32 v[240:241], v[8:9], s[46:47], v[240:241] op_sel_hi:[1,0,1]
	v_pk_fma_f32 v[34:35], v[202:203], s[50:51], v[34:35] op_sel_hi:[1,0,1]
	v_pk_fma_f32 v[36:37], v[204:205], s[50:51], v[36:37] op_sel_hi:[1,0,1]
	v_pk_fma_f32 v[30:31], v[202:203], s[58:59], v[30:31] op_sel_hi:[1,0,1]
	v_pk_fma_f32 v[32:33], v[204:205], s[58:59], v[32:33] op_sel_hi:[1,0,1]
	v_pk_fma_f32 v[26:27], v[202:203], s[98:99], v[26:27] op_sel_hi:[1,0,1]
	v_pk_fma_f32 v[28:29], v[204:205], s[98:99], v[28:29] op_sel_hi:[1,0,1]
	v_pk_fma_f32 v[22:23], v[202:203], s[100:101], v[22:23] op_sel_hi:[1,0,1]
	v_pk_fma_f32 v[24:25], v[204:205], s[100:101], v[24:25] op_sel_hi:[1,0,1]
	global_store_dwordx4 v[246:247], v[238:241], off nt
	global_load_dwordx4 v[202:205], v[242:243], off nt
	v_lshl_add_u64 v[242:243], v[242:243], 0, v[248:249]
	v_lshl_add_u64 v[246:247], v[246:247], 0, v[248:249]
	v_readlane_b32 s8, v230, 42
	v_readlane_b32 s30, v231, 42
	v_readlane_b32 s44, v232, 42
	v_readlane_b32 s46, v233, 42
	v_readlane_b32 s50, v234, 42
	v_readlane_b32 s58, v235, 42
	v_readlane_b32 s98, v236, 42
	v_readlane_b32 s100, v237, 42
	s_waitcnt vmcnt(22)
	v_pk_mul_f32 v[238:239], v[18:19], s[8:9] op_sel_hi:[1,0]
	v_pk_mul_f32 v[240:241], v[20:21], s[8:9] op_sel_hi:[1,0]
	v_pk_fma_f32 v[238:239], v[44:45], v[206:207], v[238:239]
	v_pk_fma_f32 v[240:241], v[44:45], v[208:209], v[240:241]
	v_pk_fma_f32 v[238:239], v[14:15], s[30:31], v[238:239] op_sel_hi:[1,0,1]
	v_pk_fma_f32 v[240:241], v[16:17], s[30:31], v[240:241] op_sel_hi:[1,0,1]
	v_pk_fma_f32 v[238:239], v[10:11], s[44:45], v[238:239] op_sel_hi:[1,0,1]
	v_pk_fma_f32 v[240:241], v[12:13], s[44:45], v[240:241] op_sel_hi:[1,0,1]
	v_pk_fma_f32 v[238:239], v[6:7], s[46:47], v[238:239] op_sel_hi:[1,0,1]
	v_pk_fma_f32 v[240:241], v[8:9], s[46:47], v[240:241] op_sel_hi:[1,0,1]
	v_pk_fma_f32 v[34:35], v[206:207], s[50:51], v[34:35] op_sel_hi:[1,0,1]
	v_pk_fma_f32 v[36:37], v[208:209], s[50:51], v[36:37] op_sel_hi:[1,0,1]
	v_pk_fma_f32 v[30:31], v[206:207], s[58:59], v[30:31] op_sel_hi:[1,0,1]
	v_pk_fma_f32 v[32:33], v[208:209], s[58:59], v[32:33] op_sel_hi:[1,0,1]
	v_pk_fma_f32 v[26:27], v[206:207], s[98:99], v[26:27] op_sel_hi:[1,0,1]
	v_pk_fma_f32 v[28:29], v[208:209], s[98:99], v[28:29] op_sel_hi:[1,0,1]
	v_pk_fma_f32 v[22:23], v[206:207], s[100:101], v[22:23] op_sel_hi:[1,0,1]
	v_pk_fma_f32 v[24:25], v[208:209], s[100:101], v[24:25] op_sel_hi:[1,0,1]
	global_store_dwordx4 v[246:247], v[238:241], off nt
	global_load_dwordx4 v[206:209], v[242:243], off nt
	v_lshl_add_u64 v[242:243], v[242:243], 0, v[248:249]
	v_lshl_add_u64 v[246:247], v[246:247], 0, v[248:249]
	v_readlane_b32 s8, v230, 43
	v_readlane_b32 s30, v231, 43
	v_readlane_b32 s44, v232, 43
	v_readlane_b32 s46, v233, 43
	v_readlane_b32 s50, v234, 43
	v_readlane_b32 s58, v235, 43
	v_readlane_b32 s98, v236, 43
	v_readlane_b32 s100, v237, 43
	s_waitcnt vmcnt(22)
	v_pk_mul_f32 v[238:239], v[18:19], s[8:9] op_sel_hi:[1,0]
	v_pk_mul_f32 v[240:241], v[20:21], s[8:9] op_sel_hi:[1,0]
	v_pk_fma_f32 v[238:239], v[44:45], v[210:211], v[238:239]
	v_pk_fma_f32 v[240:241], v[44:45], v[212:213], v[240:241]
	v_pk_fma_f32 v[238:239], v[14:15], s[30:31], v[238:239] op_sel_hi:[1,0,1]
	v_pk_fma_f32 v[240:241], v[16:17], s[30:31], v[240:241] op_sel_hi:[1,0,1]
	v_pk_fma_f32 v[238:239], v[10:11], s[44:45], v[238:239] op_sel_hi:[1,0,1]
	v_pk_fma_f32 v[240:241], v[12:13], s[44:45], v[240:241] op_sel_hi:[1,0,1]
	v_pk_fma_f32 v[238:239], v[6:7], s[46:47], v[238:239] op_sel_hi:[1,0,1]
	v_pk_fma_f32 v[240:241], v[8:9], s[46:47], v[240:241] op_sel_hi:[1,0,1]
	v_pk_fma_f32 v[34:35], v[210:211], s[50:51], v[34:35] op_sel_hi:[1,0,1]
	v_pk_fma_f32 v[36:37], v[212:213], s[50:51], v[36:37] op_sel_hi:[1,0,1]
	v_pk_fma_f32 v[30:31], v[210:211], s[58:59], v[30:31] op_sel_hi:[1,0,1]
	v_pk_fma_f32 v[32:33], v[212:213], s[58:59], v[32:33] op_sel_hi:[1,0,1]
	v_pk_fma_f32 v[26:27], v[210:211], s[98:99], v[26:27] op_sel_hi:[1,0,1]
	v_pk_fma_f32 v[28:29], v[212:213], s[98:99], v[28:29] op_sel_hi:[1,0,1]
	v_pk_fma_f32 v[22:23], v[210:211], s[100:101], v[22:23] op_sel_hi:[1,0,1]
	v_pk_fma_f32 v[24:25], v[212:213], s[100:101], v[24:25] op_sel_hi:[1,0,1]
	global_store_dwordx4 v[246:247], v[238:241], off nt
	global_load_dwordx4 v[210:213], v[242:243], off nt
	v_lshl_add_u64 v[242:243], v[242:243], 0, v[248:249]
	v_lshl_add_u64 v[246:247], v[246:247], 0, v[248:249]
	v_readlane_b32 s8, v230, 44
	v_readlane_b32 s30, v231, 44
	v_readlane_b32 s44, v232, 44
	v_readlane_b32 s46, v233, 44
	v_readlane_b32 s50, v234, 44
	v_readlane_b32 s58, v235, 44
	v_readlane_b32 s98, v236, 44
	v_readlane_b32 s100, v237, 44
	s_waitcnt vmcnt(22)
; __device__ __forceinline__ void mlstm_sample_unit(Frame& F, const Args& a, int b, int h) {
;     ...
; #pragma unroll 16
;     for (int i = 0; i < 64; ++i) { const int d = 4 * i + rsub;
;         const f32x4 c0 = __builtin_nontemporal_load((const f32x4*)(Cin + (size_t)d * 512));
;         f32x4 cn = c0 * decay;
; #pragma unroll
;         for (int s = 0; s < 4; ++s) { cn += vs[s] * L[MS_KW + s * 256 + d]; qc[s] += c0 * L[MS_Q + s * 256 + d]; }
;         __builtin_nontemporal_store(cn, (f32x4*)(Cout + (size_t)d * 512)); }
	v_pk_mul_f32 v[238:239], v[18:19], s[8:9] op_sel_hi:[1,0]
	v_pk_mul_f32 v[240:241], v[20:21], s[8:9] op_sel_hi:[1,0]
	v_pk_fma_f32 v[238:239], v[44:45], v[214:215], v[238:239]
	v_pk_fma_f32 v[240:241], v[44:45], v[216:217], v[240:241]
	v_pk_fma_f32 v[238:239], v[14:15], s[30:31], v[238:239] op_sel_hi:[1,0,1]
	v_pk_fma_f32 v[240:241], v[16:17], s[30:31], v[240:241] op_sel_hi:[1,0,1]
	v_pk_fma_f32 v[238:239], v[10:11], s[44:45], v[238:239] op_sel_hi:[1,0,1]
	v_pk_fma_f32 v[240:241], v[12:13], s[44:45], v[240:241] op_sel_hi:[1,0,1]
	v_pk_fma_f32 v[238:239], v[6:7], s[46:47], v[238:239] op_sel_hi:[1,0,1]
	v_pk_fma_f32 v[240:241], v[8:9], s[46:47], v[240:241] op_sel_hi:[1,0,1]
	v_pk_fma_f32 v[34:35], v[214:215], s[50:51], v[34:35] op_sel_hi:[1,0,1]
	v_pk_fma_f32 v[36:37], v[216:217], s[50:51], v[36:37] op_sel_hi:[1,0,1]
	v_pk_fma_f32 v[30:31], v[214:215], s[58:59], v[30:31] op_sel_hi:[1,0,1]
	v_pk_fma_f32 v[32:33], v[216:217], s[58:59], v[32:33] op_sel_hi:[1,0,1]
	v_pk_fma_f32 v[26:27], v[214:215], s[98:99], v[26:27] op_sel_hi:[1,0,1]
	v_pk_fma_f32 v[28:29], v[216:217], s[98:99], v[28:29] op_sel_hi:[1,0,1]
	v_pk_fma_f32 v[22:23], v[214:215], s[100:101], v[22:23] op_sel_hi:[1,0,1]
	v_pk_fma_f32 v[24:25], v[216:217], s[100:101], v[24:25] op_sel_hi:[1,0,1]
	global_store_dwordx4 v[246:247], v[238:241], off nt
	global_load_dwordx4 v[214:217], v[242:243], off nt
	v_lshl_add_u64 v[242:243], v[242:243], 0, v[248:249]
	v_lshl_add_u64 v[246:247], v[246:247], 0, v[248:249]
	v_readlane_b32 s8, v230, 45
	v_readlane_b32 s30, v231, 45
	v_readlane_b32 s44, v232, 45
	v_readlane_b32 s46, v233, 45
	v_readlane_b32 s50, v234, 45
	v_readlane_b32 s58, v235, 45
	v_readlane_b32 s98, v236, 45
	v_readlane_b32 s100, v237, 45
	s_waitcnt vmcnt(22)
	v_pk_mul_f32 v[238:239], v[18:19], s[8:9] op_sel_hi:[1,0]
	v_pk_mul_f32 v[240:241], v[20:21], s[8:9] op_sel_hi:[1,0]
	v_pk_fma_f32 v[238:239], v[44:45], v[218:219], v[238:239]
	v_pk_fma_f32 v[240:241], v[44:45], v[220:221], v[240:241]
	v_pk_fma_f32 v[238:239], v[14:15], s[30:31], v[238:239] op_sel_hi:[1,0,1]
	v_pk_fma_f32 v[240:241], v[16:17], s[30:31], v[240:241] op_sel_hi:[1,0,1]
	v_pk_fma_f32 v[238:239], v[10:11], s[44:45], v[238:239] op_sel_hi:[1,0,1]
	v_pk_fma_f32 v[240:241], v[12:13], s[44:45], v[240:241] op_sel_hi:[1,0,1]
	v_pk_fma_f32 v[238:239], v[6:7], s[46:47], v[238:239] op_sel_hi:[1,0,1]
	v_pk_fma_f32 v[240:241], v[8:9], s[46:47], v[240:241] op_sel_hi:[1,0,1]
	v_pk_fma_f32 v[34:35], v[218:219], s[50:51], v[34:35] op_sel_hi:[1,0,1]
	v_pk_fma_f32 v[36:37], v[220:221], s[50:51], v[36:37] op_sel_hi:[1,0,1]
	v_pk_fma_f32 v[30:31], v[218:219], s[58:59], v[30:31] op_sel_hi:[1,0,1]
	v_pk_fma_f32 v[32:33], v[220:221], s[58:59], v[32:33] op_sel_hi:[1,0,1]
	v_pk_fma_f32 v[26:27], v[218:219], s[98:99], v[26:27] op_sel_hi:[1,0,1]
	v_pk_fma_f32 v[28:29], v[220:221], s[98:99], v[28:29] op_sel_hi:[1,0,1]
	v_pk_fma_f32 v[22:23], v[218:219], s[100:101], v[22:23] op_sel_hi:[1,0,1]
	v_pk_fma_f32 v[24:25], v[220:221], s[100:101], v[24:25] op_sel_hi:[1,0,1]
	global_store_dwordx4 v[246:247], v[238:241], off nt
	global_load_dwordx4 v[218:221], v[242:243], off nt
	v_lshl_add_u64 v[242:243], v[242:243], 0, v[248:249]
	v_lshl_add_u64 v[246:247], v[246:247], 0, v[248:249]
	v_readlane_b32 s8, v230, 46
	v_readlane_b32 s30, v231, 46
	v_readlane_b32 s44, v232, 46
	v_readlane_b32 s46, v233, 46
	v_readlane_b32 s50, v234, 46
	v_readlane_b32 s58, v235, 46
	v_readlane_b32 s98, v236, 46
	v_readlane_b32 s100, v237, 46
	s_waitcnt vmcnt(22)
	v_pk_mul_f32 v[238:239], v[18:19], s[8:9] op_sel_hi:[1,0]
	v_pk_mul_f32 v[240:241], v[20:21], s[8:9] op_sel_hi:[1,0]
	v_pk_fma_f32 v[238:239], v[44:45], v[222:223], v[238:239]
	v_pk_fma_f32 v[240:241], v[44:45], v[224:225], v[240:241]
	v_pk_fma_f32 v[238:239], v[14:15], s[30:31], v[238:239] op_sel_hi:[1,0,1]
	v_pk_fma_f32 v[240:241], v[16:17], s[30:31], v[240:241] op_sel_hi:[1,0,1]
	v_pk_fma_f32 v[238:239], v[10:11], s[44:45], v[238:239] op_sel_hi:[1,0,1]
	v_pk_fma_f32 v[240:241], v[12:13], s[44:45], v[240:241] op_sel_hi:[1,0,1]
	v_pk_fma_f32 v[238:239], v[6:7], s[46:47], v[238:239] op_sel_hi:[1,0,1]
	v_pk_fma_f32 v[240:241], v[8:9], s[46:47], v[240:241] op_sel_hi:[1,0,1]
	v_pk_fma_f32 v[34:35], v[222:223], s[50:51], v[34:35] op_sel_hi:[1,0,1]
	v_pk_fma_f32 v[36:37], v[224:225], s[50:51], v[36:37] op_sel_hi:[1,0,1]
	v_pk_fma_f32 v[30:31], v[222:223], s[58:59], v[30:31] op_sel_hi:[1,0,1]
	v_pk_fma_f32 v[32:33], v[224:225], s[58:59], v[32:33] op_sel_hi:[1,0,1]
	v_pk_fma_f32 v[26:27], v[222:223], s[98:99], v[26:27] op_sel_hi:[1,0,1]
	v_pk_fma_f32 v[28:29], v[224:225], s[98:99], v[28:29] op_sel_hi:[1,0,1]
	v_pk_fma_f32 v[22:23], v[222:223], s[100:101], v[22:23] op_sel_hi:[1,0,1]
	v_pk_fma_f32 v[24:25], v[224:225], s[100:101], v[24:25] op_sel_hi:[1,0,1]
	global_store_dwordx4 v[246:247], v[238:241], off nt
	global_load_dwordx4 v[222:225], v[242:243], off nt
	v_lshl_add_u64 v[242:243], v[242:243], 0, v[248:249]
	v_lshl_add_u64 v[246:247], v[246:247], 0, v[248:249]
	v_readlane_b32 s8, v230, 47
	v_readlane_b32 s30, v231, 47
	v_readlane_b32 s44, v232, 47
	v_readlane_b32 s46, v233, 47
	v_readlane_b32 s50, v234, 47
	v_readlane_b32 s58, v235, 47
	v_readlane_b32 s98, v236, 47
	v_readlane_b32 s100, v237, 47
	s_waitcnt vmcnt(22)
; __device__ __forceinline__ void mlstm_sample_unit(Frame& F, const Args& a, int b, int h) {
;     ...
; #pragma unroll 16
;     for (int i = 0; i < 64; ++i) { const int d = 4 * i + rsub;
;         const f32x4 c0 = __builtin_nontemporal_load((const f32x4*)(Cin + (size_t)d * 512));
;         f32x4 cn = c0 * decay;
; #pragma unroll
;         for (int s = 0; s < 4; ++s) { cn += vs[s] * L[MS_KW + s * 256 + d]; qc[s] += c0 * L[MS_Q + s * 256 + d]; }
;         __builtin_nontemporal_store(cn, (f32x4*)(Cout + (size_t)d * 512)); }
	v_pk_mul_f32 v[238:239], v[18:19], s[8:9] op_sel_hi:[1,0]
	v_pk_mul_f32 v[240:241], v[20:21], s[8:9] op_sel_hi:[1,0]
	v_pk_fma_f32 v[238:239], v[44:45], v[226:227], v[238:239]
	v_pk_fma_f32 v[240:241], v[44:45], v[228:229], v[240:241]
	v_pk_fma_f32 v[238:239], v[14:15], s[30:31], v[238:239] op_sel_hi:[1,0,1]
	v_pk_fma_f32 v[240:241], v[16:17], s[30:31], v[240:241] op_sel_hi:[1,0,1]
	v_pk_fma_f32 v[238:239], v[10:11], s[44:45], v[238:239] op_sel_hi:[1,0,1]
	v_pk_fma_f32 v[240:241], v[12:13], s[44:45], v[240:241] op_sel_hi:[1,0,1]
	v_pk_fma_f32 v[238:239], v[6:7], s[46:47], v[238:239] op_sel_hi:[1,0,1]
	v_pk_fma_f32 v[240:241], v[8:9], s[46:47], v[240:241] op_sel_hi:[1,0,1]
	v_pk_fma_f32 v[34:35], v[226:227], s[50:51], v[34:35] op_sel_hi:[1,0,1]
	v_pk_fma_f32 v[36:37], v[228:229], s[50:51], v[36:37] op_sel_hi:[1,0,1]
	v_pk_fma_f32 v[30:31], v[226:227], s[58:59], v[30:31] op_sel_hi:[1,0,1]
	v_pk_fma_f32 v[32:33], v[228:229], s[58:59], v[32:33] op_sel_hi:[1,0,1]
	v_pk_fma_f32 v[26:27], v[226:227], s[98:99], v[26:27] op_sel_hi:[1,0,1]
	v_pk_fma_f32 v[28:29], v[228:229], s[98:99], v[28:29] op_sel_hi:[1,0,1]
	v_pk_fma_f32 v[22:23], v[226:227], s[100:101], v[22:23] op_sel_hi:[1,0,1]
	v_pk_fma_f32 v[24:25], v[228:229], s[100:101], v[24:25] op_sel_hi:[1,0,1]
	global_store_dwordx4 v[246:247], v[238:241], off nt
	global_load_dwordx4 v[226:229], v[242:243], off nt
	v_lshl_add_u64 v[242:243], v[242:243], 0, v[248:249]
	v_lshl_add_u64 v[246:247], v[246:247], 0, v[248:249]
	v_readlane_b32 s8, v230, 48
	v_readlane_b32 s30, v231, 48
	v_readlane_b32 s44, v232, 48
	v_readlane_b32 s46, v233, 48
	v_readlane_b32 s50, v234, 48
	v_readlane_b32 s58, v235, 48
	v_readlane_b32 s98, v236, 48
	v_readlane_b32 s100, v237, 48
	s_waitcnt vmcnt(22)
	v_pk_mul_f32 v[238:239], v[18:19], s[8:9] op_sel_hi:[1,0]
	v_pk_mul_f32 v[240:241], v[20:21], s[8:9] op_sel_hi:[1,0]
	v_pk_fma_f32 v[238:239], v[44:45], v[182:183], v[238:239]
	v_pk_fma_f32 v[240:241], v[44:45], v[184:185], v[240:241]
	v_pk_fma_f32 v[238:239], v[14:15], s[30:31], v[238:239] op_sel_hi:[1,0,1]
	v_pk_fma_f32 v[240:241], v[16:17], s[30:31], v[240:241] op_sel_hi:[1,0,1]
	v_pk_fma_f32 v[238:239], v[10:11], s[44:45], v[238:239] op_sel_hi:[1,0,1]
	v_pk_fma_f32 v[240:241], v[12:13], s[44:45], v[240:241] op_sel_hi:[1,0,1]
	v_pk_fma_f32 v[238:239], v[6:7], s[46:47], v[238:239] op_sel_hi:[1,0,1]
	v_pk_fma_f32 v[240:241], v[8:9], s[46:47], v[240:241] op_sel_hi:[1,0,1]
	v_pk_fma_f32 v[34:35], v[182:183], s[50:51], v[34:35] op_sel_hi:[1,0,1]
	v_pk_fma_f32 v[36:37], v[184:185], s[50:51], v[36:37] op_sel_hi:[1,0,1]
	v_pk_fma_f32 v[30:31], v[182:183], s[58:59], v[30:31] op_sel_hi:[1,0,1]
	v_pk_fma_f32 v[32:33], v[184:185], s[58:59], v[32:33] op_sel_hi:[1,0,1]
	v_pk_fma_f32 v[26:27], v[182:183], s[98:99], v[26:27] op_sel_hi:[1,0,1]
	v_pk_fma_f32 v[28:29], v[184:185], s[98:99], v[28:29] op_sel_hi:[1,0,1]
	v_pk_fma_f32 v[22:23], v[182:183], s[100:101], v[22:23] op_sel_hi:[1,0,1]
	v_pk_fma_f32 v[24:25], v[184:185], s[100:101], v[24:25] op_sel_hi:[1,0,1]
	global_store_dwordx4 v[246:247], v[238:241], off nt
	global_load_dwordx4 v[182:185], v[242:243], off nt
	v_lshl_add_u64 v[242:243], v[242:243], 0, v[248:249]
	v_lshl_add_u64 v[246:247], v[246:247], 0, v[248:249]
	v_readlane_b32 s8, v230, 49
	v_readlane_b32 s30, v231, 49
	v_readlane_b32 s44, v232, 49
	v_readlane_b32 s46, v233, 49
	v_readlane_b32 s50, v234, 49
	v_readlane_b32 s58, v235, 49
	v_readlane_b32 s98, v236, 49
	v_readlane_b32 s100, v237, 49
	s_waitcnt vmcnt(22)
	v_pk_mul_f32 v[238:239], v[18:19], s[8:9] op_sel_hi:[1,0]
	v_pk_mul_f32 v[240:241], v[20:21], s[8:9] op_sel_hi:[1,0]
	v_pk_fma_f32 v[238:239], v[44:45], v[186:187], v[238:239]
	v_pk_fma_f32 v[240:241], v[44:45], v[188:189], v[240:241]
	v_pk_fma_f32 v[238:239], v[14:15], s[30:31], v[238:239] op_sel_hi:[1,0,1]
	v_pk_fma_f32 v[240:241], v[16:17], s[30:31], v[240:241] op_sel_hi:[1,0,1]
	v_pk_fma_f32 v[238:239], v[10:11], s[44:45], v[238:239] op_sel_hi:[1,0,1]
	v_pk_fma_f32 v[240:241], v[12:13], s[44:45], v[240:241] op_sel_hi:[1,0,1]
	v_pk_fma_f32 v[238:239], v[6:7], s[46:47], v[238:239] op_sel_hi:[1,0,1]
	v_pk_fma_f32 v[240:241], v[8:9], s[46:47], v[240:241] op_sel_hi:[1,0,1]
	v_pk_fma_f32 v[34:35], v[186:187], s[50:51], v[34:35] op_sel_hi:[1,0,1]
	v_pk_fma_f32 v[36:37], v[188:189], s[50:51], v[36:37] op_sel_hi:[1,0,1]
	v_pk_fma_f32 v[30:31], v[186:187], s[58:59], v[30:31] op_sel_hi:[1,0,1]
	v_pk_fma_f32 v[32:33], v[188:189], s[58:59], v[32:33] op_sel_hi:[1,0,1]
	v_pk_fma_f32 v[26:27], v[186:187], s[98:99], v[26:27] op_sel_hi:[1,0,1]
	v_pk_fma_f32 v[28:29], v[188:189], s[98:99], v[28:29] op_sel_hi:[1,0,1]
	v_pk_fma_f32 v[22:23], v[186:187], s[100:101], v[22:23] op_sel_hi:[1,0,1]
	v_pk_fma_f32 v[24:25], v[188:189], s[100:101], v[24:25] op_sel_hi:[1,0,1]
	global_store_dwordx4 v[246:247], v[238:241], off nt
	global_load_dwordx4 v[186:189], v[242:243], off nt
	v_lshl_add_u64 v[242:243], v[242:243], 0, v[248:249]
	v_lshl_add_u64 v[246:247], v[246:247], 0, v[248:249]
	v_readlane_b32 s8, v230, 50
	v_readlane_b32 s30, v231, 50
	v_readlane_b32 s44, v232, 50
	v_readlane_b32 s46, v233, 50
	v_readlane_b32 s50, v234, 50
	v_readlane_b32 s58, v235, 50
	v_readlane_b32 s98, v236, 50
	v_readlane_b32 s100, v237, 50
	s_waitcnt vmcnt(22)
; __device__ __forceinline__ void mlstm_sample_unit(Frame& F, const Args& a, int b, int h) {
;     ...
; #pragma unroll 16
;     for (int i = 0; i < 64; ++i) { const int d = 4 * i + rsub;
;         const f32x4 c0 = __builtin_nontemporal_load((const f32x4*)(Cin + (size_t)d * 512));
;         f32x4 cn = c0 * decay;
; #pragma unroll
;         for (int s = 0; s < 4; ++s) { cn += vs[s] * L[MS_KW + s * 256 + d]; qc[s] += c0 * L[MS_Q + s * 256 + d]; }
;         __builtin_nontemporal_store(cn, (f32x4*)(Cout + (size_t)d * 512)); }
	v_pk_mul_f32 v[238:239], v[18:19], s[8:9] op_sel_hi:[1,0]
	v_pk_mul_f32 v[240:241], v[20:21], s[8:9] op_sel_hi:[1,0]
	v_pk_fma_f32 v[238:239], v[44:45], v[190:191], v[238:239]
	v_pk_fma_f32 v[240:241], v[44:45], v[192:193], v[240:241]
	v_pk_fma_f32 v[238:239], v[14:15], s[30:31], v[238:239] op_sel_hi:[1,0,1]
	v_pk_fma_f32 v[240:241], v[16:17], s[30:31], v[240:241] op_sel_hi:[1,0,1]
	v_pk_fma_f32 v[238:239], v[10:11], s[44:45], v[238:239] op_sel_hi:[1,0,1]
	v_pk_fma_f32 v[240:241], v[12:13], s[44:45], v[240:241] op_sel_hi:[1,0,1]
	v_pk_fma_f32 v[238:239], v[6:7], s[46:47], v[238:239] op_sel_hi:[1,0,1]
	v_pk_fma_f32 v[240:241], v[8:9], s[46:47], v[240:241] op_sel_hi:[1,0,1]
	v_pk_fma_f32 v[34:35], v[190:191], s[50:51], v[34:35] op_sel_hi:[1,0,1]
	v_pk_fma_f32 v[36:37], v[192:193], s[50:51], v[36:37] op_sel_hi:[1,0,1]
	v_pk_fma_f32 v[30:31], v[190:191], s[58:59], v[30:31] op_sel_hi:[1,0,1]
	v_pk_fma_f32 v[32:33], v[192:193], s[58:59], v[32:33] op_sel_hi:[1,0,1]
	v_pk_fma_f32 v[26:27], v[190:191], s[98:99], v[26:27] op_sel_hi:[1,0,1]
	v_pk_fma_f32 v[28:29], v[192:193], s[98:99], v[28:29] op_sel_hi:[1,0,1]
	v_pk_fma_f32 v[22:23], v[190:191], s[100:101], v[22:23] op_sel_hi:[1,0,1]
	v_pk_fma_f32 v[24:25], v[192:193], s[100:101], v[24:25] op_sel_hi:[1,0,1]
	global_store_dwordx4 v[246:247], v[238:241], off nt
	global_load_dwordx4 v[190:193], v[242:243], off nt
	v_lshl_add_u64 v[242:243], v[242:243], 0, v[248:249]
	v_lshl_add_u64 v[246:247], v[246:247], 0, v[248:249]
	v_readlane_b32 s8, v230, 51
	v_readlane_b32 s30, v231, 51
	v_readlane_b32 s44, v232, 51
	v_readlane_b32 s46, v233, 51
	v_readlane_b32 s50, v234, 51
	v_readlane_b32 s58, v235, 51
	v_readlane_b32 s98, v236, 51
	v_readlane_b32 s100, v237, 51
	s_waitcnt vmcnt(22)
	v_pk_mul_f32 v[238:239], v[18:19], s[8:9] op_sel_hi:[1,0]
	v_pk_mul_f32 v[240:241], v[20:21], s[8:9] op_sel_hi:[1,0]
	v_pk_fma_f32 v[238:239], v[44:45], v[194:195], v[238:239]
	v_pk_fma_f32 v[240:241], v[44:45], v[196:197], v[240:241]
	v_pk_fma_f32 v[238:239], v[14:15], s[30:31], v[238:239] op_sel_hi:[1,0,1]
	v_pk_fma_f32 v[240:241], v[16:17], s[30:31], v[240:241] op_sel_hi:[1,0,1]
	v_pk_fma_f32 v[238:239], v[10:11], s[44:45], v[238:239] op_sel_hi:[1,0,1]
	v_pk_fma_f32 v[240:241], v[12:13], s[44:45], v[240:241] op_sel_hi:[1,0,1]
	v_pk_fma_f32 v[238:239], v[6:7], s[46:47], v[238:239] op_sel_hi:[1,0,1]
	v_pk_fma_f32 v[240:241], v[8:9], s[46:47], v[240:241] op_sel_hi:[1,0,1]
	v_pk_fma_f32 v[34:35], v[194:195], s[50:51], v[34:35] op_sel_hi:[1,0,1]
	v_pk_fma_f32 v[36:37], v[196:197], s[50:51], v[36:37] op_sel_hi:[1,0,1]
	v_pk_fma_f32 v[30:31], v[194:195], s[58:59], v[30:31] op_sel_hi:[1,0,1]
	v_pk_fma_f32 v[32:33], v[196:197], s[58:59], v[32:33] op_sel_hi:[1,0,1]
	v_pk_fma_f32 v[26:27], v[194:195], s[98:99], v[26:27] op_sel_hi:[1,0,1]
	v_pk_fma_f32 v[28:29], v[196:197], s[98:99], v[28:29] op_sel_hi:[1,0,1]
	v_pk_fma_f32 v[22:23], v[194:195], s[100:101], v[22:23] op_sel_hi:[1,0,1]
	v_pk_fma_f32 v[24:25], v[196:197], s[100:101], v[24:25] op_sel_hi:[1,0,1]
	global_store_dwordx4 v[246:247], v[238:241], off nt
	global_load_dwordx4 v[194:197], v[242:243], off nt
	v_lshl_add_u64 v[242:243], v[242:243], 0, v[248:249]
	v_lshl_add_u64 v[246:247], v[246:247], 0, v[248:249]
	v_readlane_b32 s8, v230, 52
	v_readlane_b32 s30, v231, 52
	v_readlane_b32 s44, v232, 52
	v_readlane_b32 s46, v233, 52
	v_readlane_b32 s50, v234, 52
	v_readlane_b32 s58, v235, 52
	v_readlane_b32 s98, v236, 52
	v_readlane_b32 s100, v237, 52
	s_waitcnt vmcnt(22)
	v_pk_mul_f32 v[238:239], v[18:19], s[8:9] op_sel_hi:[1,0]
	v_pk_mul_f32 v[240:241], v[20:21], s[8:9] op_sel_hi:[1,0]
	v_pk_fma_f32 v[238:239], v[44:45], v[198:199], v[238:239]
	v_pk_fma_f32 v[240:241], v[44:45], v[200:201], v[240:241]
	v_pk_fma_f32 v[238:239], v[14:15], s[30:31], v[238:239] op_sel_hi:[1,0,1]
	v_pk_fma_f32 v[240:241], v[16:17], s[30:31], v[240:241] op_sel_hi:[1,0,1]
	v_pk_fma_f32 v[238:239], v[10:11], s[44:45], v[238:239] op_sel_hi:[1,0,1]
	v_pk_fma_f32 v[240:241], v[12:13], s[44:45], v[240:241] op_sel_hi:[1,0,1]
	v_pk_fma_f32 v[238:239], v[6:7], s[46:47], v[238:239] op_sel_hi:[1,0,1]
	v_pk_fma_f32 v[240:241], v[8:9], s[46:47], v[240:241] op_sel_hi:[1,0,1]
	v_pk_fma_f32 v[34:35], v[198:199], s[50:51], v[34:35] op_sel_hi:[1,0,1]
	v_pk_fma_f32 v[36:37], v[200:201], s[50:51], v[36:37] op_sel_hi:[1,0,1]
	v_pk_fma_f32 v[30:31], v[198:199], s[58:59], v[30:31] op_sel_hi:[1,0,1]
	v_pk_fma_f32 v[32:33], v[200:201], s[58:59], v[32:33] op_sel_hi:[1,0,1]
	v_pk_fma_f32 v[26:27], v[198:199], s[98:99], v[26:27] op_sel_hi:[1,0,1]
	v_pk_fma_f32 v[28:29], v[200:201], s[98:99], v[28:29] op_sel_hi:[1,0,1]
	v_pk_fma_f32 v[22:23], v[198:199], s[100:101], v[22:23] op_sel_hi:[1,0,1]
	v_pk_fma_f32 v[24:25], v[200:201], s[100:101], v[24:25] op_sel_hi:[1,0,1]
	global_store_dwordx4 v[246:247], v[238:241], off nt
	v_lshl_add_u64 v[246:247], v[246:247], 0, v[248:249]
	v_readlane_b32 s8, v230, 53
	v_readlane_b32 s30, v231, 53
	v_readlane_b32 s44, v232, 53
	v_readlane_b32 s46, v233, 53
	v_readlane_b32 s50, v234, 53
	v_readlane_b32 s58, v235, 53
	v_readlane_b32 s98, v236, 53
	v_readlane_b32 s100, v237, 53
	s_waitcnt vmcnt(21)
; __device__ __forceinline__ void mlstm_sample_unit(Frame& F, const Args& a, int b, int h) {
;     ...
; #pragma unroll 16
;     for (int i = 0; i < 64; ++i) { const int d = 4 * i + rsub;
;         const f32x4 c0 = __builtin_nontemporal_load((const f32x4*)(Cin + (size_t)d * 512));
;         f32x4 cn = c0 * decay;
; #pragma unroll
;         for (int s = 0; s < 4; ++s) { cn += vs[s] * L[MS_KW + s * 256 + d]; qc[s] += c0 * L[MS_Q + s * 256 + d]; }
;         __builtin_nontemporal_store(cn, (f32x4*)(Cout + (size_t)d * 512)); }
	v_pk_mul_f32 v[238:239], v[18:19], s[8:9] op_sel_hi:[1,0]
	v_pk_mul_f32 v[240:241], v[20:21], s[8:9] op_sel_hi:[1,0]
	v_pk_fma_f32 v[238:239], v[44:45], v[202:203], v[238:239]
	v_pk_fma_f32 v[240:241], v[44:45], v[204:205], v[240:241]
	v_pk_fma_f32 v[238:239], v[14:15], s[30:31], v[238:239] op_sel_hi:[1,0,1]
	v_pk_fma_f32 v[240:241], v[16:17], s[30:31], v[240:241] op_sel_hi:[1,0,1]
	v_pk_fma_f32 v[238:239], v[10:11], s[44:45], v[238:239] op_sel_hi:[1,0,1]
	v_pk_fma_f32 v[240:241], v[12:13], s[44:45], v[240:241] op_sel_hi:[1,0,1]
	v_pk_fma_f32 v[238:239], v[6:7], s[46:47], v[238:239] op_sel_hi:[1,0,1]
	v_pk_fma_f32 v[240:241], v[8:9], s[46:47], v[240:241] op_sel_hi:[1,0,1]
	v_pk_fma_f32 v[34:35], v[202:203], s[50:51], v[34:35] op_sel_hi:[1,0,1]
	v_pk_fma_f32 v[36:37], v[204:205], s[50:51], v[36:37] op_sel_hi:[1,0,1]
	v_pk_fma_f32 v[30:31], v[202:203], s[58:59], v[30:31] op_sel_hi:[1,0,1]
	v_pk_fma_f32 v[32:33], v[204:205], s[58:59], v[32:33] op_sel_hi:[1,0,1]
	v_pk_fma_f32 v[26:27], v[202:203], s[98:99], v[26:27] op_sel_hi:[1,0,1]
	v_pk_fma_f32 v[28:29], v[204:205], s[98:99], v[28:29] op_sel_hi:[1,0,1]
	v_pk_fma_f32 v[22:23], v[202:203], s[100:101], v[22:23] op_sel_hi:[1,0,1]
	v_pk_fma_f32 v[24:25], v[204:205], s[100:101], v[24:25] op_sel_hi:[1,0,1]
	global_store_dwordx4 v[246:247], v[238:241], off nt
	v_lshl_add_u64 v[246:247], v[246:247], 0, v[248:249]
	v_readlane_b32 s8, v230, 54
	v_readlane_b32 s30, v231, 54
	v_readlane_b32 s44, v232, 54
	v_readlane_b32 s46, v233, 54
	v_readlane_b32 s50, v234, 54
	v_readlane_b32 s58, v235, 54
	v_readlane_b32 s98, v236, 54
	v_readlane_b32 s100, v237, 54
	s_waitcnt vmcnt(20)
	v_pk_mul_f32 v[238:239], v[18:19], s[8:9] op_sel_hi:[1,0]
	v_pk_mul_f32 v[240:241], v[20:21], s[8:9] op_sel_hi:[1,0]
	v_pk_fma_f32 v[238:239], v[44:45], v[206:207], v[238:239]
	v_pk_fma_f32 v[240:241], v[44:45], v[208:209], v[240:241]
	v_pk_fma_f32 v[238:239], v[14:15], s[30:31], v[238:239] op_sel_hi:[1,0,1]
	v_pk_fma_f32 v[240:241], v[16:17], s[30:31], v[240:241] op_sel_hi:[1,0,1]
	v_pk_fma_f32 v[238:239], v[10:11], s[44:45], v[238:239] op_sel_hi:[1,0,1]
	v_pk_fma_f32 v[240:241], v[12:13], s[44:45], v[240:241] op_sel_hi:[1,0,1]
	v_pk_fma_f32 v[238:239], v[6:7], s[46:47], v[238:239] op_sel_hi:[1,0,1]
	v_pk_fma_f32 v[240:241], v[8:9], s[46:47], v[240:241] op_sel_hi:[1,0,1]
	v_pk_fma_f32 v[34:35], v[206:207], s[50:51], v[34:35] op_sel_hi:[1,0,1]
	v_pk_fma_f32 v[36:37], v[208:209], s[50:51], v[36:37] op_sel_hi:[1,0,1]
	v_pk_fma_f32 v[30:31], v[206:207], s[58:59], v[30:31] op_sel_hi:[1,0,1]
	v_pk_fma_f32 v[32:33], v[208:209], s[58:59], v[32:33] op_sel_hi:[1,0,1]
	v_pk_fma_f32 v[26:27], v[206:207], s[98:99], v[26:27] op_sel_hi:[1,0,1]
	v_pk_fma_f32 v[28:29], v[208:209], s[98:99], v[28:29] op_sel_hi:[1,0,1]
	v_pk_fma_f32 v[22:23], v[206:207], s[100:101], v[22:23] op_sel_hi:[1,0,1]
	v_pk_fma_f32 v[24:25], v[208:209], s[100:101], v[24:25] op_sel_hi:[1,0,1]
	global_store_dwordx4 v[246:247], v[238:241], off nt
	v_lshl_add_u64 v[246:247], v[246:247], 0, v[248:249]
	v_readlane_b32 s8, v230, 55
	v_readlane_b32 s30, v231, 55
	v_readlane_b32 s44, v232, 55
	v_readlane_b32 s46, v233, 55
	v_readlane_b32 s50, v234, 55
	v_readlane_b32 s58, v235, 55
	v_readlane_b32 s98, v236, 55
	v_readlane_b32 s100, v237, 55
	s_waitcnt vmcnt(19)
	v_pk_mul_f32 v[238:239], v[18:19], s[8:9] op_sel_hi:[1,0]
	v_pk_mul_f32 v[240:241], v[20:21], s[8:9] op_sel_hi:[1,0]
	v_pk_fma_f32 v[238:239], v[44:45], v[210:211], v[238:239]
	v_pk_fma_f32 v[240:241], v[44:45], v[212:213], v[240:241]
	v_pk_fma_f32 v[238:239], v[14:15], s[30:31], v[238:239] op_sel_hi:[1,0,1]
	v_pk_fma_f32 v[240:241], v[16:17], s[30:31], v[240:241] op_sel_hi:[1,0,1]
	v_pk_fma_f32 v[238:239], v[10:11], s[44:45], v[238:239] op_sel_hi:[1,0,1]
	v_pk_fma_f32 v[240:241], v[12:13], s[44:45], v[240:241] op_sel_hi:[1,0,1]
	v_pk_fma_f32 v[238:239], v[6:7], s[46:47], v[238:239] op_sel_hi:[1,0,1]
	v_pk_fma_f32 v[240:241], v[8:9], s[46:47], v[240:241] op_sel_hi:[1,0,1]
	v_pk_fma_f32 v[34:35], v[210:211], s[50:51], v[34:35] op_sel_hi:[1,0,1]
	v_pk_fma_f32 v[36:37], v[212:213], s[50:51], v[36:37] op_sel_hi:[1,0,1]
	v_pk_fma_f32 v[30:31], v[210:211], s[58:59], v[30:31] op_sel_hi:[1,0,1]
	v_pk_fma_f32 v[32:33], v[212:213], s[58:59], v[32:33] op_sel_hi:[1,0,1]
	v_pk_fma_f32 v[26:27], v[210:211], s[98:99], v[26:27] op_sel_hi:[1,0,1]
	v_pk_fma_f32 v[28:29], v[212:213], s[98:99], v[28:29] op_sel_hi:[1,0,1]
	v_pk_fma_f32 v[22:23], v[210:211], s[100:101], v[22:23] op_sel_hi:[1,0,1]
	v_pk_fma_f32 v[24:25], v[212:213], s[100:101], v[24:25] op_sel_hi:[1,0,1]
	global_store_dwordx4 v[246:247], v[238:241], off nt
	v_lshl_add_u64 v[246:247], v[246:247], 0, v[248:249]
	v_readlane_b32 s8, v230, 56
	v_readlane_b32 s30, v231, 56
	v_readlane_b32 s44, v232, 56
	v_readlane_b32 s46, v233, 56
	v_readlane_b32 s50, v234, 56
	v_readlane_b32 s58, v235, 56
	v_readlane_b32 s98, v236, 56
	v_readlane_b32 s100, v237, 56
	s_waitcnt vmcnt(18)
; __device__ __forceinline__ void mlstm_sample_unit(Frame& F, const Args& a, int b, int h) {
;     ...
; #pragma unroll 16
;     for (int i = 0; i < 64; ++i) { const int d = 4 * i + rsub;
;         const f32x4 c0 = __builtin_nontemporal_load((const f32x4*)(Cin + (size_t)d * 512));
;         f32x4 cn = c0 * decay;
; #pragma unroll
;         for (int s = 0; s < 4; ++s) { cn += vs[s] * L[MS_KW + s * 256 + d]; qc[s] += c0 * L[MS_Q + s * 256 + d]; }
;         __builtin_nontemporal_store(cn, (f32x4*)(Cout + (size_t)d * 512)); }
	v_pk_mul_f32 v[238:239], v[18:19], s[8:9] op_sel_hi:[1,0]
	v_pk_mul_f32 v[240:241], v[20:21], s[8:9] op_sel_hi:[1,0]
	v_pk_fma_f32 v[238:239], v[44:45], v[214:215], v[238:239]
	v_pk_fma_f32 v[240:241], v[44:45], v[216:217], v[240:241]
	v_pk_fma_f32 v[238:239], v[14:15], s[30:31], v[238:239] op_sel_hi:[1,0,1]
	v_pk_fma_f32 v[240:241], v[16:17], s[30:31], v[240:241] op_sel_hi:[1,0,1]
	v_pk_fma_f32 v[238:239], v[10:11], s[44:45], v[238:239] op_sel_hi:[1,0,1]
	v_pk_fma_f32 v[240:241], v[12:13], s[44:45], v[240:241] op_sel_hi:[1,0,1]
	v_pk_fma_f32 v[238:239], v[6:7], s[46:47], v[238:239] op_sel_hi:[1,0,1]
	v_pk_fma_f32 v[240:241], v[8:9], s[46:47], v[240:241] op_sel_hi:[1,0,1]
	v_pk_fma_f32 v[34:35], v[214:215], s[50:51], v[34:35] op_sel_hi:[1,0,1]
	v_pk_fma_f32 v[36:37], v[216:217], s[50:51], v[36:37] op_sel_hi:[1,0,1]
	v_pk_fma_f32 v[30:31], v[214:215], s[58:59], v[30:31] op_sel_hi:[1,0,1]
	v_pk_fma_f32 v[32:33], v[216:217], s[58:59], v[32:33] op_sel_hi:[1,0,1]
	v_pk_fma_f32 v[26:27], v[214:215], s[98:99], v[26:27] op_sel_hi:[1,0,1]
	v_pk_fma_f32 v[28:29], v[216:217], s[98:99], v[28:29] op_sel_hi:[1,0,1]
	v_pk_fma_f32 v[22:23], v[214:215], s[100:101], v[22:23] op_sel_hi:[1,0,1]
	v_pk_fma_f32 v[24:25], v[216:217], s[100:101], v[24:25] op_sel_hi:[1,0,1]
	global_store_dwordx4 v[246:247], v[238:241], off nt
	v_lshl_add_u64 v[246:247], v[246:247], 0, v[248:249]
	v_readlane_b32 s8, v230, 57
	v_readlane_b32 s30, v231, 57
	v_readlane_b32 s44, v232, 57
	v_readlane_b32 s46, v233, 57
	v_readlane_b32 s50, v234, 57
	v_readlane_b32 s58, v235, 57
	v_readlane_b32 s98, v236, 57
	v_readlane_b32 s100, v237, 57
	s_waitcnt vmcnt(17)
	v_pk_mul_f32 v[238:239], v[18:19], s[8:9] op_sel_hi:[1,0]
	v_pk_mul_f32 v[240:241], v[20:21], s[8:9] op_sel_hi:[1,0]
	v_pk_fma_f32 v[238:239], v[44:45], v[218:219], v[238:239]
	v_pk_fma_f32 v[240:241], v[44:45], v[220:221], v[240:241]
	v_pk_fma_f32 v[238:239], v[14:15], s[30:31], v[238:239] op_sel_hi:[1,0,1]
	v_pk_fma_f32 v[240:241], v[16:17], s[30:31], v[240:241] op_sel_hi:[1,0,1]
	v_pk_fma_f32 v[238:239], v[10:11], s[44:45], v[238:239] op_sel_hi:[1,0,1]
	v_pk_fma_f32 v[240:241], v[12:13], s[44:45], v[240:241] op_sel_hi:[1,0,1]
	v_pk_fma_f32 v[238:239], v[6:7], s[46:47], v[238:239] op_sel_hi:[1,0,1]
	v_pk_fma_f32 v[240:241], v[8:9], s[46:47], v[240:241] op_sel_hi:[1,0,1]
	v_pk_fma_f32 v[34:35], v[218:219], s[50:51], v[34:35] op_sel_hi:[1,0,1]
	v_pk_fma_f32 v[36:37], v[220:221], s[50:51], v[36:37] op_sel_hi:[1,0,1]
	v_pk_fma_f32 v[30:31], v[218:219], s[58:59], v[30:31] op_sel_hi:[1,0,1]
	v_pk_fma_f32 v[32:33], v[220:221], s[58:59], v[32:33] op_sel_hi:[1,0,1]
	v_pk_fma_f32 v[26:27], v[218:219], s[98:99], v[26:27] op_sel_hi:[1,0,1]
	v_pk_fma_f32 v[28:29], v[220:221], s[98:99], v[28:29] op_sel_hi:[1,0,1]
	v_pk_fma_f32 v[22:23], v[218:219], s[100:101], v[22:23] op_sel_hi:[1,0,1]
	v_pk_fma_f32 v[24:25], v[220:221], s[100:101], v[24:25] op_sel_hi:[1,0,1]
	global_store_dwordx4 v[246:247], v[238:241], off nt
	v_lshl_add_u64 v[246:247], v[246:247], 0, v[248:249]
	v_readlane_b32 s8, v230, 58
	v_readlane_b32 s30, v231, 58
	v_readlane_b32 s44, v232, 58
	v_readlane_b32 s46, v233, 58
	v_readlane_b32 s50, v234, 58
	v_readlane_b32 s58, v235, 58
	v_readlane_b32 s98, v236, 58
	v_readlane_b32 s100, v237, 58
	s_waitcnt vmcnt(16)
	v_pk_mul_f32 v[238:239], v[18:19], s[8:9] op_sel_hi:[1,0]
	v_pk_mul_f32 v[240:241], v[20:21], s[8:9] op_sel_hi:[1,0]
	v_pk_fma_f32 v[238:239], v[44:45], v[222:223], v[238:239]
	v_pk_fma_f32 v[240:241], v[44:45], v[224:225], v[240:241]
	v_pk_fma_f32 v[238:239], v[14:15], s[30:31], v[238:239] op_sel_hi:[1,0,1]
	v_pk_fma_f32 v[240:241], v[16:17], s[30:31], v[240:241] op_sel_hi:[1,0,1]
	v_pk_fma_f32 v[238:239], v[10:11], s[44:45], v[238:239] op_sel_hi:[1,0,1]
	v_pk_fma_f32 v[240:241], v[12:13], s[44:45], v[240:241] op_sel_hi:[1,0,1]
	v_pk_fma_f32 v[238:239], v[6:7], s[46:47], v[238:239] op_sel_hi:[1,0,1]
	v_pk_fma_f32 v[240:241], v[8:9], s[46:47], v[240:241] op_sel_hi:[1,0,1]
	v_pk_fma_f32 v[34:35], v[222:223], s[50:51], v[34:35] op_sel_hi:[1,0,1]
	v_pk_fma_f32 v[36:37], v[224:225], s[50:51], v[36:37] op_sel_hi:[1,0,1]
	v_pk_fma_f32 v[30:31], v[222:223], s[58:59], v[30:31] op_sel_hi:[1,0,1]
	v_pk_fma_f32 v[32:33], v[224:225], s[58:59], v[32:33] op_sel_hi:[1,0,1]
	v_pk_fma_f32 v[26:27], v[222:223], s[98:99], v[26:27] op_sel_hi:[1,0,1]
	v_pk_fma_f32 v[28:29], v[224:225], s[98:99], v[28:29] op_sel_hi:[1,0,1]
	v_pk_fma_f32 v[22:23], v[222:223], s[100:101], v[22:23] op_sel_hi:[1,0,1]
	v_pk_fma_f32 v[24:25], v[224:225], s[100:101], v[24:25] op_sel_hi:[1,0,1]
	global_store_dwordx4 v[246:247], v[238:241], off nt
	v_lshl_add_u64 v[246:247], v[246:247], 0, v[248:249]
	v_readlane_b32 s8, v230, 59
	v_readlane_b32 s30, v231, 59
	v_readlane_b32 s44, v232, 59
	v_readlane_b32 s46, v233, 59
	v_readlane_b32 s50, v234, 59
	v_readlane_b32 s58, v235, 59
	v_readlane_b32 s98, v236, 59
	v_readlane_b32 s100, v237, 59
	s_waitcnt vmcnt(15)
; __device__ __forceinline__ void mlstm_sample_unit(Frame& F, const Args& a, int b, int h) {
;     ...
; #pragma unroll 16
;     for (int i = 0; i < 64; ++i) { const int d = 4 * i + rsub;
;         const f32x4 c0 = __builtin_nontemporal_load((const f32x4*)(Cin + (size_t)d * 512));
;         f32x4 cn = c0 * decay;
; #pragma unroll
;         for (int s = 0; s < 4; ++s) { cn += vs[s] * L[MS_KW + s * 256 + d]; qc[s] += c0 * L[MS_Q + s * 256 + d]; }
;         __builtin_nontemporal_store(cn, (f32x4*)(Cout + (size_t)d * 512)); }
	v_pk_mul_f32 v[238:239], v[18:19], s[8:9] op_sel_hi:[1,0]
	v_pk_mul_f32 v[240:241], v[20:21], s[8:9] op_sel_hi:[1,0]
	v_pk_fma_f32 v[238:239], v[44:45], v[226:227], v[238:239]
	v_pk_fma_f32 v[240:241], v[44:45], v[228:229], v[240:241]
	v_pk_fma_f32 v[238:239], v[14:15], s[30:31], v[238:239] op_sel_hi:[1,0,1]
	v_pk_fma_f32 v[240:241], v[16:17], s[30:31], v[240:241] op_sel_hi:[1,0,1]
	v_pk_fma_f32 v[238:239], v[10:11], s[44:45], v[238:239] op_sel_hi:[1,0,1]
	v_pk_fma_f32 v[240:241], v[12:13], s[44:45], v[240:241] op_sel_hi:[1,0,1]
	v_pk_fma_f32 v[238:239], v[6:7], s[46:47], v[238:239] op_sel_hi:[1,0,1]
	v_pk_fma_f32 v[240:241], v[8:9], s[46:47], v[240:241] op_sel_hi:[1,0,1]
	v_pk_fma_f32 v[34:35], v[226:227], s[50:51], v[34:35] op_sel_hi:[1,0,1]
	v_pk_fma_f32 v[36:37], v[228:229], s[50:51], v[36:37] op_sel_hi:[1,0,1]
	v_pk_fma_f32 v[30:31], v[226:227], s[58:59], v[30:31] op_sel_hi:[1,0,1]
	v_pk_fma_f32 v[32:33], v[228:229], s[58:59], v[32:33] op_sel_hi:[1,0,1]
	v_pk_fma_f32 v[26:27], v[226:227], s[98:99], v[26:27] op_sel_hi:[1,0,1]
	v_pk_fma_f32 v[28:29], v[228:229], s[98:99], v[28:29] op_sel_hi:[1,0,1]
	v_pk_fma_f32 v[22:23], v[226:227], s[100:101], v[22:23] op_sel_hi:[1,0,1]
	v_pk_fma_f32 v[24:25], v[228:229], s[100:101], v[24:25] op_sel_hi:[1,0,1]
	global_store_dwordx4 v[246:247], v[238:241], off nt
	v_lshl_add_u64 v[246:247], v[246:247], 0, v[248:249]
	v_readlane_b32 s8, v230, 60
	v_readlane_b32 s30, v231, 60
	v_readlane_b32 s44, v232, 60
	v_readlane_b32 s46, v233, 60
	v_readlane_b32 s50, v234, 60
	v_readlane_b32 s58, v235, 60
	v_readlane_b32 s98, v236, 60
	v_readlane_b32 s100, v237, 60
	s_waitcnt vmcnt(14)
	v_pk_mul_f32 v[238:239], v[18:19], s[8:9] op_sel_hi:[1,0]
	v_pk_mul_f32 v[240:241], v[20:21], s[8:9] op_sel_hi:[1,0]
	v_pk_fma_f32 v[238:239], v[44:45], v[182:183], v[238:239]
	v_pk_fma_f32 v[240:241], v[44:45], v[184:185], v[240:241]
	v_pk_fma_f32 v[238:239], v[14:15], s[30:31], v[238:239] op_sel_hi:[1,0,1]
	v_pk_fma_f32 v[240:241], v[16:17], s[30:31], v[240:241] op_sel_hi:[1,0,1]
	v_pk_fma_f32 v[238:239], v[10:11], s[44:45], v[238:239] op_sel_hi:[1,0,1]
	v_pk_fma_f32 v[240:241], v[12:13], s[44:45], v[240:241] op_sel_hi:[1,0,1]
	v_pk_fma_f32 v[238:239], v[6:7], s[46:47], v[238:239] op_sel_hi:[1,0,1]
	v_pk_fma_f32 v[240:241], v[8:9], s[46:47], v[240:241] op_sel_hi:[1,0,1]
	v_pk_fma_f32 v[34:35], v[182:183], s[50:51], v[34:35] op_sel_hi:[1,0,1]
	v_pk_fma_f32 v[36:37], v[184:185], s[50:51], v[36:37] op_sel_hi:[1,0,1]
	v_pk_fma_f32 v[30:31], v[182:183], s[58:59], v[30:31] op_sel_hi:[1,0,1]
	v_pk_fma_f32 v[32:33], v[184:185], s[58:59], v[32:33] op_sel_hi:[1,0,1]
	v_pk_fma_f32 v[26:27], v[182:183], s[98:99], v[26:27] op_sel_hi:[1,0,1]
	v_pk_fma_f32 v[28:29], v[184:185], s[98:99], v[28:29] op_sel_hi:[1,0,1]
	v_pk_fma_f32 v[22:23], v[182:183], s[100:101], v[22:23] op_sel_hi:[1,0,1]
	v_pk_fma_f32 v[24:25], v[184:185], s[100:101], v[24:25] op_sel_hi:[1,0,1]
	global_store_dwordx4 v[246:247], v[238:241], off nt
	v_lshl_add_u64 v[246:247], v[246:247], 0, v[248:249]
	v_readlane_b32 s8, v230, 61
	v_readlane_b32 s30, v231, 61
	v_readlane_b32 s44, v232, 61
	v_readlane_b32 s46, v233, 61
	v_readlane_b32 s50, v234, 61
	v_readlane_b32 s58, v235, 61
	v_readlane_b32 s98, v236, 61
	v_readlane_b32 s100, v237, 61
	s_waitcnt vmcnt(13)
	v_pk_mul_f32 v[238:239], v[18:19], s[8:9] op_sel_hi:[1,0]
	v_pk_mul_f32 v[240:241], v[20:21], s[8:9] op_sel_hi:[1,0]
	v_pk_fma_f32 v[238:239], v[44:45], v[186:187], v[238:239]
	v_pk_fma_f32 v[240:241], v[44:45], v[188:189], v[240:241]
	v_pk_fma_f32 v[238:239], v[14:15], s[30:31], v[238:239] op_sel_hi:[1,0,1]
	v_pk_fma_f32 v[240:241], v[16:17], s[30:31], v[240:241] op_sel_hi:[1,0,1]
	v_pk_fma_f32 v[238:239], v[10:11], s[44:45], v[238:239] op_sel_hi:[1,0,1]
	v_pk_fma_f32 v[240:241], v[12:13], s[44:45], v[240:241] op_sel_hi:[1,0,1]
	v_pk_fma_f32 v[238:239], v[6:7], s[46:47], v[238:239] op_sel_hi:[1,0,1]
	v_pk_fma_f32 v[240:241], v[8:9], s[46:47], v[240:241] op_sel_hi:[1,0,1]
	v_pk_fma_f32 v[34:35], v[186:187], s[50:51], v[34:35] op_sel_hi:[1,0,1]
	v_pk_fma_f32 v[36:37], v[188:189], s[50:51], v[36:37] op_sel_hi:[1,0,1]
	v_pk_fma_f32 v[30:31], v[186:187], s[58:59], v[30:31] op_sel_hi:[1,0,1]
	v_pk_fma_f32 v[32:33], v[188:189], s[58:59], v[32:33] op_sel_hi:[1,0,1]
	v_pk_fma_f32 v[26:27], v[186:187], s[98:99], v[26:27] op_sel_hi:[1,0,1]
	v_pk_fma_f32 v[28:29], v[188:189], s[98:99], v[28:29] op_sel_hi:[1,0,1]
	v_pk_fma_f32 v[22:23], v[186:187], s[100:101], v[22:23] op_sel_hi:[1,0,1]
	v_pk_fma_f32 v[24:25], v[188:189], s[100:101], v[24:25] op_sel_hi:[1,0,1]
	global_store_dwordx4 v[246:247], v[238:241], off nt
	v_lshl_add_u64 v[246:247], v[246:247], 0, v[248:249]
	v_readlane_b32 s8, v230, 62
	v_readlane_b32 s30, v231, 62
	v_readlane_b32 s44, v232, 62
	v_readlane_b32 s46, v233, 62
	v_readlane_b32 s50, v234, 62
	v_readlane_b32 s58, v235, 62
	v_readlane_b32 s98, v236, 62
	v_readlane_b32 s100, v237, 62
	s_waitcnt vmcnt(12)
; #define GAS __attribute__((address_space(1)))
; #define LAS __attribute__((address_space(3)))
; __device__ __forceinline__ unsigned pk2(float lo, float hi) { return f2bf(lo) | (f2bf(hi) << 16); }
; __device__ __forceinline__ void mlstm_sample_unit(Frame& F, const Args& a, int b, int h) {
;     ...
; #pragma unroll 16
;     for (int i = 0; i < 64; ++i) { const int d = 4 * i + rsub;
;         const f32x4 c0 = __builtin_nontemporal_load((const f32x4*)(Cin + (size_t)d * 512));
;         f32x4 cn = c0 * decay;
; #pragma unroll
;         for (int s = 0; s < 4; ++s) { cn += vs[s] * L[MS_KW + s * 256 + d]; qc[s] += c0 * L[MS_Q + s * 256 + d]; }
;         __builtin_nontemporal_store(cn, (f32x4*)(Cout + (size_t)d * 512)); }
; #pragma unroll
;     for (int t = 0; t < 4; ++t) *(LAS f32x4*)(L + MS_RED + (rsub * 4 + t) * 512 + 4 * c4) = qc[t];
;     __syncthreads();
;     { const int t = rsub; f32x4 s = (f32x4){0.f, 0.f, 0.f, 0.f};
; #pragma unroll
;       for (int rs = 0; rs < 4; ++rs) s += *(const LAS f32x4*)(L + MS_RED + (rs * 4 + t) * 512 + 4 * c4);
;       const float wp = L[MS_SC + 8 + t]; f32x4 num = s * wp; float den = wp * L[MS_QN + t];
; #pragma unroll
;       for (int s2 = 0; s2 < 4; ++s2) { const float sp = L[MS_SP + t * 4 + s2]; num += vs[s2] * sp; den += sp; }
;       const float inv = 1.0f / fmaxf(fabsf(den), L[MS_SC + 12 + t]);
;       const f32x4 o = num * inv; v2u w; w.x = pk2(o[0], o[1]); w.y = pk2(o[2], o[3]); *(GAS v2u*)(HRAW + (r0 + t) * D + h * 512 + 4 * c4) = w; }
;     if (tid < 4) *(GAS f32x4*)(WSP(float, WS_DENINV) + ((r0 + tid) * 4 + h) * 4) = (f32x4){1.0f, 0.0f, 0.0f, 0.0f};
	v_pk_mul_f32 v[238:239], v[18:19], s[8:9] op_sel_hi:[1,0]
	v_pk_mul_f32 v[240:241], v[20:21], s[8:9] op_sel_hi:[1,0]
	v_pk_fma_f32 v[238:239], v[44:45], v[190:191], v[238:239]
	v_pk_fma_f32 v[240:241], v[44:45], v[192:193], v[240:241]
	v_pk_fma_f32 v[238:239], v[14:15], s[30:31], v[238:239] op_sel_hi:[1,0,1]
	v_pk_fma_f32 v[240:241], v[16:17], s[30:31], v[240:241] op_sel_hi:[1,0,1]
	v_pk_fma_f32 v[238:239], v[10:11], s[44:45], v[238:239] op_sel_hi:[1,0,1]
	v_pk_fma_f32 v[240:241], v[12:13], s[44:45], v[240:241] op_sel_hi:[1,0,1]
	v_pk_fma_f32 v[238:239], v[6:7], s[46:47], v[238:239] op_sel_hi:[1,0,1]
	v_pk_fma_f32 v[240:241], v[8:9], s[46:47], v[240:241] op_sel_hi:[1,0,1]
	v_pk_fma_f32 v[34:35], v[190:191], s[50:51], v[34:35] op_sel_hi:[1,0,1]
	v_pk_fma_f32 v[36:37], v[192:193], s[50:51], v[36:37] op_sel_hi:[1,0,1]
	v_pk_fma_f32 v[30:31], v[190:191], s[58:59], v[30:31] op_sel_hi:[1,0,1]
	v_pk_fma_f32 v[32:33], v[192:193], s[58:59], v[32:33] op_sel_hi:[1,0,1]
	v_pk_fma_f32 v[26:27], v[190:191], s[98:99], v[26:27] op_sel_hi:[1,0,1]
	v_pk_fma_f32 v[28:29], v[192:193], s[98:99], v[28:29] op_sel_hi:[1,0,1]
	v_pk_fma_f32 v[22:23], v[190:191], s[100:101], v[22:23] op_sel_hi:[1,0,1]
	v_pk_fma_f32 v[24:25], v[192:193], s[100:101], v[24:25] op_sel_hi:[1,0,1]
	global_store_dwordx4 v[246:247], v[238:241], off nt
	v_lshl_add_u64 v[246:247], v[246:247], 0, v[248:249]
	v_readlane_b32 s8, v230, 63
	v_readlane_b32 s30, v231, 63
	v_readlane_b32 s44, v232, 63
	v_readlane_b32 s46, v233, 63
	v_readlane_b32 s50, v234, 63
	v_readlane_b32 s58, v235, 63
	v_readlane_b32 s98, v236, 63
	v_readlane_b32 s100, v237, 63
	s_waitcnt vmcnt(11)
	v_pk_mul_f32 v[238:239], v[18:19], s[8:9] op_sel_hi:[1,0]
	v_pk_mul_f32 v[240:241], v[20:21], s[8:9] op_sel_hi:[1,0]
	v_pk_fma_f32 v[238:239], v[44:45], v[194:195], v[238:239]
	v_pk_fma_f32 v[240:241], v[44:45], v[196:197], v[240:241]
	v_pk_fma_f32 v[238:239], v[14:15], s[30:31], v[238:239] op_sel_hi:[1,0,1]
	v_pk_fma_f32 v[240:241], v[16:17], s[30:31], v[240:241] op_sel_hi:[1,0,1]
	v_pk_fma_f32 v[238:239], v[10:11], s[44:45], v[238:239] op_sel_hi:[1,0,1]
	v_pk_fma_f32 v[240:241], v[12:13], s[44:45], v[240:241] op_sel_hi:[1,0,1]
	v_pk_fma_f32 v[238:239], v[6:7], s[46:47], v[238:239] op_sel_hi:[1,0,1]
	v_pk_fma_f32 v[240:241], v[8:9], s[46:47], v[240:241] op_sel_hi:[1,0,1]
	v_pk_fma_f32 v[34:35], v[194:195], s[50:51], v[34:35] op_sel_hi:[1,0,1]
	v_pk_fma_f32 v[36:37], v[196:197], s[50:51], v[36:37] op_sel_hi:[1,0,1]
	v_pk_fma_f32 v[30:31], v[194:195], s[58:59], v[30:31] op_sel_hi:[1,0,1]
	v_pk_fma_f32 v[32:33], v[196:197], s[58:59], v[32:33] op_sel_hi:[1,0,1]
	v_pk_fma_f32 v[26:27], v[194:195], s[98:99], v[26:27] op_sel_hi:[1,0,1]
	v_pk_fma_f32 v[28:29], v[196:197], s[98:99], v[28:29] op_sel_hi:[1,0,1]
	v_pk_fma_f32 v[22:23], v[194:195], s[100:101], v[22:23] op_sel_hi:[1,0,1]
	v_pk_fma_f32 v[24:25], v[196:197], s[100:101], v[24:25] op_sel_hi:[1,0,1]
	global_store_dwordx4 v[246:247], v[238:241], off nt
	v_lshl_add_u64 v[246:247], v[246:247], 0, v[248:249]
	v_mov_b32_e32 v43, v42
	s_mov_b32 s16, 0x4f3a000
	s_mov_b64 s[6:7], 0x80000
	v_lshlrev_b32_e32 v41, 13, v40
	v_add3_u32 v41, 0, v41, v79
	ds_write_b128 v41, v[34:37] offset:22528
	ds_write_b128 v41, v[30:33] offset:24576
	ds_write_b128 v41, v[26:29] offset:26624
	ds_write_b128 v41, v[22:25] offset:28672
	v_lshlrev_b32_e32 v22, 11, v40
	v_add3_u32 v30, 0, v22, v79
	s_waitcnt lgkmcnt(0)
	s_barrier
	ds_read_b128 v[22:25], v30 offset:22528
	ds_read_b32 v32, v78 offset:21696
	s_lshl_b32 s86, s86, 1
	v_lshlrev_b32_e32 v66, 3, v66
	s_waitcnt lgkmcnt(1)
	v_pk_add_f32 v[26:27], v[24:25], 0 op_sel_hi:[1,0]
	v_pk_add_f32 v[28:29], v[22:23], 0 op_sel_hi:[1,0]
	ds_read_b128 v[22:25], v30 offset:30720
	s_waitcnt lgkmcnt(0)
	v_pk_add_f32 v[26:27], v[26:27], v[24:25]
	v_pk_add_f32 v[28:29], v[28:29], v[22:23]
	ds_read_b128 v[22:25], v30 offset:38912
	s_waitcnt lgkmcnt(0)
	v_pk_add_f32 v[26:27], v[26:27], v[24:25]
	v_pk_add_f32 v[28:29], v[28:29], v[22:23]
	ds_read_b128 v[22:25], v30 offset:47104
	v_add_u32_e32 v30, 0x5400, v78
	ds_read2_b32 v[30:31], v30 offset0:8 offset1:12
	s_waitcnt lgkmcnt(1)
	v_pk_add_f32 v[28:29], v[28:29], v[22:23]
	v_lshl_add_u32 v22, v40, 4, 0
	v_pk_add_f32 v[26:27], v[26:27], v[24:25]
	ds_read_b128 v[22:25], v22 offset:21632
	s_waitcnt lgkmcnt(0)
	v_pk_mul_f32 v[18:19], v[18:19], v[22:23] op_sel_hi:[1,0]
	v_pk_mul_f32 v[20:21], v[20:21], v[22:23] op_sel_hi:[1,0]
	v_pk_fma_f32 v[18:19], v[28:29], v[30:31], v[18:19] op_sel_hi:[1,0,1]
	v_pk_fma_f32 v[20:21], v[26:27], v[30:31], v[20:21] op_sel_hi:[1,0,1]
	v_fma_f32 v26, v30, v32, v22
	v_pk_fma_f32 v[14:15], v[14:15], v[22:23], v[18:19] op_sel:[0,1,0]
	v_add_f32_e32 v18, v26, v23
	v_pk_fma_f32 v[10:11], v[10:11], v[24:25], v[14:15] op_sel_hi:[1,0,1]
	v_add_f32_e32 v15, v18, v24
	v_mov_b32_e32 v14, v25
	v_pk_fma_f32 v[6:7], v[6:7], v[14:15], v[10:11] op_sel_hi:[1,0,1]
	v_add_f32_e32 v10, v15, v25
	v_max_f32_e32 v11, v31, v31
	v_pk_fma_f32 v[16:17], v[16:17], v[22:23], v[20:21] op_sel:[0,1,0]
	v_max_f32_e64 v10, |v10|, v11
	v_pk_fma_f32 v[12:13], v[12:13], v[24:25], v[16:17] op_sel_hi:[1,0,1]
	v_div_scale_f32 v11, s[6:7], v10, v10, 1.0
	v_pk_fma_f32 v[8:9], v[8:9], v[14:15], v[12:13] op_sel_hi:[1,0,1]
	v_rcp_f32_e32 v12, v11
	s_nop 0
	v_fma_f32 v13, -v11, v12, 1.0
	v_fmac_f32_e32 v12, v13, v12
	v_div_scale_f32 v13, vcc, 1.0, v10, 1.0
	v_mul_f32_e32 v14, v13, v12
	v_fma_f32 v15, -v11, v14, v13
	v_fmac_f32_e32 v14, v15, v12
	v_fma_f32 v11, -v11, v14, v13
	v_div_fmas_f32 v11, v11, v12, v14
	v_div_fixup_f32 v10, v11, v10, 1.0
	v_pk_mul_f32 v[6:7], v[6:7], v[10:11] op_sel_hi:[1,0]
	v_pk_mul_f32 v[8:9], v[8:9], v[10:11] op_sel_hi:[1,0]
	v_bfe_u32 v10, v6, 16, 1
	v_add3_u32 v6, v6, v10, s3
	v_bfe_u32 v10, v7, 16, 1
	v_lshrrev_b32_e32 v6, 16, v6
	v_add3_u32 v7, v7, v10, s3
	v_and_or_b32 v6, v7, s66, v6
	v_bfe_u32 v7, v8, 16, 1
	v_add3_u32 v7, v8, v7, s3
	v_bfe_u32 v8, v9, 16, 1
	v_lshrrev_b32_e32 v7, 16, v7
	v_add3_u32 v8, v9, v8, s3
	v_and_or_b32 v7, v8, s66, v7
	v_lshl_add_u64 v[8:9], s[90:91], 0, v[38:39]
	v_lshl_add_u64 v[8:9], v[8:9], 0, s[86:87]
	v_lshl_add_u64 v[8:9], v[8:9], 0, v[66:67]
	v_cmp_gt_i32_e32 vcc, 4, v68
	global_store_dwordx2 v[8:9], v[6:7], off
	s_and_saveexec_b64 s[6:7], vcc
	s_cbranch_execnz .LBB0_1081
	s_or_b64 exec, exec, s[6:7]
	s_and_saveexec_b64 s[6:7], s[0:1]
	s_cbranch_execnz .LBB0_1082

; __global__ void __launch_bounds__(NWAVES * 64, 2) fwd_kernel(Args args) {
	.amdhsa_kernel _Z10fwd_kernel4Args
		.amdhsa_group_segment_fixed_size 0
		.amdhsa_private_segment_fixed_size 0
		.amdhsa_kernarg_size 576
		.amdhsa_user_sgpr_count 2
		.amdhsa_user_sgpr_dispatch_ptr 0
		.amdhsa_user_sgpr_queue_ptr 0
		.amdhsa_user_sgpr_kernarg_segment_ptr 1
		.amdhsa_user_sgpr_dispatch_id 0
		.amdhsa_user_sgpr_kernarg_preload_length 0
		.amdhsa_user_sgpr_kernarg_preload_offset 0
		.amdhsa_user_sgpr_private_segment_size 0
		.amdhsa_uses_dynamic_stack 0
		.amdhsa_enable_private_segment 0
		.amdhsa_system_sgpr_workgroup_id_x 1
		.amdhsa_system_sgpr_workgroup_id_y 0
		.amdhsa_system_sgpr_workgroup_id_z 0
		.amdhsa_system_sgpr_workgroup_info 0
		.amdhsa_system_vgpr_workitem_id 2
		.amdhsa_next_free_vgpr 256
		.amdhsa_next_free_sgpr 102
		.amdhsa_accum_offset 256
		.amdhsa_reserve_vcc 1
		.amdhsa_float_round_mode_32 0
		.amdhsa_float_round_mode_16_64 0
		.amdhsa_float_denorm_mode_32 3
		.amdhsa_float_denorm_mode_16_64 3
		.amdhsa_dx10_clamp 1
		.amdhsa_ieee_mode 1
		.amdhsa_fp16_overflow 0
		.amdhsa_tg_split 0
		.amdhsa_exception_fp_ieee_invalid_op 0
		.amdhsa_exception_fp_denorm_src 0
		.amdhsa_exception_fp_ieee_div_zero 0
		.amdhsa_exception_fp_ieee_overflow 0
		.amdhsa_exception_fp_ieee_underflow 0
		.amdhsa_exception_fp_ieee_inexact 0
		.amdhsa_exception_int_div_zero 0
	.end_amdhsa_kernel

; __global__ void __launch_bounds__(NWAVES * 64, 2) fwd_kernel(Args args) {
amdhsa.kernels:
  - .agpr_count:     0
    .args:
      - .offset:         0
        .size:           320
        .value_kind:     by_value
      - .offset:         320
        .size:           4
        .value_kind:     hidden_block_count_x
      - .offset:         324
        .size:           4
        .value_kind:     hidden_block_count_y
      - .offset:         328
        .size:           4
        .value_kind:     hidden_block_count_z
      - .offset:         332
        .size:           2
        .value_kind:     hidden_group_size_x
      - .offset:         334
        .size:           2
        .value_kind:     hidden_group_size_y
      - .offset:         336
        .size:           2
        .value_kind:     hidden_group_size_z
      - .offset:         338
        .size:           2
        .value_kind:     hidden_remainder_x
      - .offset:         340
        .size:           2
        .value_kind:     hidden_remainder_y
      - .offset:         342
        .size:           2
        .value_kind:     hidden_remainder_z
      - .offset:         360
        .size:           8
        .value_kind:     hidden_global_offset_x
      - .offset:         368
        .size:           8
        .value_kind:     hidden_global_offset_y
      - .offset:         376
        .size:           8
        .value_kind:     hidden_global_offset_z
      - .offset:         384
        .size:           2
        .value_kind:     hidden_grid_dims
      - .offset:         408
        .size:           8
        .value_kind:     hidden_multigrid_sync_arg
      - .offset:         440
        .size:           4
        .value_kind:     hidden_dynamic_lds_size
    .group_segment_fixed_size: 0
    .kernarg_segment_align: 8
    .kernarg_segment_size: 576
    .language:       OpenCL C
    .language_version:
      - 2
      - 0
    .max_flat_workgroup_size: 512
    .name:           _Z10fwd_kernel4Args
    .private_segment_fixed_size: 0
    .sgpr_count:     108
    .sgpr_spill_count: 140
    .symbol:         _Z10fwd_kernel4Args.kd
    .uniform_work_group_size: 1
    .uses_dynamic_stack: false
    .vgpr_count:     256
    .vgpr_spill_count: 0
    .wavefront_size: 64
